# v14 + GELU epilogues: the -2log2e multiply before v_exp folded into the two polynomial constants (x*((k*c1)x^2+k*c0)), 320 VALU ops removed; same f32 math kinds
# speedup vs baseline: 1.0202x; 1.0007x over previous
; __device__ __forceinline__ void load_rs8(const float* ss, int t0, int fq, float (&rs)[8], int tmax) {
; #pragma unroll
;     for (int j = 0; j < 8; ++j) { int t = t0 + j; t = t < 0 ? 0 : (t > tmax ? tmax : t);
;         const f32x4 p = *(const f32x4*)(ss + (size_t)t * 16 + 4 * fq); float s = (p.x + p.y) + (p.z + p.w);
;         s += __shfl_xor(s, 16); s += __shfl_xor(s, 32); rs[j] = __builtin_amdgcn_rsqf(s * (1.0f / DMOD) + EPS); }
;     __device__ __forceinline__ void operator()(f32x4 (&acc)[2][2][4][2], const Unit& u, int wr, int wc, int fr, int fq) const {
;         const int t0 = u.pm * 252 - 1 + wr * 126 + fr * 8;
;         { float rs[8]; load_rs8(ss, t0, fq, rs, M_TOK - 1);
; #pragma unroll
;           for (int ai = 0; ai < 2; ++ai)
; #pragma unroll
;             for (int m = 0; m < 4; ++m)
; #pragma unroll
;                 for (int bj = 0; bj < 2; ++bj)
; #pragma unroll
;                     for (int n = 0; n < 2; ++n) acc[ai][bj][m][n] = acc[ai][bj][m][n] * rs[4 * ai + m]; }
;         unsigned vmask = 0, smask = 0, emask = 0;
; #pragma unroll
;         for (int j = 0; j < 8; ++j) { const int t = t0 + j, loc = fr * 8 + j;
;             if (loc >= 1 && loc <= 126 && t < M_TOK) vmask |= 1u << j;
;             const int sm = (t < NPROMPT) ? (SEQ_P - 1) : (SEQ_S - 1);
;             if ((t & sm) == 0) smask |= 1u << j;
;             if ((t & sm) == sm) emask |= 1u << j; }
; #pragma unroll
;         for (int n = 0; n < 2; ++n) {
;             const int cg_ = 128 * u.pn + 32 * wc + 8 * fq + 4 * n;
;             const f32x4 w0g = *(const f32x4*)(cw + cg_), w1g = *(const f32x4*)(cw + 4096 + cg_), w2g = *(const f32x4*)(cw + 8192 + cg_), bg = *(const f32x4*)(cb + cg_);
;             const f32x4 w0v = *(const f32x4*)(cw + 2048 + cg_), w1v = *(const f32x4*)(cw + 4096 + 2048 + cg_), w2v = *(const f32x4*)(cw + 8192 + 2048 + cg_), bv = *(const f32x4*)(cb + 2048 + cg_);
.LBB0_120:
	s_mul_i32 s0, s50, 0xfc
	v_add_u32_e32 v182, s0, v236
	v_min_u32_e32 v0, 0x17fff, v182
	v_lshlrev_b32_e32 v0, 4, v0
	v_cmp_lt_i32_e32 vcc, -1, v182
	v_and_b32_e32 v93, 64, v219
	v_xor_b32_e32 v92, 16, v219
	v_cndmask_b32_e32 v0, 0, v0, vcc
	v_lshlrev_b32_e32 v0, 2, v0
	v_lshl_add_u64 v[90:91], v[174:175], 0, v[0:1]
	v_min_i32_e32 v0, 0x17ffe, v182
	v_lshl_add_u32 v0, v0, 4, 16
	v_cmp_lt_i32_e32 vcc, -2, v182
	global_load_dwordx4 v[114:117], v[90:91], off
	v_xor_b32_e32 v94, 32, v219
	v_cndmask_b32_e32 v0, 0, v0, vcc
	v_lshl_add_u64 v[90:91], v[0:1], 2, v[174:175]
	global_load_dwordx4 v[118:121], v[90:91], off
	v_min_i32_e32 v0, 0x17ffd, v182
	v_lshl_add_u32 v0, v0, 4, 32
	v_cmp_lt_i32_e32 vcc, -3, v182
	v_lshl_or_b32 v180, s42, 7, v237
	v_ashrrev_i32_e32 v181, 31, v180
	v_cndmask_b32_e32 v0, 0, v0, vcc
	v_lshl_add_u64 v[90:91], v[0:1], 2, v[174:175]
	global_load_dwordx4 v[196:199], v[90:91], off
	v_min_i32_e32 v0, 0x17ffc, v182
	v_lshl_add_u32 v0, v0, 4, 48
	v_cmp_lt_i32_e32 vcc, -4, v182
	v_readlane_b32 s0, v255, 12
	v_lshlrev_b64 v[224:225], 2, v[180:181]
	v_cndmask_b32_e32 v0, 0, v0, vcc
	v_lshl_add_u64 v[90:91], v[0:1], 2, v[174:175]
	v_min_i32_e32 v0, 0x17ffb, v182
	global_load_dwordx4 v[162:165], v[90:91], off
	v_lshl_add_u32 v0, v0, 4, 64
	v_cmp_lt_i32_e32 vcc, -5, v182
	v_readlane_b32 s1, v255, 13
	s_waitcnt vmcnt(0)
	v_mov_b32_e32 v188, v115
	v_cndmask_b32_e32 v0, 0, v0, vcc
	v_lshl_add_u64 v[90:91], v[0:1], 2, v[174:175]
	v_min_i32_e32 v0, 0x17ffa, v182
	global_load_dwordx4 v[200:203], v[90:91], off
	v_min_i32_e32 v90, 0x17ff9, v182
	v_lshl_add_u32 v0, v0, 4, v220
	v_cmp_lt_i32_e32 vcc, -6, v182
	v_min_i32_e32 v91, 0x17ff8, v182
	v_lshl_add_u32 v95, v90, 4, v221
	v_cndmask_b32_e32 v0, 0, v0, vcc
	v_cmp_lt_i32_e32 vcc, -7, v182
	v_lshl_add_u32 v96, v91, 4, v222
	v_lshl_add_u64 v[90:91], v[0:1], 2, v[174:175]
	v_cndmask_b32_e32 v0, 0, v95, vcc
	v_cmp_lt_i32_e32 vcc, -8, v182
	global_load_dwordx4 v[204:207], v[90:91], off
	v_lshl_add_u64 v[90:91], v[0:1], 2, v[174:175]
	v_cndmask_b32_e32 v0, 0, v96, vcc
	global_load_dwordx4 v[208:211], v[90:91], off
	v_lshl_add_u64 v[90:91], v[0:1], 2, v[174:175]
	global_load_dwordx4 v[212:215], v[90:91], off
	v_add_u32_e32 v0, 64, v93
	v_cmp_lt_i32_e32 vcc, v92, v0
	v_mov_b32_e32 v189, v116
	v_mov_b32_e32 v115, v117
	v_cndmask_b32_e32 v90, v219, v92, vcc
	v_cmp_lt_i32_e32 vcc, v94, v0
	v_pk_add_f32 v[114:115], v[188:189], v[114:115]
	v_mov_b32_e32 v116, v119
	v_cndmask_b32_e32 v0, v219, v94, vcc
	v_mov_b32_e32 v117, v120
	v_mov_b32_e32 v119, v121
	v_lshlrev_b32_e32 v183, 2, v90
	v_lshlrev_b32_e32 v228, 2, v0
	v_add_f32_e32 v0, v114, v115
	v_pk_add_f32 v[114:115], v[116:117], v[118:119]
	ds_bpermute_b32 v118, v183, v0
	v_add_f32_e32 v119, v114, v115
	v_lshl_add_u64 v[184:185], s[0:1], 0, v[224:225]
	v_readlane_b32 s0, v255, 4
	ds_bpermute_b32 v120, v183, v119
	v_readlane_b32 s1, v255, 5
	v_mov_b32_e32 v116, v197
	v_mov_b32_e32 v117, v198
	v_lshl_add_u64 v[90:91], s[0:1], 0, v[224:225]
	v_readlane_b32 s0, v255, 6
	v_readlane_b32 s1, v255, 7
	v_mov_b32_e32 v197, v199
	s_waitcnt lgkmcnt(1)
	v_add_f32_e32 v0, v0, v118
	v_lshl_add_u64 v[92:93], s[0:1], 0, v[224:225]
	v_readlane_b32 s0, v255, 16
	v_readlane_b32 s1, v255, 17
	v_pk_add_f32 v[114:115], v[116:117], v[196:197]
	ds_bpermute_b32 v116, v228, v0
	s_waitcnt lgkmcnt(1)
	v_add_f32_e32 v117, v119, v120
	v_lshl_add_u64 v[186:187], s[0:1], 0, v[224:225]
	v_readlane_b32 s0, v255, 8
	ds_bpermute_b32 v118, v228, v117
	v_readlane_b32 s1, v255, 9
	s_waitcnt lgkmcnt(1)
	v_add_f32_e32 v0, v0, v116
	v_add_f32_e32 v189, v114, v115
	v_lshl_add_u64 v[94:95], s[0:1], 0, v[224:225]
	v_readlane_b32 s0, v255, 10
	v_readlane_b32 s1, v255, 11
	v_fmamk_f32 v0, v0, 0x3a800000, v218
	s_waitcnt lgkmcnt(0)
	v_add_f32_e32 v114, v117, v118
	v_lshl_add_u64 v[96:97], s[0:1], 0, v[224:225]
	v_readlane_b32 s0, v255, 14
	global_load_dwordx4 v[98:101], v[184:185], off
	global_load_dwordx4 v[110:113], v[90:91], off
	global_load_dwordx4 v[102:105], v[92:93], off
	global_load_dwordx4 v[106:109], v[186:187], off
	s_nop 0
	global_load_dwordx4 v[90:93], v[94:95], off
	s_nop 0
	global_load_dwordx4 v[94:97], v[96:97], off
	v_readlane_b32 s1, v255, 15
	v_rsq_f32_e32 v196, v0
	v_fmamk_f32 v0, v114, 0x3a800000, v218
	v_lshl_add_u64 v[114:115], s[0:1], 0, v[224:225]
	v_readlane_b32 s0, v255, 18
	v_readlane_b32 s1, v255, 19
	global_load_dwordx4 v[114:117], v[114:115], off
	v_mov_b32_e32 v198, v163
	v_lshl_add_u64 v[118:119], s[0:1], 0, v[224:225]
	global_load_dwordx4 v[118:121], v[118:119], off
	v_mov_b32_e32 v199, v164
	v_mov_b32_e32 v163, v165
	v_pk_add_f32 v[162:163], v[198:199], v[162:163]
	v_rsq_f32_e32 v188, v0
	v_add_f32_e32 v0, v162, v163
	ds_bpermute_b32 v164, v183, v0
	s_waitcnt vmcnt(11)
	v_mov_b32_e32 v162, v201
	v_mov_b32_e32 v163, v202
	v_mov_b32_e32 v201, v203
	v_pk_add_f32 v[162:163], v[162:163], v[200:201]
	s_waitcnt lgkmcnt(0)
	v_add_f32_e32 v241, v0, v164
	v_add_f32_e32 v162, v162, v163
	ds_bpermute_b32 v163, v183, v162
	ds_bpermute_b32 v197, v183, v189
	s_mov_b32 s0, 0x18000
	v_cmp_gt_i32_e32 vcc, s0, v182
	v_readlane_b32 s0, v255, 0
	s_waitcnt lgkmcnt(1)
	v_add_f32_e32 v239, v162, v163
	s_waitcnt vmcnt(10)
	v_mov_b32_e32 v162, v205
	v_mov_b32_e32 v163, v206
	v_mov_b32_e32 v205, v207
	s_waitcnt vmcnt(8)
	v_mov_b32_e32 v164, v213
	v_mov_b32_e32 v165, v214
	v_mov_b32_e32 v213, v215
	v_pk_add_f32 v[164:165], v[164:165], v[212:213]
	v_pk_add_f32 v[162:163], v[162:163], v[204:205]
	v_add_f32_e32 v164, v164, v165
	ds_bpermute_b32 v165, v183, v164
	v_add_f32_e32 v0, v162, v163
	v_mov_b32_e32 v162, v209
	v_mov_b32_e32 v163, v210
	v_mov_b32_e32 v209, v211
	v_pk_add_f32 v[162:163], v[162:163], v[208:209]
	s_waitcnt lgkmcnt(0)
;     __device__ __forceinline__ void operator()(f32x4 (&acc)[2][2][4][2], const Unit& u, int wr, int wc, int fr, int fq) const {
;     ...
;         { float rs[8]; load_rs8(ss, t0, fq, rs, M_TOK - 1);
; #pragma unroll
;           for (int ai = 0; ai < 2; ++ai)
; #pragma unroll
;             for (int m = 0; m < 4; ++m)
; #pragma unroll
;                 for (int bj = 0; bj < 2; ++bj)
; #pragma unroll
;                     for (int n = 0; n < 2; ++n) acc[ai][bj][m][n] = acc[ai][bj][m][n] * rs[4 * ai + m]; }
;         unsigned vmask = 0, smask = 0, emask = 0;
; #pragma unroll
;         for (int j = 0; j < 8; ++j) { const int t = t0 + j, loc = fr * 8 + j;
;             if (loc >= 1 && loc <= 126 && t < M_TOK) vmask |= 1u << j;
;             const int sm = (t < NPROMPT) ? (SEQ_P - 1) : (SEQ_S - 1);
;             if ((t & sm) == 0) smask |= 1u << j;
;             if ((t & sm) == sm) emask |= 1u << j; }
; #pragma unroll
;         for (int n = 0; n < 2; ++n) {
;             const int cg_ = 128 * u.pn + 32 * wc + 8 * fq + 4 * n;
;             const f32x4 w0g = *(const f32x4*)(cw + cg_), w1g = *(const f32x4*)(cw + 4096 + cg_), w2g = *(const f32x4*)(cw + 8192 + cg_), bg = *(const f32x4*)(cb + cg_);
;             const f32x4 w0v = *(const f32x4*)(cw + 2048 + cg_), w1v = *(const f32x4*)(cw + 4096 + 2048 + cg_), w2v = *(const f32x4*)(cw + 8192 + 2048 + cg_), bv = *(const f32x4*)(cb + 2048 + cg_);
;             float h[8][4];
; #pragma unroll
;             for (int i = 0; i < 4; ++i) {
;                 float ag[8], av[8];
; #pragma unroll
;                 for (int j = 0; j < 8; ++j) { ag[j] = acc[j >> 2][0][j & 3][n][i]; av[j] = acc[j >> 2][1][j & 3][n][i]; }
;                 const float lg = dpp_shr1(ag[7]), rg = dpp_shl1(ag[0]), lv = dpp_shr1(av[7]), rv = dpp_shl1(av[0]);
; #pragma unroll
;                 for (int j = 0; j < 8; ++j) {
;                     float Lg = j == 0 ? lg : ag[j == 0 ? 0 : j - 1], Rg = j == 7 ? rg : ag[j == 7 ? 7 : j + 1];
;                     float Lv = j == 0 ? lv : av[j == 0 ? 0 : j - 1], Rv = j == 7 ? rv : av[j == 7 ? 7 : j + 1];
;                     if ((smask >> j) & 1u) { Lg = 0.f; Lv = 0.f; }
;                     if ((emask >> j) & 1u) { Rg = 0.f; Rv = 0.f; }
;                     const float cgv = w0g[i] * Lg + w1g[i] * ag[j] + w2g[i] * Rg + bg[i];
;                     const float cvv = w0v[i] * Lv + w1v[i] * av[j] + w2v[i] * Rv + bv[i];
	v_add_f32_e32 v164, v164, v165
	v_add_f32_e32 v162, v162, v163
	v_add_f32_e32 v200, v189, v197
	ds_bpermute_b32 v189, v183, v0
	ds_bpermute_b32 v163, v183, v162
	ds_bpermute_b32 v165, v228, v164
	v_readlane_b32 s1, v255, 1
	ds_bpermute_b32 v201, v228, v200
	s_waitcnt lgkmcnt(3)
	v_add_f32_e32 v189, v0, v189
	s_waitcnt lgkmcnt(2)
	v_add_f32_e32 v0, v162, v163
	s_waitcnt lgkmcnt(1)
	v_add_f32_e32 v162, v164, v165
	ds_bpermute_b32 v197, v228, v189
	ds_bpermute_b32 v163, v228, v0
	v_fmamk_f32 v162, v162, 0x3a800000, v218
	v_rsq_f32_e32 v162, v162
	ds_bpermute_b32 v242, v228, v241
	ds_bpermute_b32 v240, v228, v239
	s_and_b64 s[82:83], s[0:1], vcc
	s_mov_b32 s0, 0x8000
	v_cmp_gt_i32_e32 vcc, s0, v182
	s_waitcnt lgkmcnt(3)
	v_pk_mul_f32 v[202:203], v[152:153], v[196:197] op_sel_hi:[1,0]
	s_waitcnt lgkmcnt(2)
	v_pk_mul_f32 v[152:153], v[138:139], v[162:163] op_sel_hi:[1,0]
	v_cndmask_b32_e32 v138, v223, v227, vcc
	v_pk_mul_f32 v[210:211], v[160:161], v[196:197] op_sel_hi:[1,0]
	v_pk_mul_f32 v[214:215], v[158:159], v[196:197] op_sel_hi:[1,0]
	v_pk_mul_f32 v[212:213], v[150:151], v[196:197] op_sel_hi:[1,0]
	v_pk_mul_f32 v[206:207], v[146:147], v[188:189] op_sel_hi:[1,0]
	v_pk_mul_f32 v[164:165], v[148:149], v[188:189] op_sel_hi:[1,0]
	v_pk_mul_f32 v[148:149], v[144:145], v[162:163] op_sel_hi:[1,0]
	v_pk_mul_f32 v[158:159], v[142:143], v[162:163] op_sel_hi:[1,0]
	v_pk_mul_f32 v[146:147], v[140:141], v[162:163] op_sel_hi:[1,0]
	v_or_b32_e32 v138, v138, v182
	v_pk_mul_f32 v[208:209], v[154:155], v[188:189] op_sel_hi:[1,0]
	v_pk_mul_f32 v[198:199], v[156:157], v[188:189] op_sel_hi:[1,0]
	v_cmp_eq_u32_e64 s[42:43], -1, v138
	v_mov_b32_dpp v140, v158 row_shr:1 row_mask:0xf bank_mask:0xf bound_ctrl:1
	v_mov_b32_dpp v160, v214 row_shl:1 row_mask:0xf bank_mask:0xf bound_ctrl:1
	v_mov_b32_dpp v138, v152 row_shr:1 row_mask:0xf bank_mask:0xf bound_ctrl:1
	v_mov_b32_dpp v154, v212 row_shl:1 row_mask:0xf bank_mask:0xf bound_ctrl:1
	v_mov_b32_dpp v141, v159 row_shr:1 row_mask:0xf bank_mask:0xf bound_ctrl:1
	v_mov_b32_dpp v161, v215 row_shl:1 row_mask:0xf bank_mask:0xf bound_ctrl:1
	v_mov_b32_dpp v139, v153 row_shr:1 row_mask:0xf bank_mask:0xf bound_ctrl:1
	v_mov_b32_dpp v155, v213 row_shl:1 row_mask:0xf bank_mask:0xf bound_ctrl:1
	v_mov_b32_dpp v144, v148 row_shr:1 row_mask:0xf bank_mask:0xf bound_ctrl:1
	v_mov_b32_dpp v156, v210 row_shl:1 row_mask:0xf bank_mask:0xf bound_ctrl:1
	v_mov_b32_dpp v142, v146 row_shr:1 row_mask:0xf bank_mask:0xf bound_ctrl:1
	v_mov_b32_dpp v150, v202 row_shl:1 row_mask:0xf bank_mask:0xf bound_ctrl:1
	v_mov_b32_dpp v145, v149 row_shr:1 row_mask:0xf bank_mask:0xf bound_ctrl:1
	v_mov_b32_dpp v157, v211 row_shl:1 row_mask:0xf bank_mask:0xf bound_ctrl:1
	v_mov_b32_dpp v143, v147 row_shr:1 row_mask:0xf bank_mask:0xf bound_ctrl:1
	v_mov_b32_dpp v151, v203 row_shl:1 row_mask:0xf bank_mask:0xf bound_ctrl:1
	v_ashrrev_i32_e32 v183, 31, v182
	s_waitcnt vmcnt(0)
	s_and_saveexec_b64 s[0:1], s[82:83]
	s_cbranch_execz .LBB0_122
	v_pk_mul_f32 v[144:145], v[100:101], v[144:145]
	v_cndmask_b32_e64 v225, v199, 0, s[42:43]
	v_cndmask_b32_e64 v224, v198, 0, s[42:43]
	v_pk_fma_f32 v[144:145], v[210:211], v[112:113], v[144:145]
	v_pk_mul_f32 v[142:143], v[92:93], v[142:143]
	v_pk_fma_f32 v[144:145], v[224:225], v[104:105], v[144:145]
	v_cndmask_b32_e64 v205, v165, 0, s[42:43]
	v_pk_add_f32 v[144:145], v[108:109], v[144:145]
	v_cndmask_b32_e64 v204, v164, 0, s[42:43]
	v_mul_f32_e32 v224, 0xbdd2d3e7, v145
	v_fmaak_f32 v224, v145, v224, 0xc0135761
	v_mul_f32_e32 v225, 0xbdd2d3e7, v144
	v_mul_f32_e32 v224, v145, v224
	v_fmaak_f32 v225, v144, v225, 0xc0135761
	v_mul_f32_e32 v225, v144, v225
	v_exp_f32_e32 v224, v224
	s_nop 0
	v_exp_f32_e32 v228, v225
	v_pk_fma_f32 v[142:143], v[202:203], v[96:97], v[142:143]
	v_pk_mul_f32 v[140:141], v[98:99], v[140:141]
	v_pk_fma_f32 v[142:143], v[204:205], v[116:117], v[142:143]
	v_cndmask_b32_e64 v205, v209, 0, s[42:43]
	v_cndmask_b32_e64 v204, v208, 0, s[42:43]
	v_pk_fma_f32 v[140:141], v[214:215], v[110:111], v[140:141]
	v_add_f32_e32 v224, 1.0, v224
	v_pk_fma_f32 v[140:141], v[204:205], v[102:103], v[140:141]
	v_rcp_f32_e32 v225, v224
	v_pk_add_f32 v[140:141], v[106:107], v[140:141]
	v_add_f32_e32 v224, 1.0, v228
	v_mul_f32_e32 v204, 0xbdd2d3e7, v141
	v_rcp_f32_e32 v224, v224
	v_fmaak_f32 v204, v141, v204, 0xc0135761
	v_mul_f32_e32 v205, 0xbdd2d3e7, v140
	v_mul_f32_e32 v204, v141, v204
	v_fmaak_f32 v205, v140, v205, 0xc0135761
	v_mul_f32_e32 v205, v140, v205
	v_exp_f32_e32 v204, v204
	s_nop 0
	v_pk_mul_f32 v[144:145], v[144:145], v[224:225]
	v_exp_f32_e32 v224, v205
	v_add_f32_e32 v204, 1.0, v204
	v_rcp_f32_e32 v205, v204
	v_pk_add_f32 v[142:143], v[120:121], v[142:143]
	v_add_f32_e32 v204, 1.0, v224
	v_rcp_f32_e32 v204, v204
	v_pk_mul_f32 v[138:139], v[90:91], v[138:139]
	v_pk_mul_f32 v[142:143], v[142:143], v[144:145]
	v_cndmask_b32_e64 v145, v207, 0, s[42:43]
	v_cndmask_b32_e64 v144, v206, 0, s[42:43]
	v_pk_fma_f32 v[138:139], v[212:213], v[94:95], v[138:139]
	v_pk_mul_f32 v[140:141], v[140:141], v[204:205]
	v_pk_fma_f32 v[138:139], v[144:145], v[114:115], v[138:139]
	s_nop 0
	v_pk_add_f32 v[138:139], v[118:119], v[138:139]
	s_nop 0
	v_pk_mul_f32 v[138:139], v[138:139], v[140:141]
	v_lshlrev_b64 v[140:141], 12, v[182:183]
	v_lshl_add_u64 v[140:141], s[70:71], 0, v[140:141]
	v_cvt_pk_bf16_f32 v138, v138, v139
	v_cvt_pk_bf16_f32 v139, v142, v143
	v_lshl_add_u64 v[140:141], v[180:181], 1, v[140:141]
	global_store_dwordx2 v[140:141], v[138:139], off
; __device__ __forceinline__ unsigned cvt_pk_bf16(float lo, float hi) { f32x2 v = {lo, hi}; bf16x2_t_ b = __builtin_convertvector(v, bf16x2_t_); return __builtin_bit_cast(unsigned, b); }
; __device__ __forceinline__ float dpp_shr1(float v) { return __int_as_float(__builtin_amdgcn_update_dpp(0, __float_as_int(v), 0x111, 0xF, 0xF, true)); }
; __device__ __forceinline__ float dpp_shl1(float v) { return __int_as_float(__builtin_amdgcn_update_dpp(0, __float_as_int(v), 0x101, 0xF, 0xF, true)); }
;     __device__ __forceinline__ void operator()(f32x4 (&acc)[2][2][4][2], const Unit& u, int wr, int wc, int fr, int fq) const {
;     ...
;             for (int i = 0; i < 4; ++i) {
;                 float ag[8], av[8];
; #pragma unroll
;                 for (int j = 0; j < 8; ++j) { ag[j] = acc[j >> 2][0][j & 3][n][i]; av[j] = acc[j >> 2][1][j & 3][n][i]; }
;                 const float lg = dpp_shr1(ag[7]), rg = dpp_shl1(ag[0]), lv = dpp_shr1(av[7]), rv = dpp_shl1(av[0]);
; #pragma unroll
;                 for (int j = 0; j < 8; ++j) {
;                     float Lg = j == 0 ? lg : ag[j == 0 ? 0 : j - 1], Rg = j == 7 ? rg : ag[j == 7 ? 7 : j + 1];
;                     float Lv = j == 0 ? lv : av[j == 0 ? 0 : j - 1], Rv = j == 7 ? rv : av[j == 7 ? 7 : j + 1];
;                     if ((smask >> j) & 1u) { Lg = 0.f; Lv = 0.f; }
;                     if ((emask >> j) & 1u) { Rg = 0.f; Rv = 0.f; }
;                     const float cgv = w0g[i] * Lg + w1g[i] * ag[j] + w2g[i] * Rg + bg[i];
;                     const float cvv = w0v[i] * Lv + w1v[i] * av[j] + w2v[i] * Rv + bv[i];
;                     h[j][i] = gelu_t(cgv) * cvv;
;                 }
;             }
; #pragma unroll
;             for (int j = 0; j < 8; ++j) if ((vmask >> j) & 1u) { u32x2 w; w.x = cvt_pk_bf16(h[j][0], h[j][1]); w.y = cvt_pk_bf16(h[j][2], h[j][3]);
;                 *(u32x2*)(H2 + (size_t)(t0 + j) * 2048 + cg_) = w; }
.LBB0_122:
	s_or_b64 exec, exec, s[0:1]
	v_add_f32_e32 v138, v200, v201
	v_fmamk_f32 v138, v138, 0x3a800000, v218
	v_rsq_f32_e32 v138, v138
	s_mov_b32 s0, 0x17fff
	v_cmp_gt_i32_e64 s[56:57], s0, v182
	s_movk_i32 s0, 0x7fff
	v_cmp_gt_i32_e32 vcc, s0, v182
	v_pk_mul_f32 v[200:201], v[130:131], v[138:139] op_sel_hi:[1,0]
	v_add_u32_e32 v130, 1, v182
	v_cndmask_b32_e32 v131, v217, v226, vcc
	v_and_b32_e32 v131, v131, v130
	v_pk_mul_f32 v[142:143], v[136:137], v[138:139] op_sel_hi:[1,0]
	v_pk_mul_f32 v[204:205], v[134:135], v[138:139] op_sel_hi:[1,0]
	v_pk_mul_f32 v[132:133], v[132:133], v[138:139] op_sel_hi:[1,0]
	v_cmp_eq_u32_e32 vcc, 0, v131
	v_ashrrev_i32_e32 v131, 31, v130
	s_and_saveexec_b64 s[0:1], s[56:57]
	s_cbranch_execz .LBB0_124
	v_cndmask_b32_e64 v135, v215, 0, vcc
	v_cndmask_b32_e64 v134, v214, 0, vcc
	v_pk_mul_f32 v[136:137], v[208:209], v[110:111]
	v_cndmask_b32_e64 v141, v213, 0, vcc
	v_pk_fma_f32 v[134:135], v[134:135], v[98:99], v[136:137]
	v_cndmask_b32_e64 v140, v212, 0, vcc
	v_pk_fma_f32 v[134:135], v[204:205], v[102:103], v[134:135]
	v_pk_mul_f32 v[144:145], v[206:207], v[94:95]
	v_pk_add_f32 v[134:135], v[106:107], v[134:135]
	v_pk_fma_f32 v[140:141], v[140:141], v[90:91], v[144:145]
	v_mul_f32_e32 v136, 0xbdd2d3e7, v134
	v_mul_f32_e32 v137, 0xbdd2d3e7, v135
	v_fmaak_f32 v136, v134, v136, 0xc0135761
	v_fmaak_f32 v137, v135, v137, 0xc0135761
	v_mul_f32_e32 v136, v134, v136
	v_mul_f32_e32 v137, v135, v137
	v_exp_f32_e32 v136, v136
	v_exp_f32_e32 v137, v137
	v_pk_fma_f32 v[140:141], v[200:201], v[114:115], v[140:141]
	v_cndmask_b32_e64 v145, v203, 0, vcc
	v_add_f32_e32 v136, 1.0, v136
	v_add_f32_e32 v137, 1.0, v137
	v_rcp_f32_e32 v136, v136
	v_rcp_f32_e32 v137, v137
	v_pk_add_f32 v[140:141], v[118:119], v[140:141]
	v_cndmask_b32_e64 v144, v202, 0, vcc
	v_pk_mul_f32 v[202:203], v[164:165], v[96:97]
	v_pk_mul_f32 v[134:135], v[134:135], v[136:137]
	v_cndmask_b32_e64 v137, v211, 0, vcc
	v_pk_mul_f32 v[134:135], v[140:141], v[134:135]
	v_cndmask_b32_e64 v136, v210, 0, vcc
	v_pk_mul_f32 v[140:141], v[198:199], v[112:113]
	v_pk_fma_f32 v[144:145], v[144:145], v[92:93], v[202:203]
	v_pk_fma_f32 v[136:137], v[136:137], v[100:101], v[140:141]
	v_pk_fma_f32 v[144:145], v[132:133], v[116:117], v[144:145]
	v_pk_fma_f32 v[136:137], v[142:143], v[104:105], v[136:137]
	v_pk_add_f32 v[144:145], v[120:121], v[144:145]
	v_pk_add_f32 v[136:137], v[108:109], v[136:137]
	v_cvt_pk_bf16_f32 v134, v134, v135
	v_mul_f32_e32 v139, 0xbdd2d3e7, v136
	v_fmaak_f32 v139, v136, v139, 0xc0135761
	v_mul_f32_e32 v139, v136, v139
	v_exp_f32_e32 v139, v139
	s_nop 0
	v_add_f32_e32 v139, 1.0, v139
	v_rcp_f32_e32 v140, v139
	v_mul_f32_e32 v139, 0xbdd2d3e7, v137
	v_fmaak_f32 v139, v137, v139, 0xc0135761
	v_mul_f32_e32 v139, v137, v139
	v_exp_f32_e32 v139, v139
	s_nop 0
	v_add_f32_e32 v139, 1.0, v139
	v_rcp_f32_e32 v141, v139
	s_nop 0
	v_pk_mul_f32 v[136:137], v[136:137], v[140:141]
	s_nop 0
	v_pk_mul_f32 v[136:137], v[144:145], v[136:137]
	s_nop 0
	v_cvt_pk_bf16_f32 v135, v136, v137
	v_lshlrev_b64 v[136:137], 12, v[130:131]
	v_lshl_add_u64 v[136:137], s[70:71], 0, v[136:137]
	v_lshl_add_u64 v[136:137], v[180:181], 1, v[136:137]
	global_store_dwordx2 v[136:137], v[134:135], off
.LBB0_124:
	s_or_b64 exec, exec, s[0:1]
	s_waitcnt lgkmcnt(1)
	v_add_f32_e32 v134, v241, v242
	v_fmamk_f32 v134, v134, 0x3a800000, v218
	v_rsq_f32_e32 v136, v134
	s_mov_b32 s0, 0x17ffe
	v_cmp_gt_i32_e64 s[58:59], s0, v182
	s_movk_i32 s0, 0x7ffe
	v_cmp_gt_i32_e64 s[0:1], s0, v182
	v_pk_mul_f32 v[144:145], v[122:123], v[136:137] op_sel_hi:[1,0]
	v_add_u32_e32 v122, 2, v182
	v_cndmask_b32_e64 v123, v223, v227, s[0:1]
	v_or_b32_e32 v123, v123, v122
	v_pk_mul_f32 v[134:135], v[128:129], v[136:137] op_sel_hi:[1,0]
	v_pk_mul_f32 v[202:203], v[126:127], v[136:137] op_sel_hi:[1,0]
	v_pk_mul_f32 v[128:129], v[124:125], v[136:137] op_sel_hi:[1,0]
	v_cmp_eq_u32_e64 s[44:45], -1, v123
	v_ashrrev_i32_e32 v123, 31, v122
	s_and_saveexec_b64 s[0:1], s[58:59]
	s_cbranch_execz .LBB0_126
	v_pk_mul_f32 v[126:127], v[204:205], v[110:111]
	v_cndmask_b32_e64 v125, v203, 0, s[44:45]
	v_cndmask_b32_e64 v124, v202, 0, s[44:45]
	v_pk_fma_f32 v[126:127], v[208:209], v[98:99], v[126:127]
	v_pk_mul_f32 v[208:209], v[200:201], v[94:95]
	v_pk_fma_f32 v[124:125], v[124:125], v[102:103], v[126:127]
	v_cndmask_b32_e64 v141, v145, 0, s[44:45]
	v_pk_add_f32 v[124:125], v[106:107], v[124:125]
	v_cndmask_b32_e64 v140, v144, 0, s[44:45]
	v_mul_f32_e32 v126, 0xbdd2d3e7, v124
	v_mul_f32_e32 v127, 0xbdd2d3e7, v125
	v_fmaak_f32 v126, v124, v126, 0xc0135761
	v_fmaak_f32 v127, v125, v127, 0xc0135761
	v_mul_f32_e32 v126, v124, v126
	v_mul_f32_e32 v127, v125, v127
	v_exp_f32_e32 v126, v126
	v_exp_f32_e32 v127, v127
	v_pk_fma_f32 v[206:207], v[206:207], v[90:91], v[208:209]
	v_add_f32_e32 v126, 1.0, v126
	v_add_f32_e32 v127, 1.0, v127
	v_rcp_f32_e32 v126, v126
	v_rcp_f32_e32 v127, v127
	v_pk_fma_f32 v[140:141], v[140:141], v[114:115], v[206:207]
	v_pk_mul_f32 v[206:207], v[132:133], v[96:97]
	v_pk_add_f32 v[140:141], v[118:119], v[140:141]
	v_pk_mul_f32 v[124:125], v[124:125], v[126:127]
	v_cndmask_b32_e64 v127, v135, 0, s[44:45]
	v_pk_mul_f32 v[124:125], v[140:141], v[124:125]
	v_pk_mul_f32 v[140:141], v[142:143], v[112:113]
	v_cndmask_b32_e64 v126, v134, 0, s[44:45]
	v_pk_fma_f32 v[140:141], v[198:199], v[100:101], v[140:141]
	v_cndmask_b32_e64 v199, v129, 0, s[44:45]
	v_pk_fma_f32 v[126:127], v[126:127], v[104:105], v[140:141]
	v_cndmask_b32_e64 v198, v128, 0, s[44:45]
	v_pk_add_f32 v[126:127], v[108:109], v[126:127]
	v_pk_fma_f32 v[164:165], v[164:165], v[92:93], v[206:207]
	v_mul_f32_e32 v137, 0xbdd2d3e7, v126
	v_fmaak_f32 v137, v126, v137, 0xc0135761
	v_mul_f32_e32 v137, v126, v137
	v_exp_f32_e32 v137, v137
	v_pk_fma_f32 v[164:165], v[198:199], v[116:117], v[164:165]
	v_cvt_pk_bf16_f32 v124, v124, v125
	v_pk_add_f32 v[164:165], v[120:121], v[164:165]
	v_add_f32_e32 v137, 1.0, v137
	v_rcp_f32_e32 v140, v137
	v_mul_f32_e32 v137, 0xbdd2d3e7, v127
	v_fmaak_f32 v137, v127, v137, 0xc0135761
	v_mul_f32_e32 v137, v127, v137
	v_exp_f32_e32 v137, v137
	s_nop 0
	v_add_f32_e32 v137, 1.0, v137
	v_rcp_f32_e32 v141, v137
	s_nop 0
	v_pk_mul_f32 v[126:127], v[126:127], v[140:141]
	s_nop 0
	v_pk_mul_f32 v[126:127], v[164:165], v[126:127]
	s_nop 0
	v_cvt_pk_bf16_f32 v125, v126, v127
	v_lshlrev_b64 v[126:127], 12, v[122:123]
	v_lshl_add_u64 v[126:127], s[70:71], 0, v[126:127]
	v_lshl_add_u64 v[126:127], v[180:181], 1, v[126:127]
	global_store_dwordx2 v[126:127], v[124:125], off
; __device__ __forceinline__ unsigned cvt_pk_bf16(float lo, float hi) { f32x2 v = {lo, hi}; bf16x2_t_ b = __builtin_convertvector(v, bf16x2_t_); return __builtin_bit_cast(unsigned, b); }
; __device__ __forceinline__ float dpp_shr1(float v) { return __int_as_float(__builtin_amdgcn_update_dpp(0, __float_as_int(v), 0x111, 0xF, 0xF, true)); }
; __device__ __forceinline__ float dpp_shl1(float v) { return __int_as_float(__builtin_amdgcn_update_dpp(0, __float_as_int(v), 0x101, 0xF, 0xF, true)); }
;     __device__ __forceinline__ void operator()(f32x4 (&acc)[2][2][4][2], const Unit& u, int wr, int wc, int fr, int fq) const {
;     ...
;             for (int i = 0; i < 4; ++i) {
;                 float ag[8], av[8];
; #pragma unroll
;                 for (int j = 0; j < 8; ++j) { ag[j] = acc[j >> 2][0][j & 3][n][i]; av[j] = acc[j >> 2][1][j & 3][n][i]; }
;                 const float lg = dpp_shr1(ag[7]), rg = dpp_shl1(ag[0]), lv = dpp_shr1(av[7]), rv = dpp_shl1(av[0]);
; #pragma unroll
;                 for (int j = 0; j < 8; ++j) {
;                     float Lg = j == 0 ? lg : ag[j == 0 ? 0 : j - 1], Rg = j == 7 ? rg : ag[j == 7 ? 7 : j + 1];
;                     float Lv = j == 0 ? lv : av[j == 0 ? 0 : j - 1], Rv = j == 7 ? rv : av[j == 7 ? 7 : j + 1];
;                     if ((smask >> j) & 1u) { Lg = 0.f; Lv = 0.f; }
;                     if ((emask >> j) & 1u) { Rg = 0.f; Rv = 0.f; }
;                     const float cgv = w0g[i] * Lg + w1g[i] * ag[j] + w2g[i] * Rg + bg[i];
;                     const float cvv = w0v[i] * Lv + w1v[i] * av[j] + w2v[i] * Rv + bv[i];
;                     h[j][i] = gelu_t(cgv) * cvv;
;                 }
;             }
; #pragma unroll
;             for (int j = 0; j < 8; ++j) if ((vmask >> j) & 1u) { u32x2 w; w.x = cvt_pk_bf16(h[j][0], h[j][1]); w.y = cvt_pk_bf16(h[j][2], h[j][3]);
;                 *(u32x2*)(H2 + (size_t)(t0 + j) * 2048 + cg_) = w; }
.LBB0_126:
	s_or_b64 exec, exec, s[0:1]
	s_waitcnt lgkmcnt(0)
	v_add_f32_e32 v124, v239, v240
	v_fmamk_f32 v124, v124, 0x3a800000, v218
	s_mov_b32 s0, 0x17ffd
	v_rsq_f32_e32 v140, v124
	v_cmp_gt_i32_e64 s[60:61], s0, v182
	s_movk_i32 s0, 0x7ffd
	v_cmp_gt_i32_e64 s[0:1], s0, v182
	v_add_u32_e32 v124, 3, v182
	v_pk_mul_f32 v[88:89], v[88:89], v[140:141] op_sel_hi:[1,0]
	v_cndmask_b32_e64 v125, v217, v226, s[0:1]
	v_and_b32_e32 v125, v125, v124
	v_pk_mul_f32 v[86:87], v[86:87], v[140:141] op_sel_hi:[1,0]
	v_pk_mul_f32 v[84:85], v[84:85], v[140:141] op_sel_hi:[1,0]
	v_pk_mul_f32 v[82:83], v[82:83], v[140:141] op_sel_hi:[1,0]
	v_cmp_eq_u32_e64 s[46:47], 0, v125
	v_ashrrev_i32_e32 v125, 31, v124
	s_and_saveexec_b64 s[0:1], s[60:61]
	s_cbranch_execz .LBB0_128
	v_cndmask_b32_e64 v127, v205, 0, s[46:47]
	v_cndmask_b32_e64 v126, v204, 0, s[46:47]
	v_pk_mul_f32 v[164:165], v[202:203], v[110:111]
	v_cndmask_b32_e64 v143, v143, 0, s[46:47]
	v_pk_fma_f32 v[126:127], v[126:127], v[98:99], v[164:165]
	v_cndmask_b32_e64 v142, v142, 0, s[46:47]
	v_pk_fma_f32 v[126:127], v[86:87], v[102:103], v[126:127]
	v_cndmask_b32_e64 v199, v201, 0, s[46:47]
	v_pk_add_f32 v[126:127], v[106:107], v[126:127]
	v_cndmask_b32_e64 v198, v200, 0, s[46:47]
	v_mul_f32_e32 v137, 0xbdd2d3e7, v126
	v_fmaak_f32 v137, v126, v137, 0xc0135761
	v_mul_f32_e32 v137, v126, v137
	v_exp_f32_e32 v137, v137
	v_pk_mul_f32 v[200:201], v[144:145], v[94:95]
	v_cndmask_b32_e64 v133, v133, 0, s[46:47]
	v_pk_fma_f32 v[198:199], v[198:199], v[90:91], v[200:201]
	v_add_f32_e32 v137, 1.0, v137
	v_rcp_f32_e32 v164, v137
	v_mul_f32_e32 v137, 0xbdd2d3e7, v127
	v_fmaak_f32 v137, v127, v137, 0xc0135761
	v_mul_f32_e32 v137, v127, v137
	v_exp_f32_e32 v137, v137
	v_pk_fma_f32 v[198:199], v[82:83], v[114:115], v[198:199]
	v_cndmask_b32_e64 v132, v132, 0, s[46:47]
	v_pk_add_f32 v[198:199], v[118:119], v[198:199]
	v_add_f32_e32 v137, 1.0, v137
	v_rcp_f32_e32 v165, v137
	s_nop 0
	v_pk_mul_f32 v[126:127], v[126:127], v[164:165]
	v_pk_mul_f32 v[164:165], v[134:135], v[112:113]
	v_pk_mul_f32 v[126:127], v[198:199], v[126:127]
	v_pk_fma_f32 v[142:143], v[142:143], v[100:101], v[164:165]
	v_pk_mul_f32 v[198:199], v[128:129], v[96:97]
	v_pk_fma_f32 v[142:143], v[88:89], v[104:105], v[142:143]
	v_pk_fma_f32 v[132:133], v[132:133], v[92:93], v[198:199]
	v_pk_add_f32 v[142:143], v[108:109], v[142:143]
	v_pk_fma_f32 v[132:133], v[84:85], v[116:117], v[132:133]
	v_mul_f32_e32 v137, 0xbdd2d3e7, v142
	v_fmaak_f32 v137, v142, v137, 0xc0135761
	v_mul_f32_e32 v137, v142, v137
	v_exp_f32_e32 v137, v137
	v_pk_add_f32 v[132:133], v[120:121], v[132:133]
	v_cvt_pk_bf16_f32 v126, v126, v127
	v_add_f32_e32 v137, 1.0, v137
	v_rcp_f32_e32 v164, v137
	v_mul_f32_e32 v137, 0xbdd2d3e7, v143
	v_fmaak_f32 v137, v143, v137, 0xc0135761
	v_mul_f32_e32 v137, v143, v137
	v_exp_f32_e32 v137, v137
	s_nop 0
	v_add_f32_e32 v137, 1.0, v137
	v_rcp_f32_e32 v165, v137
	s_nop 0
	v_pk_mul_f32 v[142:143], v[142:143], v[164:165]
	s_nop 0
	v_pk_mul_f32 v[132:133], v[132:133], v[142:143]
	s_nop 0
	v_cvt_pk_bf16_f32 v127, v132, v133
	v_lshlrev_b64 v[132:133], 12, v[124:125]
	v_lshl_add_u64 v[132:133], s[70:71], 0, v[132:133]
	v_lshl_add_u64 v[132:133], v[180:181], 1, v[132:133]
	global_store_dwordx2 v[132:133], v[126:127], off
.LBB0_128:
	s_or_b64 exec, exec, s[0:1]
	v_add_f32_e32 v126, v189, v197
	v_fmamk_f32 v126, v126, 0x3a800000, v218
	s_mov_b32 s0, 0x17ffc
	v_rsq_f32_e32 v142, v126
	v_cmp_gt_i32_e64 s[62:63], s0, v182
	s_movk_i32 s0, 0x7ffc
	v_cmp_gt_i32_e64 s[0:1], s0, v182
	v_add_u32_e32 v126, 4, v182
	v_pk_mul_f32 v[80:81], v[80:81], v[142:143] op_sel_hi:[1,0]
	v_cndmask_b32_e64 v127, v223, v227, s[0:1]
	v_or_b32_e32 v127, v127, v126
	v_pk_mul_f32 v[78:79], v[78:79], v[142:143] op_sel_hi:[1,0]
	v_pk_mul_f32 v[76:77], v[76:77], v[142:143] op_sel_hi:[1,0]
	v_pk_mul_f32 v[74:75], v[74:75], v[142:143] op_sel_hi:[1,0]
	v_cmp_eq_u32_e64 s[48:49], -1, v127
	v_ashrrev_i32_e32 v127, 31, v126
	s_and_saveexec_b64 s[0:1], s[62:63]
	s_cbranch_execz .LBB0_130
	v_pk_mul_f32 v[164:165], v[86:87], v[110:111]
	v_cndmask_b32_e64 v133, v79, 0, s[48:49]
	v_cndmask_b32_e64 v132, v78, 0, s[48:49]
	v_pk_fma_f32 v[164:165], v[202:203], v[98:99], v[164:165]
	v_pk_mul_f32 v[200:201], v[82:83], v[94:95]
	v_pk_fma_f32 v[132:133], v[102:103], v[132:133], v[164:165]
	v_cndmask_b32_e64 v199, v75, 0, s[48:49]
	v_pk_add_f32 v[132:133], v[106:107], v[132:133]
	v_cndmask_b32_e64 v198, v74, 0, s[48:49]
	v_mul_f32_e32 v137, 0xbdd2d3e7, v132
	v_fmaak_f32 v137, v132, v137, 0xc0135761
	v_mul_f32_e32 v137, v132, v137
	v_exp_f32_e32 v137, v137
	v_pk_fma_f32 v[144:145], v[144:145], v[90:91], v[200:201]
	v_add_f32_e32 v137, 1.0, v137
	v_rcp_f32_e32 v164, v137
	v_mul_f32_e32 v137, 0xbdd2d3e7, v133
	v_fmaak_f32 v137, v133, v137, 0xc0135761
	v_mul_f32_e32 v137, v133, v137
	v_exp_f32_e32 v137, v137
	v_pk_fma_f32 v[144:145], v[198:199], v[114:115], v[144:145]
	v_pk_mul_f32 v[198:199], v[84:85], v[96:97]
	v_pk_add_f32 v[144:145], v[118:119], v[144:145]
	v_add_f32_e32 v137, 1.0, v137
	v_rcp_f32_e32 v165, v137
	v_pk_fma_f32 v[128:129], v[128:129], v[92:93], v[198:199]
	v_pk_mul_f32 v[132:133], v[132:133], v[164:165]
	v_pk_mul_f32 v[164:165], v[88:89], v[112:113]
	v_pk_mul_f32 v[132:133], v[144:145], v[132:133]
	v_cndmask_b32_e64 v145, v81, 0, s[48:49]
	v_cndmask_b32_e64 v144, v80, 0, s[48:49]
	v_pk_fma_f32 v[134:135], v[134:135], v[100:101], v[164:165]
	v_cndmask_b32_e64 v165, v77, 0, s[48:49]
	v_pk_fma_f32 v[134:135], v[104:105], v[144:145], v[134:135]
	v_cndmask_b32_e64 v164, v76, 0, s[48:49]
	v_pk_add_f32 v[134:135], v[108:109], v[134:135]
	v_pk_fma_f32 v[128:129], v[164:165], v[116:117], v[128:129]
	v_mul_f32_e32 v137, 0xbdd2d3e7, v134
	v_fmaak_f32 v137, v134, v137, 0xc0135761
	v_mul_f32_e32 v137, v134, v137
	v_exp_f32_e32 v137, v137
	v_pk_add_f32 v[128:129], v[120:121], v[128:129]
	v_cvt_pk_bf16_f32 v132, v132, v133
	v_add_f32_e32 v137, 1.0, v137
	v_rcp_f32_e32 v144, v137
	v_mul_f32_e32 v137, 0xbdd2d3e7, v135
	v_fmaak_f32 v137, v135, v137, 0xc0135761
	v_mul_f32_e32 v137, v135, v137
	v_exp_f32_e32 v137, v137
	s_nop 0
	v_add_f32_e32 v137, 1.0, v137
	v_rcp_f32_e32 v145, v137
	s_nop 0
	v_pk_mul_f32 v[134:135], v[134:135], v[144:145]
	s_nop 0
	v_pk_mul_f32 v[128:129], v[128:129], v[134:135]
	s_nop 0
	v_cvt_pk_bf16_f32 v133, v128, v129
	v_lshlrev_b64 v[128:129], 12, v[126:127]
	v_lshl_add_u64 v[128:129], s[70:71], 0, v[128:129]
	v_lshl_add_u64 v[128:129], v[180:181], 1, v[128:129]
	global_store_dwordx2 v[128:129], v[132:133], off
; __device__ __forceinline__ unsigned cvt_pk_bf16(float lo, float hi) { f32x2 v = {lo, hi}; bf16x2_t_ b = __builtin_convertvector(v, bf16x2_t_); return __builtin_bit_cast(unsigned, b); }
; __device__ __forceinline__ float dpp_shr1(float v) { return __int_as_float(__builtin_amdgcn_update_dpp(0, __float_as_int(v), 0x111, 0xF, 0xF, true)); }
; __device__ __forceinline__ float dpp_shl1(float v) { return __int_as_float(__builtin_amdgcn_update_dpp(0, __float_as_int(v), 0x101, 0xF, 0xF, true)); }
;     __device__ __forceinline__ void operator()(f32x4 (&acc)[2][2][4][2], const Unit& u, int wr, int wc, int fr, int fq) const {
;     ...
;             for (int i = 0; i < 4; ++i) {
;                 float ag[8], av[8];
; #pragma unroll
;                 for (int j = 0; j < 8; ++j) { ag[j] = acc[j >> 2][0][j & 3][n][i]; av[j] = acc[j >> 2][1][j & 3][n][i]; }
;                 const float lg = dpp_shr1(ag[7]), rg = dpp_shl1(ag[0]), lv = dpp_shr1(av[7]), rv = dpp_shl1(av[0]);
; #pragma unroll
;                 for (int j = 0; j < 8; ++j) {
;                     float Lg = j == 0 ? lg : ag[j == 0 ? 0 : j - 1], Rg = j == 7 ? rg : ag[j == 7 ? 7 : j + 1];
;                     float Lv = j == 0 ? lv : av[j == 0 ? 0 : j - 1], Rv = j == 7 ? rv : av[j == 7 ? 7 : j + 1];
;                     if ((smask >> j) & 1u) { Lg = 0.f; Lv = 0.f; }
;                     if ((emask >> j) & 1u) { Rg = 0.f; Rv = 0.f; }
;                     const float cgv = w0g[i] * Lg + w1g[i] * ag[j] + w2g[i] * Rg + bg[i];
;                     const float cvv = w0v[i] * Lv + w1v[i] * av[j] + w2v[i] * Rv + bv[i];
;                     h[j][i] = gelu_t(cgv) * cvv;
;                 }
;             }
; #pragma unroll
;             for (int j = 0; j < 8; ++j) if ((vmask >> j) & 1u) { u32x2 w; w.x = cvt_pk_bf16(h[j][0], h[j][1]); w.y = cvt_pk_bf16(h[j][2], h[j][3]);
;                 *(u32x2*)(H2 + (size_t)(t0 + j) * 2048 + cg_) = w; }
.LBB0_130:
	s_or_b64 exec, exec, s[0:1]
	v_add_f32_e32 v0, v0, v163
	v_fmamk_f32 v0, v0, 0x3a800000, v218
	s_mov_b32 s0, 0x17ffb
	v_rsq_f32_e32 v144, v0
	v_cmp_gt_i32_e64 s[64:65], s0, v182
	s_movk_i32 s0, 0x7ffb
	v_cmp_gt_i32_e64 s[0:1], s0, v182
	v_add_u32_e32 v128, 5, v182
	v_pk_mul_f32 v[72:73], v[72:73], v[144:145] op_sel_hi:[1,0]
	v_cndmask_b32_e64 v0, v217, v226, s[0:1]
	v_and_b32_e32 v0, v0, v128
	v_pk_mul_f32 v[70:71], v[70:71], v[144:145] op_sel_hi:[1,0]
	v_pk_mul_f32 v[68:69], v[68:69], v[144:145] op_sel_hi:[1,0]
	v_pk_mul_f32 v[66:67], v[66:67], v[144:145] op_sel_hi:[1,0]
	v_cmp_eq_u32_e64 s[50:51], 0, v0
	v_ashrrev_i32_e32 v129, 31, v128
	s_and_saveexec_b64 s[0:1], s[64:65]
	s_cbranch_execz .LBB0_132
	v_cndmask_b32_e64 v87, v87, 0, s[50:51]
	v_cndmask_b32_e64 v86, v86, 0, s[50:51]
	v_pk_mul_f32 v[132:133], v[110:111], v[78:79]
	v_cndmask_b32_e64 v83, v83, 0, s[50:51]
	v_pk_fma_f32 v[86:87], v[98:99], v[86:87], v[132:133]
	v_cndmask_b32_e64 v82, v82, 0, s[50:51]
	v_pk_fma_f32 v[86:87], v[102:103], v[70:71], v[86:87]
	v_pk_mul_f32 v[134:135], v[74:75], v[94:95]
	v_pk_add_f32 v[86:87], v[106:107], v[86:87]
	v_pk_fma_f32 v[82:83], v[82:83], v[90:91], v[134:135]
	v_mul_f32_e32 v0, 0xbdd2d3e7, v86
	v_fmaak_f32 v0, v86, v0, 0xc0135761
	v_mul_f32_e32 v0, v86, v0
	v_exp_f32_e32 v0, v0
	v_pk_fma_f32 v[82:83], v[66:67], v[114:115], v[82:83]
	v_cndmask_b32_e64 v85, v85, 0, s[50:51]
	v_pk_add_f32 v[82:83], v[118:119], v[82:83]
	v_add_f32_e32 v0, 1.0, v0
	v_rcp_f32_e32 v132, v0
	v_mul_f32_e32 v0, 0xbdd2d3e7, v87
	v_fmaak_f32 v0, v87, v0, 0xc0135761
	v_mul_f32_e32 v0, v87, v0
	v_exp_f32_e32 v0, v0
	v_cndmask_b32_e64 v84, v84, 0, s[50:51]
	v_add_f32_e32 v0, 1.0, v0
	v_rcp_f32_e32 v133, v0
	s_nop 0
	v_pk_mul_f32 v[86:87], v[86:87], v[132:133]
	s_nop 0
	v_pk_mul_f32 v[82:83], v[82:83], v[86:87]
	v_cndmask_b32_e64 v87, v89, 0, s[50:51]
	v_cndmask_b32_e64 v86, v88, 0, s[50:51]
	v_pk_mul_f32 v[88:89], v[112:113], v[80:81]
	v_pk_mul_f32 v[132:133], v[76:77], v[96:97]
	v_pk_fma_f32 v[86:87], v[100:101], v[86:87], v[88:89]
	v_pk_fma_f32 v[84:85], v[84:85], v[92:93], v[132:133]
	v_pk_fma_f32 v[86:87], v[104:105], v[72:73], v[86:87]
	v_pk_fma_f32 v[84:85], v[68:69], v[116:117], v[84:85]
	v_pk_add_f32 v[86:87], v[108:109], v[86:87]
	v_pk_add_f32 v[84:85], v[120:121], v[84:85]
	v_mul_f32_e32 v0, 0xbdd2d3e7, v86
	v_fmaak_f32 v0, v86, v0, 0xc0135761
	v_mul_f32_e32 v0, v86, v0
	v_exp_f32_e32 v0, v0
	v_cvt_pk_bf16_f32 v82, v82, v83
	v_add_f32_e32 v0, 1.0, v0
	v_rcp_f32_e32 v88, v0
	v_mul_f32_e32 v0, 0xbdd2d3e7, v87
	v_fmaak_f32 v0, v87, v0, 0xc0135761
	v_mul_f32_e32 v0, v87, v0
	v_exp_f32_e32 v0, v0
	s_nop 0
	v_add_f32_e32 v0, 1.0, v0
	v_rcp_f32_e32 v89, v0
	s_nop 0
	v_pk_mul_f32 v[86:87], v[86:87], v[88:89]
	s_nop 0
	v_pk_mul_f32 v[84:85], v[84:85], v[86:87]
	s_nop 0
	v_cvt_pk_bf16_f32 v83, v84, v85
	v_lshlrev_b64 v[84:85], 12, v[128:129]
	v_lshl_add_u64 v[84:85], s[70:71], 0, v[84:85]
	v_lshl_add_u64 v[84:85], v[180:181], 1, v[84:85]
	global_store_dwordx2 v[84:85], v[82:83], off
.LBB0_132:
	s_or_b64 exec, exec, s[0:1]
	s_mov_b32 s0, 0x17ffa
	v_cmp_gt_i32_e64 s[66:67], s0, v182
	s_movk_i32 s0, 0x7ffa
	v_cmp_gt_i32_e64 s[0:1], s0, v182
	v_add_u32_e32 v132, 6, v182
	v_ashrrev_i32_e32 v133, 31, v132
	v_cndmask_b32_e64 v0, v223, v227, s[0:1]
	v_or_b32_e32 v0, v0, v132
	v_cmp_eq_u32_e64 s[52:53], -1, v0
	s_and_saveexec_b64 s[0:1], s[66:67]
	s_cbranch_execz .LBB0_134
	v_pk_mul_f32 v[84:85], v[110:111], v[70:71]
	v_cndmask_b32_e64 v83, v159, 0, s[52:53]
	v_cndmask_b32_e64 v82, v158, 0, s[52:53]
	v_pk_fma_f32 v[78:79], v[98:99], v[78:79], v[84:85]
	v_pk_mul_f32 v[86:87], v[94:95], v[66:67]
	v_pk_fma_f32 v[78:79], v[102:103], v[82:83], v[78:79]
	v_cndmask_b32_e64 v85, v153, 0, s[52:53]
	v_pk_add_f32 v[78:79], v[106:107], v[78:79]
	v_cndmask_b32_e64 v84, v152, 0, s[52:53]
	v_mul_f32_e32 v0, 0xbdd2d3e7, v78
	v_fmaak_f32 v0, v78, v0, 0xc0135761
	v_mul_f32_e32 v0, v78, v0
	v_exp_f32_e32 v0, v0
	v_pk_fma_f32 v[74:75], v[74:75], v[90:91], v[86:87]
	v_add_f32_e32 v0, 1.0, v0
	v_rcp_f32_e32 v82, v0
	v_mul_f32_e32 v0, 0xbdd2d3e7, v79
	v_fmaak_f32 v0, v79, v0, 0xc0135761
	v_mul_f32_e32 v0, v79, v0
	v_exp_f32_e32 v0, v0
	v_pk_fma_f32 v[74:75], v[114:115], v[84:85], v[74:75]
	v_pk_mul_f32 v[84:85], v[96:97], v[68:69]
	v_pk_add_f32 v[74:75], v[118:119], v[74:75]
	v_add_f32_e32 v0, 1.0, v0
	v_rcp_f32_e32 v83, v0
	v_pk_fma_f32 v[76:77], v[76:77], v[92:93], v[84:85]
	v_pk_mul_f32 v[78:79], v[78:79], v[82:83]
	v_pk_mul_f32 v[82:83], v[112:113], v[72:73]
	v_pk_mul_f32 v[74:75], v[74:75], v[78:79]
	v_cndmask_b32_e64 v79, v149, 0, s[52:53]
	v_cndmask_b32_e64 v78, v148, 0, s[52:53]
	v_pk_fma_f32 v[80:81], v[100:101], v[80:81], v[82:83]
	v_cndmask_b32_e64 v83, v147, 0, s[52:53]
	v_pk_fma_f32 v[78:79], v[104:105], v[78:79], v[80:81]
	v_cndmask_b32_e64 v82, v146, 0, s[52:53]
	v_pk_add_f32 v[78:79], v[108:109], v[78:79]
	v_pk_fma_f32 v[76:77], v[116:117], v[82:83], v[76:77]
	v_mul_f32_e32 v0, 0xbdd2d3e7, v78
	v_fmaak_f32 v0, v78, v0, 0xc0135761
	v_mul_f32_e32 v0, v78, v0
	v_exp_f32_e32 v0, v0
	v_pk_add_f32 v[76:77], v[120:121], v[76:77]
	v_cvt_pk_bf16_f32 v74, v74, v75
	v_add_f32_e32 v0, 1.0, v0
	v_rcp_f32_e32 v80, v0
	v_mul_f32_e32 v0, 0xbdd2d3e7, v79
	v_fmaak_f32 v0, v79, v0, 0xc0135761
	v_mul_f32_e32 v0, v79, v0
	v_exp_f32_e32 v0, v0
	s_nop 0
	v_add_f32_e32 v0, 1.0, v0
	v_rcp_f32_e32 v81, v0
	s_nop 0
	v_pk_mul_f32 v[78:79], v[78:79], v[80:81]
	s_nop 0
	v_pk_mul_f32 v[76:77], v[76:77], v[78:79]
	s_nop 0
	v_cvt_pk_bf16_f32 v75, v76, v77
	v_lshlrev_b64 v[76:77], 12, v[132:133]
	v_lshl_add_u64 v[76:77], s[70:71], 0, v[76:77]
	v_lshl_add_u64 v[76:77], v[180:181], 1, v[76:77]
	global_store_dwordx2 v[76:77], v[74:75], off
; __device__ __forceinline__ unsigned cvt_pk_bf16(float lo, float hi) { f32x2 v = {lo, hi}; bf16x2_t_ b = __builtin_convertvector(v, bf16x2_t_); return __builtin_bit_cast(unsigned, b); }
; __device__ __forceinline__ float dpp_shr1(float v) { return __int_as_float(__builtin_amdgcn_update_dpp(0, __float_as_int(v), 0x111, 0xF, 0xF, true)); }
;     __device__ __forceinline__ void operator()(f32x4 (&acc)[2][2][4][2], const Unit& u, int wr, int wc, int fr, int fq) const {
;     ...
;         for (int n = 0; n < 2; ++n) {
;             const int cg_ = 128 * u.pn + 32 * wc + 8 * fq + 4 * n;
;             const f32x4 w0g = *(const f32x4*)(cw + cg_), w1g = *(const f32x4*)(cw + 4096 + cg_), w2g = *(const f32x4*)(cw + 8192 + cg_), bg = *(const f32x4*)(cb + cg_);
;             const f32x4 w0v = *(const f32x4*)(cw + 2048 + cg_), w1v = *(const f32x4*)(cw + 4096 + 2048 + cg_), w2v = *(const f32x4*)(cw + 8192 + 2048 + cg_), bv = *(const f32x4*)(cb + 2048 + cg_);
;             float h[8][4];
; #pragma unroll
;             for (int i = 0; i < 4; ++i) {
;                 float ag[8], av[8];
; #pragma unroll
;                 for (int j = 0; j < 8; ++j) { ag[j] = acc[j >> 2][0][j & 3][n][i]; av[j] = acc[j >> 2][1][j & 3][n][i]; }
;                 const float lg = dpp_shr1(ag[7]), rg = dpp_shl1(ag[0]), lv = dpp_shr1(av[7]), rv = dpp_shl1(av[0]);
; #pragma unroll
;                 for (int j = 0; j < 8; ++j) {
;                     float Lg = j == 0 ? lg : ag[j == 0 ? 0 : j - 1], Rg = j == 7 ? rg : ag[j == 7 ? 7 : j + 1];
;                     float Lv = j == 0 ? lv : av[j == 0 ? 0 : j - 1], Rv = j == 7 ? rv : av[j == 7 ? 7 : j + 1];
;                     if ((smask >> j) & 1u) { Lg = 0.f; Lv = 0.f; }
;                     if ((emask >> j) & 1u) { Rg = 0.f; Rv = 0.f; }
;                     const float cgv = w0g[i] * Lg + w1g[i] * ag[j] + w2g[i] * Rg + bg[i];
;                     const float cvv = w0v[i] * Lv + w1v[i] * av[j] + w2v[i] * Rv + bv[i];
;                     h[j][i] = gelu_t(cgv) * cvv;
;                 }
;             }
; #pragma unroll
;             for (int j = 0; j < 8; ++j) if ((vmask >> j) & 1u) { u32x2 w; w.x = cvt_pk_bf16(h[j][0], h[j][1]); w.y = cvt_pk_bf16(h[j][2], h[j][3]);
;                 *(u32x2*)(H2 + (size_t)(t0 + j) * 2048 + cg_) = w; }
.LBB0_134:
	s_or_b64 exec, exec, s[0:1]
	s_mov_b32 s0, 0x17ff9
	v_readlane_b32 s34, v255, 20
	v_cmp_gt_i32_e64 s[0:1], s0, v182
	v_readlane_b32 s35, v255, 21
	s_and_b64 s[76:77], s[34:35], s[0:1]
	s_movk_i32 s0, 0x7ff9
	v_cmp_gt_i32_e64 s[0:1], s0, v182
	v_add_u32_e32 v134, 7, v182
	v_ashrrev_i32_e32 v135, 31, v134
	v_cndmask_b32_e64 v0, v217, v226, s[0:1]
	v_and_b32_e32 v0, v0, v134
	v_cmp_eq_u32_e64 s[54:55], 0, v0
	s_and_saveexec_b64 s[0:1], s[76:77]
	s_cbranch_execz .LBB0_136
	v_cndmask_b32_e64 v71, v71, 0, s[54:55]
	v_cndmask_b32_e64 v70, v70, 0, s[54:55]
	v_pk_mul_f32 v[74:75], v[110:111], v[158:159]
	v_cndmask_b32_e64 v67, v67, 0, s[54:55]
	v_pk_fma_f32 v[70:71], v[98:99], v[70:71], v[74:75]
	v_cndmask_b32_e64 v66, v66, 0, s[54:55]
	v_pk_fma_f32 v[70:71], v[102:103], v[160:161], v[70:71]
	v_pk_mul_f32 v[76:77], v[94:95], v[152:153]
	v_pk_add_f32 v[70:71], v[106:107], v[70:71]
	v_pk_fma_f32 v[66:67], v[90:91], v[66:67], v[76:77]
	v_mul_f32_e32 v0, 0xbdd2d3e7, v70
	v_fmaak_f32 v0, v70, v0, 0xc0135761
	v_mul_f32_e32 v0, v70, v0
	v_exp_f32_e32 v0, v0
	v_cndmask_b32_e64 v73, v73, 0, s[54:55]
	v_cndmask_b32_e64 v72, v72, 0, s[54:55]
	v_pk_mul_f32 v[76:77], v[112:113], v[148:149]
	v_add_f32_e32 v0, 1.0, v0
	v_rcp_f32_e32 v74, v0
	v_mul_f32_e32 v0, 0xbdd2d3e7, v71
	v_fmaak_f32 v0, v71, v0, 0xc0135761
	v_mul_f32_e32 v0, v71, v0
	v_exp_f32_e32 v0, v0
	v_pk_fma_f32 v[72:73], v[100:101], v[72:73], v[76:77]
	v_pk_fma_f32 v[66:67], v[114:115], v[154:155], v[66:67]
	v_pk_fma_f32 v[72:73], v[104:105], v[156:157], v[72:73]
	v_add_f32_e32 v0, 1.0, v0
	v_pk_add_f32 v[72:73], v[108:109], v[72:73]
	v_rcp_f32_e32 v75, v0
	v_mul_f32_e32 v0, 0xbdd2d3e7, v72
	v_fmaak_f32 v0, v72, v0, 0xc0135761
	v_mul_f32_e32 v0, v72, v0
	v_exp_f32_e32 v0, v0
	v_pk_add_f32 v[66:67], v[118:119], v[66:67]
	v_pk_mul_f32 v[70:71], v[70:71], v[74:75]
	v_cndmask_b32_e64 v69, v69, 0, s[54:55]
	v_add_f32_e32 v0, 1.0, v0
	v_pk_mul_f32 v[66:67], v[66:67], v[70:71]
	v_rcp_f32_e32 v70, v0
	v_mul_f32_e32 v0, 0xbdd2d3e7, v73
	v_fmaak_f32 v0, v73, v0, 0xc0135761
	v_mul_f32_e32 v0, v73, v0
	v_exp_f32_e32 v0, v0
	v_cndmask_b32_e64 v68, v68, 0, s[54:55]
	v_pk_mul_f32 v[74:75], v[96:97], v[146:147]
	v_cvt_pk_bf16_f32 v66, v66, v67
	v_add_f32_e32 v0, 1.0, v0
	v_rcp_f32_e32 v71, v0
	v_pk_fma_f32 v[68:69], v[92:93], v[68:69], v[74:75]
	v_pk_mul_f32 v[70:71], v[72:73], v[70:71]
	v_pk_fma_f32 v[68:69], v[116:117], v[150:151], v[68:69]
	s_nop 0
	v_pk_add_f32 v[68:69], v[120:121], v[68:69]
	s_nop 0
	v_pk_mul_f32 v[68:69], v[68:69], v[70:71]
	s_nop 0
	v_cvt_pk_bf16_f32 v67, v68, v69
	v_lshlrev_b64 v[68:69], 12, v[134:135]
	v_lshl_add_u64 v[68:69], s[70:71], 0, v[68:69]
	v_lshl_add_u64 v[68:69], v[180:181], 1, v[68:69]
	global_store_dwordx2 v[68:69], v[66:67], off
.LBB0_136:
	s_or_b64 exec, exec, s[0:1]
	v_or_b32_e32 v66, 4, v180
	v_ashrrev_i32_e32 v67, 31, v66
	v_readlane_b32 s0, v255, 4
	v_lshlrev_b64 v[78:79], 2, v[66:67]
	v_readlane_b32 s1, v255, 5
	global_load_dwordx4 v[82:85], v[184:185], off offset:16
	v_mov_b32_e32 v197, v196
	v_lshl_add_u64 v[66:67], s[0:1], 0, v[78:79]
	v_readlane_b32 s0, v255, 6
	v_readlane_b32 s1, v255, 7
	v_mov_b32_e32 v189, v188
	v_mov_b32_e32 v163, v162
	v_lshl_add_u64 v[68:69], s[0:1], 0, v[78:79]
	v_readlane_b32 s0, v255, 8
	v_readlane_b32 s1, v255, 9
	global_load_dwordx4 v[94:97], v[66:67], off
	global_load_dwordx4 v[86:89], v[68:69], off
	global_load_dwordx4 v[90:93], v[186:187], off offset:16
	v_lshl_add_u64 v[66:67], s[0:1], 0, v[78:79]
	v_readlane_b32 s0, v255, 10
	v_readlane_b32 s1, v255, 11
	s_waitcnt vmcnt(11)
	v_mov_b32_e32 v98, v196
	v_mov_b32_e32 v99, v196
	v_lshl_add_u64 v[70:71], s[0:1], 0, v[78:79]
	v_readlane_b32 s0, v255, 14
	v_readlane_b32 s1, v255, 15
	global_load_dwordx4 v[66:69], v[66:67], off
	s_nop 0
	global_load_dwordx4 v[70:73], v[70:71], off
	v_lshl_add_u64 v[74:75], s[0:1], 0, v[78:79]
	v_readlane_b32 s0, v255, 18
	v_readlane_b32 s1, v255, 19
	global_load_dwordx4 v[74:77], v[74:75], off
	s_waitcnt vmcnt(12)
	v_pk_mul_f32 v[104:105], v[62:63], v[196:197]
	v_lshl_add_u64 v[78:79], s[0:1], 0, v[78:79]
	global_load_dwordx4 v[78:81], v[78:79], off
	v_pk_mul_f32 v[102:103], v[54:55], v[196:197]
	v_mov_b32_e32 v54, v188
	v_mov_b32_e32 v55, v188
	v_pk_mul_f32 v[62:63], v[50:51], v[188:189]
	v_mov_b32_e32 v50, v162
	v_mov_b32_e32 v51, v162
	v_pk_mul_f32 v[100:101], v[64:65], v[98:99]
	v_pk_mul_f32 v[98:99], v[56:57], v[98:99]
	v_pk_mul_f32 v[60:61], v[60:61], v[54:55]
	v_pk_mul_f32 v[64:65], v[58:59], v[188:189]
	v_pk_mul_f32 v[58:59], v[52:53], v[54:55]
	v_pk_mul_f32 v[48:49], v[48:49], v[50:51]
	v_pk_mul_f32 v[54:55], v[46:47], v[162:163]
	v_pk_mul_f32 v[44:45], v[44:45], v[50:51]
	v_pk_mul_f32 v[46:47], v[42:43], v[162:163]
	s_waitcnt vmcnt(12)
	v_mov_b32_dpp v108, v54 row_shr:1 row_mask:0xf bank_mask:0xf bound_ctrl:1
	v_mov_b32_dpp v56, v104 row_shl:1 row_mask:0xf bank_mask:0xf bound_ctrl:1
	v_mov_b32_dpp v106, v46 row_shr:1 row_mask:0xf bank_mask:0xf bound_ctrl:1
	v_mov_b32_dpp v50, v102 row_shl:1 row_mask:0xf bank_mask:0xf bound_ctrl:1
	v_mov_b32_dpp v109, v55 row_shr:1 row_mask:0xf bank_mask:0xf bound_ctrl:1
	v_mov_b32_dpp v57, v105 row_shl:1 row_mask:0xf bank_mask:0xf bound_ctrl:1
	v_mov_b32_dpp v107, v47 row_shr:1 row_mask:0xf bank_mask:0xf bound_ctrl:1
	v_mov_b32_dpp v51, v103 row_shl:1 row_mask:0xf bank_mask:0xf bound_ctrl:1
	v_mov_b32_dpp v112, v48 row_shr:1 row_mask:0xf bank_mask:0xf bound_ctrl:1
	v_mov_b32_dpp v52, v100 row_shl:1 row_mask:0xf bank_mask:0xf bound_ctrl:1
	v_mov_b32_dpp v110, v44 row_shr:1 row_mask:0xf bank_mask:0xf bound_ctrl:1
	v_mov_b32_dpp v42, v98 row_shl:1 row_mask:0xf bank_mask:0xf bound_ctrl:1
	v_mov_b32_dpp v113, v49 row_shr:1 row_mask:0xf bank_mask:0xf bound_ctrl:1
	v_mov_b32_dpp v53, v101 row_shl:1 row_mask:0xf bank_mask:0xf bound_ctrl:1
	v_mov_b32_dpp v111, v45 row_shr:1 row_mask:0xf bank_mask:0xf bound_ctrl:1
	v_mov_b32_dpp v43, v99 row_shl:1 row_mask:0xf bank_mask:0xf bound_ctrl:1
	s_waitcnt vmcnt(0)
	s_and_saveexec_b64 s[0:1], s[82:83]
	s_cbranch_execz .LBB0_138
; __device__ __forceinline__ unsigned cvt_pk_bf16(float lo, float hi) { f32x2 v = {lo, hi}; bf16x2_t_ b = __builtin_convertvector(v, bf16x2_t_); return __builtin_bit_cast(unsigned, b); }
; __device__ __forceinline__ float dpp_shr1(float v) { return __int_as_float(__builtin_amdgcn_update_dpp(0, __float_as_int(v), 0x111, 0xF, 0xF, true)); }
; __device__ __forceinline__ float dpp_shl1(float v) { return __int_as_float(__builtin_amdgcn_update_dpp(0, __float_as_int(v), 0x101, 0xF, 0xF, true)); }
;     __device__ __forceinline__ void operator()(f32x4 (&acc)[2][2][4][2], const Unit& u, int wr, int wc, int fr, int fq) const {
;     ...
;             for (int i = 0; i < 4; ++i) {
;                 float ag[8], av[8];
; #pragma unroll
;                 for (int j = 0; j < 8; ++j) { ag[j] = acc[j >> 2][0][j & 3][n][i]; av[j] = acc[j >> 2][1][j & 3][n][i]; }
;                 const float lg = dpp_shr1(ag[7]), rg = dpp_shl1(ag[0]), lv = dpp_shr1(av[7]), rv = dpp_shl1(av[0]);
; #pragma unroll
;                 for (int j = 0; j < 8; ++j) {
;                     float Lg = j == 0 ? lg : ag[j == 0 ? 0 : j - 1], Rg = j == 7 ? rg : ag[j == 7 ? 7 : j + 1];
;                     float Lv = j == 0 ? lv : av[j == 0 ? 0 : j - 1], Rv = j == 7 ? rv : av[j == 7 ? 7 : j + 1];
;                     if ((smask >> j) & 1u) { Lg = 0.f; Lv = 0.f; }
;                     if ((emask >> j) & 1u) { Rg = 0.f; Rv = 0.f; }
;                     const float cgv = w0g[i] * Lg + w1g[i] * ag[j] + w2g[i] * Rg + bg[i];
;                     const float cvv = w0v[i] * Lv + w1v[i] * av[j] + w2v[i] * Rv + bv[i];
;                     h[j][i] = gelu_t(cgv) * cvv;
;                 }
;             }
; #pragma unroll
;             for (int j = 0; j < 8; ++j) if ((vmask >> j) & 1u) { u32x2 w; w.x = cvt_pk_bf16(h[j][0], h[j][1]); w.y = cvt_pk_bf16(h[j][2], h[j][3]);
;                 *(u32x2*)(H2 + (size_t)(t0 + j) * 2048 + cg_) = w; }
	v_pk_mul_f32 v[112:113], v[84:85], v[112:113]
	v_cndmask_b32_e64 v117, v61, 0, s[42:43]
	v_cndmask_b32_e64 v116, v60, 0, s[42:43]
	v_pk_fma_f32 v[112:113], v[100:101], v[96:97], v[112:113]
	v_pk_mul_f32 v[110:111], v[68:69], v[110:111]
	v_pk_fma_f32 v[112:113], v[116:117], v[88:89], v[112:113]
	v_cndmask_b32_e64 v115, v59, 0, s[42:43]
	v_pk_add_f32 v[112:113], v[92:93], v[112:113]
	v_cndmask_b32_e64 v114, v58, 0, s[42:43]
	v_mul_f32_e32 v0, 0xbdd2d3e7, v113
	v_fmaak_f32 v0, v113, v0, 0xc0135761
	v_mul_f32_e32 v116, 0xbdd2d3e7, v112
	v_mul_f32_e32 v0, v113, v0
	v_fmaak_f32 v116, v112, v116, 0xc0135761
	v_mul_f32_e32 v116, v112, v116
	v_exp_f32_e32 v0, v0
	s_nop 0
	v_exp_f32_e32 v116, v116
	v_pk_fma_f32 v[110:111], v[98:99], v[72:73], v[110:111]
	v_pk_mul_f32 v[108:109], v[82:83], v[108:109]
	v_pk_fma_f32 v[110:111], v[114:115], v[76:77], v[110:111]
	v_cndmask_b32_e64 v115, v65, 0, s[42:43]
	v_cndmask_b32_e64 v114, v64, 0, s[42:43]
	v_pk_fma_f32 v[108:109], v[104:105], v[94:95], v[108:109]
	v_add_f32_e32 v0, 1.0, v0
	v_pk_fma_f32 v[108:109], v[114:115], v[86:87], v[108:109]
	v_rcp_f32_e32 v117, v0
	v_add_f32_e32 v0, 1.0, v116
	v_pk_add_f32 v[108:109], v[90:91], v[108:109]
	v_rcp_f32_e32 v116, v0
	v_mul_f32_e32 v0, 0xbdd2d3e7, v109
	v_fmaak_f32 v0, v109, v0, 0xc0135761
	v_mul_f32_e32 v114, 0xbdd2d3e7, v108
	v_mul_f32_e32 v0, v109, v0
	v_fmaak_f32 v114, v108, v114, 0xc0135761
	v_mul_f32_e32 v114, v108, v114
	v_exp_f32_e32 v0, v0
	s_nop 0
	v_exp_f32_e32 v114, v114
	v_pk_add_f32 v[110:111], v[80:81], v[110:111]
	v_add_f32_e32 v0, 1.0, v0
	v_rcp_f32_e32 v115, v0
	v_add_f32_e32 v0, 1.0, v114
	v_rcp_f32_e32 v114, v0
	v_pk_mul_f32 v[112:113], v[112:113], v[116:117]
	v_pk_mul_f32 v[106:107], v[66:67], v[106:107]
	v_pk_mul_f32 v[110:111], v[110:111], v[112:113]
	v_cndmask_b32_e64 v113, v63, 0, s[42:43]
	v_cndmask_b32_e64 v112, v62, 0, s[42:43]
	v_pk_fma_f32 v[106:107], v[102:103], v[70:71], v[106:107]
	v_pk_mul_f32 v[108:109], v[108:109], v[114:115]
	v_pk_fma_f32 v[106:107], v[112:113], v[74:75], v[106:107]
	s_nop 0
	v_pk_add_f32 v[106:107], v[78:79], v[106:107]
	s_nop 0
	v_pk_mul_f32 v[106:107], v[106:107], v[108:109]
	v_lshlrev_b64 v[108:109], 12, v[182:183]
	v_lshl_add_u64 v[108:109], s[70:71], 0, v[108:109]
	v_cvt_pk_bf16_f32 v106, v106, v107
	v_cvt_pk_bf16_f32 v107, v110, v111
	v_lshl_add_u64 v[108:109], v[180:181], 1, v[108:109]
	global_store_dwordx2 v[108:109], v[106:107], off offset:8
.LBB0_138:
	s_or_b64 exec, exec, s[0:1]
	v_mov_b32_e32 v139, v138
	v_mov_b32_e32 v106, v138
	v_mov_b32_e32 v107, v138
	v_pk_mul_f32 v[40:41], v[40:41], v[106:107]
	v_pk_mul_f32 v[38:39], v[38:39], v[138:139]
	v_pk_mul_f32 v[36:37], v[36:37], v[106:107]
	v_pk_mul_f32 v[34:35], v[34:35], v[138:139]
	s_and_saveexec_b64 s[0:1], s[56:57]
	s_cbranch_execz .LBB0_140
	v_cndmask_b32_e64 v105, v105, 0, vcc
	v_cndmask_b32_e64 v104, v104, 0, vcc
	v_pk_mul_f32 v[106:107], v[64:65], v[94:95]
	v_cndmask_b32_e64 v103, v103, 0, vcc
	v_pk_fma_f32 v[104:105], v[104:105], v[82:83], v[106:107]
	v_cndmask_b32_e64 v102, v102, 0, vcc
	v_pk_fma_f32 v[104:105], v[38:39], v[86:87], v[104:105]
	v_pk_mul_f32 v[108:109], v[62:63], v[70:71]
	v_pk_add_f32 v[104:105], v[90:91], v[104:105]
	v_pk_fma_f32 v[102:103], v[102:103], v[66:67], v[108:109]
	v_mul_f32_e32 v0, 0xbdd2d3e7, v104
	v_fmaak_f32 v0, v104, v0, 0xc0135761
	v_mul_f32_e32 v0, v104, v0
	v_exp_f32_e32 v0, v0
	v_pk_fma_f32 v[102:103], v[34:35], v[74:75], v[102:103]
	v_cndmask_b32_e64 v101, v101, 0, vcc
	v_pk_add_f32 v[102:103], v[78:79], v[102:103]
	v_add_f32_e32 v0, 1.0, v0
	v_rcp_f32_e32 v106, v0
	v_mul_f32_e32 v0, 0xbdd2d3e7, v105
	v_fmaak_f32 v0, v105, v0, 0xc0135761
	v_mul_f32_e32 v0, v105, v0
	v_exp_f32_e32 v0, v0
	v_cndmask_b32_e64 v100, v100, 0, vcc
	v_cndmask_b32_e64 v99, v99, 0, vcc
	v_cndmask_b32_e64 v98, v98, 0, vcc
	v_add_f32_e32 v0, 1.0, v0
	v_rcp_f32_e32 v107, v0
	s_nop 0
	v_pk_mul_f32 v[104:105], v[104:105], v[106:107]
	s_nop 0
	v_pk_mul_f32 v[102:103], v[102:103], v[104:105]
	v_pk_mul_f32 v[104:105], v[60:61], v[96:97]
	v_pk_mul_f32 v[106:107], v[58:59], v[72:73]
	v_pk_fma_f32 v[100:101], v[100:101], v[84:85], v[104:105]
	v_pk_fma_f32 v[98:99], v[98:99], v[68:69], v[106:107]
	v_pk_fma_f32 v[100:101], v[40:41], v[88:89], v[100:101]
	v_pk_fma_f32 v[98:99], v[36:37], v[76:77], v[98:99]
	v_pk_add_f32 v[100:101], v[92:93], v[100:101]
	v_pk_add_f32 v[98:99], v[80:81], v[98:99]
	v_mul_f32_e32 v0, 0xbdd2d3e7, v100
	v_fmaak_f32 v0, v100, v0, 0xc0135761
	v_mul_f32_e32 v0, v100, v0
	v_exp_f32_e32 v0, v0
	s_nop 0
	v_add_f32_e32 v0, 1.0, v0
	v_rcp_f32_e32 v104, v0
	v_mul_f32_e32 v0, 0xbdd2d3e7, v101
	v_fmaak_f32 v0, v101, v0, 0xc0135761
	v_mul_f32_e32 v0, v101, v0
	v_exp_f32_e32 v0, v0
	s_nop 0
	v_add_f32_e32 v0, 1.0, v0
	v_rcp_f32_e32 v105, v0
	s_nop 0
	v_pk_mul_f32 v[100:101], v[100:101], v[104:105]
	s_nop 0
	v_pk_mul_f32 v[98:99], v[98:99], v[100:101]
	v_cvt_pk_bf16_f32 v100, v102, v103
	v_cvt_pk_bf16_f32 v101, v98, v99
	v_lshlrev_b64 v[98:99], 12, v[130:131]
	v_lshl_add_u64 v[98:99], s[70:71], 0, v[98:99]
	v_lshl_add_u64 v[98:99], v[180:181], 1, v[98:99]
	global_store_dwordx2 v[98:99], v[100:101], off offset:8
; __device__ __forceinline__ unsigned cvt_pk_bf16(float lo, float hi) { f32x2 v = {lo, hi}; bf16x2_t_ b = __builtin_convertvector(v, bf16x2_t_); return __builtin_bit_cast(unsigned, b); }
; __device__ __forceinline__ float dpp_shr1(float v) { return __int_as_float(__builtin_amdgcn_update_dpp(0, __float_as_int(v), 0x111, 0xF, 0xF, true)); }
; __device__ __forceinline__ float dpp_shl1(float v) { return __int_as_float(__builtin_amdgcn_update_dpp(0, __float_as_int(v), 0x101, 0xF, 0xF, true)); }
;     __device__ __forceinline__ void operator()(f32x4 (&acc)[2][2][4][2], const Unit& u, int wr, int wc, int fr, int fq) const {
;     ...
;             for (int i = 0; i < 4; ++i) {
;                 float ag[8], av[8];
; #pragma unroll
;                 for (int j = 0; j < 8; ++j) { ag[j] = acc[j >> 2][0][j & 3][n][i]; av[j] = acc[j >> 2][1][j & 3][n][i]; }
;                 const float lg = dpp_shr1(ag[7]), rg = dpp_shl1(ag[0]), lv = dpp_shr1(av[7]), rv = dpp_shl1(av[0]);
; #pragma unroll
;                 for (int j = 0; j < 8; ++j) {
;                     float Lg = j == 0 ? lg : ag[j == 0 ? 0 : j - 1], Rg = j == 7 ? rg : ag[j == 7 ? 7 : j + 1];
;                     float Lv = j == 0 ? lv : av[j == 0 ? 0 : j - 1], Rv = j == 7 ? rv : av[j == 7 ? 7 : j + 1];
;                     if ((smask >> j) & 1u) { Lg = 0.f; Lv = 0.f; }
;                     if ((emask >> j) & 1u) { Rg = 0.f; Rv = 0.f; }
;                     const float cgv = w0g[i] * Lg + w1g[i] * ag[j] + w2g[i] * Rg + bg[i];
;                     const float cvv = w0v[i] * Lv + w1v[i] * av[j] + w2v[i] * Rv + bv[i];
;                     h[j][i] = gelu_t(cgv) * cvv;
;                 }
;             }
; #pragma unroll
;             for (int j = 0; j < 8; ++j) if ((vmask >> j) & 1u) { u32x2 w; w.x = cvt_pk_bf16(h[j][0], h[j][1]); w.y = cvt_pk_bf16(h[j][2], h[j][3]);
;                 *(u32x2*)(H2 + (size_t)(t0 + j) * 2048 + cg_) = w; }
.LBB0_140:
	s_or_b64 exec, exec, s[0:1]
	v_mov_b32_e32 v137, v136
	v_mov_b32_e32 v98, v136
	v_mov_b32_e32 v99, v136
	v_pk_mul_f32 v[32:33], v[32:33], v[98:99]
	v_pk_mul_f32 v[30:31], v[30:31], v[136:137]
	v_pk_mul_f32 v[28:29], v[28:29], v[98:99]
	v_pk_mul_f32 v[26:27], v[26:27], v[136:137]
	s_and_saveexec_b64 s[0:1], s[58:59]
	s_cbranch_execz .LBB0_142
	v_pk_mul_f32 v[100:101], v[38:39], v[94:95]
	v_cndmask_b32_e64 v99, v31, 0, s[44:45]
	v_cndmask_b32_e64 v98, v30, 0, s[44:45]
	v_pk_fma_f32 v[64:65], v[64:65], v[82:83], v[100:101]
	v_pk_mul_f32 v[102:103], v[34:35], v[70:71]
	v_pk_fma_f32 v[64:65], v[98:99], v[86:87], v[64:65]
	v_cndmask_b32_e64 v101, v27, 0, s[44:45]
	v_pk_add_f32 v[64:65], v[90:91], v[64:65]
	v_cndmask_b32_e64 v100, v26, 0, s[44:45]
	v_mul_f32_e32 v0, 0xbdd2d3e7, v64
	v_fmaak_f32 v0, v64, v0, 0xc0135761
	v_mul_f32_e32 v0, v64, v0
	v_exp_f32_e32 v0, v0
	v_pk_fma_f32 v[62:63], v[62:63], v[66:67], v[102:103]
	v_add_f32_e32 v0, 1.0, v0
	v_rcp_f32_e32 v98, v0
	v_mul_f32_e32 v0, 0xbdd2d3e7, v65
	v_fmaak_f32 v0, v65, v0, 0xc0135761
	v_mul_f32_e32 v0, v65, v0
	v_exp_f32_e32 v0, v0
	v_pk_fma_f32 v[62:63], v[100:101], v[74:75], v[62:63]
	v_pk_mul_f32 v[100:101], v[36:37], v[72:73]
	v_pk_add_f32 v[62:63], v[78:79], v[62:63]
	v_add_f32_e32 v0, 1.0, v0
	v_rcp_f32_e32 v99, v0
	v_pk_fma_f32 v[58:59], v[58:59], v[68:69], v[100:101]
	v_pk_mul_f32 v[64:65], v[64:65], v[98:99]
	v_pk_mul_f32 v[98:99], v[40:41], v[96:97]
	v_pk_mul_f32 v[62:63], v[62:63], v[64:65]
	v_cndmask_b32_e64 v65, v33, 0, s[44:45]
	v_cndmask_b32_e64 v64, v32, 0, s[44:45]
	v_pk_fma_f32 v[60:61], v[60:61], v[84:85], v[98:99]
	v_cndmask_b32_e64 v99, v29, 0, s[44:45]
	v_pk_fma_f32 v[60:61], v[64:65], v[88:89], v[60:61]
	v_cndmask_b32_e64 v98, v28, 0, s[44:45]
	v_pk_add_f32 v[60:61], v[92:93], v[60:61]
	v_pk_fma_f32 v[58:59], v[98:99], v[76:77], v[58:59]
	v_mul_f32_e32 v0, 0xbdd2d3e7, v60
	v_fmaak_f32 v0, v60, v0, 0xc0135761
	v_mul_f32_e32 v0, v60, v0
	v_exp_f32_e32 v0, v0
	v_pk_add_f32 v[58:59], v[80:81], v[58:59]
	v_add_f32_e32 v0, 1.0, v0
	v_rcp_f32_e32 v64, v0
	v_mul_f32_e32 v0, 0xbdd2d3e7, v61
	v_fmaak_f32 v0, v61, v0, 0xc0135761
	v_mul_f32_e32 v0, v61, v0
	v_exp_f32_e32 v0, v0
	s_nop 0
	v_add_f32_e32 v0, 1.0, v0
	v_rcp_f32_e32 v65, v0
	s_nop 0
	v_pk_mul_f32 v[60:61], v[60:61], v[64:65]
	s_nop 0
	v_pk_mul_f32 v[58:59], v[58:59], v[60:61]
	v_cvt_pk_bf16_f32 v60, v62, v63
	v_cvt_pk_bf16_f32 v61, v58, v59
	v_lshlrev_b64 v[58:59], 12, v[122:123]
	v_lshl_add_u64 v[58:59], s[70:71], 0, v[58:59]
	v_lshl_add_u64 v[58:59], v[180:181], 1, v[58:59]
	global_store_dwordx2 v[58:59], v[60:61], off offset:8
; __device__ __forceinline__ unsigned cvt_pk_bf16(float lo, float hi) { f32x2 v = {lo, hi}; bf16x2_t_ b = __builtin_convertvector(v, bf16x2_t_); return __builtin_bit_cast(unsigned, b); }
; __device__ __forceinline__ float dpp_shr1(float v) { return __int_as_float(__builtin_amdgcn_update_dpp(0, __float_as_int(v), 0x111, 0xF, 0xF, true)); }
; __device__ __forceinline__ float dpp_shl1(float v) { return __int_as_float(__builtin_amdgcn_update_dpp(0, __float_as_int(v), 0x101, 0xF, 0xF, true)); }
;     __device__ __forceinline__ void operator()(f32x4 (&acc)[2][2][4][2], const Unit& u, int wr, int wc, int fr, int fq) const {
;     ...
;             for (int i = 0; i < 4; ++i) {
;                 float ag[8], av[8];
; #pragma unroll
;                 for (int j = 0; j < 8; ++j) { ag[j] = acc[j >> 2][0][j & 3][n][i]; av[j] = acc[j >> 2][1][j & 3][n][i]; }
;                 const float lg = dpp_shr1(ag[7]), rg = dpp_shl1(ag[0]), lv = dpp_shr1(av[7]), rv = dpp_shl1(av[0]);
; #pragma unroll
;                 for (int j = 0; j < 8; ++j) {
;                     float Lg = j == 0 ? lg : ag[j == 0 ? 0 : j - 1], Rg = j == 7 ? rg : ag[j == 7 ? 7 : j + 1];
;                     float Lv = j == 0 ? lv : av[j == 0 ? 0 : j - 1], Rv = j == 7 ? rv : av[j == 7 ? 7 : j + 1];
;                     if ((smask >> j) & 1u) { Lg = 0.f; Lv = 0.f; }
;                     if ((emask >> j) & 1u) { Rg = 0.f; Rv = 0.f; }
;                     const float cgv = w0g[i] * Lg + w1g[i] * ag[j] + w2g[i] * Rg + bg[i];
;                     const float cvv = w0v[i] * Lv + w1v[i] * av[j] + w2v[i] * Rv + bv[i];
;                     h[j][i] = gelu_t(cgv) * cvv;
;                 }
;             }
; #pragma unroll
;             for (int j = 0; j < 8; ++j) if ((vmask >> j) & 1u) { u32x2 w; w.x = cvt_pk_bf16(h[j][0], h[j][1]); w.y = cvt_pk_bf16(h[j][2], h[j][3]);
;                 *(u32x2*)(H2 + (size_t)(t0 + j) * 2048 + cg_) = w; }
.LBB0_142:
	s_or_b64 exec, exec, s[0:1]
	v_mov_b32_e32 v141, v140
	v_mov_b32_e32 v58, v140
	v_mov_b32_e32 v59, v140
	v_pk_mul_f32 v[24:25], v[24:25], v[58:59]
	v_pk_mul_f32 v[22:23], v[22:23], v[140:141]
	v_pk_mul_f32 v[20:21], v[20:21], v[58:59]
	v_pk_mul_f32 v[18:19], v[18:19], v[140:141]
	s_and_saveexec_b64 s[0:1], s[60:61]
	s_cbranch_execz .LBB0_144
	v_cndmask_b32_e64 v39, v39, 0, s[46:47]
	v_cndmask_b32_e64 v38, v38, 0, s[46:47]
	v_pk_mul_f32 v[58:59], v[30:31], v[94:95]
	v_cndmask_b32_e64 v35, v35, 0, s[46:47]
	v_pk_fma_f32 v[38:39], v[38:39], v[82:83], v[58:59]
	v_cndmask_b32_e64 v34, v34, 0, s[46:47]
	v_pk_fma_f32 v[38:39], v[22:23], v[86:87], v[38:39]
	v_pk_mul_f32 v[60:61], v[26:27], v[70:71]
	v_pk_add_f32 v[38:39], v[90:91], v[38:39]
	v_pk_fma_f32 v[34:35], v[34:35], v[66:67], v[60:61]
	v_mul_f32_e32 v0, 0xbdd2d3e7, v38
	v_fmaak_f32 v0, v38, v0, 0xc0135761
	v_mul_f32_e32 v0, v38, v0
	v_exp_f32_e32 v0, v0
	v_pk_fma_f32 v[34:35], v[18:19], v[74:75], v[34:35]
	v_cndmask_b32_e64 v37, v37, 0, s[46:47]
	v_pk_add_f32 v[34:35], v[78:79], v[34:35]
	v_add_f32_e32 v0, 1.0, v0
	v_rcp_f32_e32 v58, v0
	v_mul_f32_e32 v0, 0xbdd2d3e7, v39
	v_fmaak_f32 v0, v39, v0, 0xc0135761
	v_mul_f32_e32 v0, v39, v0
	v_exp_f32_e32 v0, v0
	v_cndmask_b32_e64 v36, v36, 0, s[46:47]
	v_add_f32_e32 v0, 1.0, v0
	v_rcp_f32_e32 v59, v0
	s_nop 0
	v_pk_mul_f32 v[38:39], v[38:39], v[58:59]
	s_nop 0
	v_pk_mul_f32 v[34:35], v[34:35], v[38:39]
	v_cndmask_b32_e64 v39, v41, 0, s[46:47]
	v_cndmask_b32_e64 v38, v40, 0, s[46:47]
	v_pk_mul_f32 v[40:41], v[32:33], v[96:97]
	v_pk_mul_f32 v[58:59], v[28:29], v[72:73]
	v_pk_fma_f32 v[38:39], v[38:39], v[84:85], v[40:41]
	v_pk_fma_f32 v[36:37], v[36:37], v[68:69], v[58:59]
	v_pk_fma_f32 v[38:39], v[24:25], v[88:89], v[38:39]
	v_pk_fma_f32 v[36:37], v[20:21], v[76:77], v[36:37]
	v_pk_add_f32 v[38:39], v[92:93], v[38:39]
	v_pk_add_f32 v[36:37], v[80:81], v[36:37]
	v_mul_f32_e32 v0, 0xbdd2d3e7, v38
	v_fmaak_f32 v0, v38, v0, 0xc0135761
	v_mul_f32_e32 v0, v38, v0
	v_exp_f32_e32 v0, v0
	v_cvt_pk_bf16_f32 v34, v34, v35
	v_add_f32_e32 v0, 1.0, v0
	v_rcp_f32_e32 v40, v0
	v_mul_f32_e32 v0, 0xbdd2d3e7, v39
	v_fmaak_f32 v0, v39, v0, 0xc0135761
	v_mul_f32_e32 v0, v39, v0
	v_exp_f32_e32 v0, v0
	s_nop 0
	v_add_f32_e32 v0, 1.0, v0
	v_rcp_f32_e32 v41, v0
	s_nop 0
	v_pk_mul_f32 v[38:39], v[38:39], v[40:41]
	s_nop 0
	v_pk_mul_f32 v[36:37], v[36:37], v[38:39]
	s_nop 0
	v_cvt_pk_bf16_f32 v35, v36, v37
	v_lshlrev_b64 v[36:37], 12, v[124:125]
	v_lshl_add_u64 v[36:37], s[70:71], 0, v[36:37]
	v_lshl_add_u64 v[36:37], v[180:181], 1, v[36:37]
	global_store_dwordx2 v[36:37], v[34:35], off offset:8
.LBB0_144:
	s_or_b64 exec, exec, s[0:1]
	v_mov_b32_e32 v143, v142
	v_mov_b32_e32 v34, v142
	v_mov_b32_e32 v35, v142
	v_pk_mul_f32 v[16:17], v[16:17], v[34:35]
	v_pk_mul_f32 v[14:15], v[14:15], v[142:143]
	v_pk_mul_f32 v[12:13], v[12:13], v[34:35]
	v_pk_mul_f32 v[10:11], v[10:11], v[142:143]
	s_and_saveexec_b64 s[0:1], s[62:63]
	s_cbranch_execz .LBB0_146
	v_pk_mul_f32 v[36:37], v[22:23], v[94:95]
	v_cndmask_b32_e64 v35, v15, 0, s[48:49]
	v_cndmask_b32_e64 v34, v14, 0, s[48:49]
	v_pk_fma_f32 v[30:31], v[30:31], v[82:83], v[36:37]
	v_pk_mul_f32 v[38:39], v[18:19], v[70:71]
	v_pk_fma_f32 v[30:31], v[34:35], v[86:87], v[30:31]
	v_cndmask_b32_e64 v37, v11, 0, s[48:49]
	v_pk_add_f32 v[30:31], v[90:91], v[30:31]
	v_cndmask_b32_e64 v36, v10, 0, s[48:49]
	v_mul_f32_e32 v0, 0xbdd2d3e7, v30
	v_fmaak_f32 v0, v30, v0, 0xc0135761
	v_mul_f32_e32 v0, v30, v0
	v_exp_f32_e32 v0, v0
	v_pk_fma_f32 v[26:27], v[26:27], v[66:67], v[38:39]
	v_add_f32_e32 v0, 1.0, v0
	v_rcp_f32_e32 v34, v0
	v_mul_f32_e32 v0, 0xbdd2d3e7, v31
	v_fmaak_f32 v0, v31, v0, 0xc0135761
	v_mul_f32_e32 v0, v31, v0
	v_exp_f32_e32 v0, v0
	v_pk_fma_f32 v[26:27], v[36:37], v[74:75], v[26:27]
	v_pk_mul_f32 v[36:37], v[20:21], v[72:73]
	v_pk_add_f32 v[26:27], v[78:79], v[26:27]
	v_add_f32_e32 v0, 1.0, v0
	v_rcp_f32_e32 v35, v0
	v_pk_fma_f32 v[28:29], v[28:29], v[68:69], v[36:37]
	v_pk_mul_f32 v[30:31], v[30:31], v[34:35]
	v_pk_mul_f32 v[34:35], v[24:25], v[96:97]
	v_pk_mul_f32 v[26:27], v[26:27], v[30:31]
	v_cndmask_b32_e64 v31, v17, 0, s[48:49]
	v_cndmask_b32_e64 v30, v16, 0, s[48:49]
	v_pk_fma_f32 v[32:33], v[32:33], v[84:85], v[34:35]
	v_cndmask_b32_e64 v35, v13, 0, s[48:49]
	v_pk_fma_f32 v[30:31], v[30:31], v[88:89], v[32:33]
	v_cndmask_b32_e64 v34, v12, 0, s[48:49]
	v_pk_add_f32 v[30:31], v[92:93], v[30:31]
	v_pk_fma_f32 v[28:29], v[34:35], v[76:77], v[28:29]
	v_mul_f32_e32 v0, 0xbdd2d3e7, v30
	v_fmaak_f32 v0, v30, v0, 0xc0135761
	v_mul_f32_e32 v0, v30, v0
	v_exp_f32_e32 v0, v0
	v_pk_add_f32 v[28:29], v[80:81], v[28:29]
	v_cvt_pk_bf16_f32 v26, v26, v27
	v_add_f32_e32 v0, 1.0, v0
	v_rcp_f32_e32 v32, v0
	v_mul_f32_e32 v0, 0xbdd2d3e7, v31
	v_fmaak_f32 v0, v31, v0, 0xc0135761
	v_mul_f32_e32 v0, v31, v0
	v_exp_f32_e32 v0, v0
	s_nop 0
	v_add_f32_e32 v0, 1.0, v0
	v_rcp_f32_e32 v33, v0
	s_nop 0
	v_pk_mul_f32 v[30:31], v[30:31], v[32:33]
	s_nop 0
	v_pk_mul_f32 v[28:29], v[28:29], v[30:31]
	s_nop 0
	v_cvt_pk_bf16_f32 v27, v28, v29
	v_lshlrev_b64 v[28:29], 12, v[126:127]
	v_lshl_add_u64 v[28:29], s[70:71], 0, v[28:29]
	v_lshl_add_u64 v[28:29], v[180:181], 1, v[28:29]
	global_store_dwordx2 v[28:29], v[26:27], off offset:8

; __device__ __forceinline__ unsigned cvt_pk_bf16(float lo, float hi) { f32x2 v = {lo, hi}; bf16x2_t_ b = __builtin_convertvector(v, bf16x2_t_); return __builtin_bit_cast(unsigned, b); }
; __device__ __forceinline__ float dpp_shr1(float v) { return __int_as_float(__builtin_amdgcn_update_dpp(0, __float_as_int(v), 0x111, 0xF, 0xF, true)); }
; __device__ __forceinline__ float dpp_shl1(float v) { return __int_as_float(__builtin_amdgcn_update_dpp(0, __float_as_int(v), 0x101, 0xF, 0xF, true)); }
;     __device__ __forceinline__ void operator()(f32x4 (&acc)[2][2][4][2], const Unit& u, int wr, int wc, int fr, int fq) const {
;     ...
;             for (int i = 0; i < 4; ++i) {
;                 float ag[8], av[8];
; #pragma unroll
;                 for (int j = 0; j < 8; ++j) { ag[j] = acc[j >> 2][0][j & 3][n][i]; av[j] = acc[j >> 2][1][j & 3][n][i]; }
;                 const float lg = dpp_shr1(ag[7]), rg = dpp_shl1(ag[0]), lv = dpp_shr1(av[7]), rv = dpp_shl1(av[0]);
; #pragma unroll
;                 for (int j = 0; j < 8; ++j) {
;                     float Lg = j == 0 ? lg : ag[j == 0 ? 0 : j - 1], Rg = j == 7 ? rg : ag[j == 7 ? 7 : j + 1];
;                     float Lv = j == 0 ? lv : av[j == 0 ? 0 : j - 1], Rv = j == 7 ? rv : av[j == 7 ? 7 : j + 1];
;                     if ((smask >> j) & 1u) { Lg = 0.f; Lv = 0.f; }
;                     if ((emask >> j) & 1u) { Rg = 0.f; Rv = 0.f; }
;                     const float cgv = w0g[i] * Lg + w1g[i] * ag[j] + w2g[i] * Rg + bg[i];
;                     const float cvv = w0v[i] * Lv + w1v[i] * av[j] + w2v[i] * Rv + bv[i];
;                     h[j][i] = gelu_t(cgv) * cvv;
;                 }
;             }
; #pragma unroll
;             for (int j = 0; j < 8; ++j) if ((vmask >> j) & 1u) { u32x2 w; w.x = cvt_pk_bf16(h[j][0], h[j][1]); w.y = cvt_pk_bf16(h[j][2], h[j][3]);
;                 *(u32x2*)(H2 + (size_t)(t0 + j) * 2048 + cg_) = w; }
.LBB0_149:
	v_cndmask_b32_e64 v7, v7, 0, s[54:55]
	v_cndmask_b32_e64 v6, v6, 0, s[54:55]
	v_pk_mul_f32 v[10:11], v[54:55], v[94:95]
	v_cndmask_b32_e64 v3, v3, 0, s[54:55]
	v_pk_fma_f32 v[6:7], v[6:7], v[82:83], v[10:11]
	v_cndmask_b32_e64 v2, v2, 0, s[54:55]
	v_pk_fma_f32 v[6:7], v[86:87], v[56:57], v[6:7]
	v_pk_mul_f32 v[12:13], v[46:47], v[70:71]
	v_pk_add_f32 v[6:7], v[90:91], v[6:7]
	v_pk_fma_f32 v[2:3], v[2:3], v[66:67], v[12:13]
	v_mul_f32_e32 v0, 0xbdd2d3e7, v6
	v_fmaak_f32 v0, v6, v0, 0xc0135761
	v_mul_f32_e32 v0, v6, v0
	v_exp_f32_e32 v0, v0
	v_cndmask_b32_e64 v9, v9, 0, s[54:55]
	v_cndmask_b32_e64 v8, v8, 0, s[54:55]
	v_pk_mul_f32 v[12:13], v[48:49], v[96:97]
	v_add_f32_e32 v0, 1.0, v0
	v_rcp_f32_e32 v10, v0
	v_mul_f32_e32 v0, 0xbdd2d3e7, v7
	v_fmaak_f32 v0, v7, v0, 0xc0135761
	v_mul_f32_e32 v0, v7, v0
	v_exp_f32_e32 v0, v0
	v_pk_fma_f32 v[8:9], v[8:9], v[84:85], v[12:13]
	v_pk_fma_f32 v[2:3], v[74:75], v[50:51], v[2:3]
	v_pk_fma_f32 v[8:9], v[88:89], v[52:53], v[8:9]
	v_add_f32_e32 v0, 1.0, v0
	v_pk_add_f32 v[8:9], v[92:93], v[8:9]
	v_rcp_f32_e32 v11, v0
	v_mul_f32_e32 v0, 0xbdd2d3e7, v8
	v_fmaak_f32 v0, v8, v0, 0xc0135761
	v_mul_f32_e32 v0, v8, v0
	v_exp_f32_e32 v0, v0
	v_pk_add_f32 v[2:3], v[78:79], v[2:3]
	v_pk_mul_f32 v[6:7], v[6:7], v[10:11]
	v_cndmask_b32_e64 v5, v5, 0, s[54:55]
	v_add_f32_e32 v0, 1.0, v0
	v_pk_mul_f32 v[2:3], v[2:3], v[6:7]
	v_rcp_f32_e32 v6, v0
	v_mul_f32_e32 v0, 0xbdd2d3e7, v9
	v_fmaak_f32 v0, v9, v0, 0xc0135761
	v_mul_f32_e32 v0, v9, v0
	v_exp_f32_e32 v0, v0
	v_cndmask_b32_e64 v4, v4, 0, s[54:55]
	v_pk_mul_f32 v[10:11], v[44:45], v[72:73]
	v_cvt_pk_bf16_f32 v2, v2, v3
	v_add_f32_e32 v0, 1.0, v0
	v_rcp_f32_e32 v7, v0
	v_pk_fma_f32 v[4:5], v[4:5], v[68:69], v[10:11]
	v_pk_mul_f32 v[6:7], v[8:9], v[6:7]
	v_pk_fma_f32 v[4:5], v[76:77], v[42:43], v[4:5]
	s_nop 0
	v_pk_add_f32 v[4:5], v[80:81], v[4:5]
	s_nop 0
	v_pk_mul_f32 v[4:5], v[4:5], v[6:7]
	s_nop 0
	v_cvt_pk_bf16_f32 v3, v4, v5
	v_lshlrev_b64 v[4:5], 12, v[134:135]
	v_lshl_add_u64 v[4:5], s[70:71], 0, v[4:5]
	v_lshl_add_u64 v[4:5], v[180:181], 1, v[4:5]
	global_store_dwordx2 v[4:5], v[2:3], off offset:8

; __device__ __forceinline__ unsigned cvt_pk_bf16(float lo, float hi) { f32x2 v = {lo, hi}; bf16x2_t_ b = __builtin_convertvector(v, bf16x2_t_); return __builtin_bit_cast(unsigned, b); }
; __device__ __forceinline__ float dpp_shr1(float v) { return __int_as_float(__builtin_amdgcn_update_dpp(0, __float_as_int(v), 0x111, 0xF, 0xF, true)); }
; __device__ __forceinline__ float dpp_shl1(float v) { return __int_as_float(__builtin_amdgcn_update_dpp(0, __float_as_int(v), 0x101, 0xF, 0xF, true)); }
;     __device__ __forceinline__ void operator()(f32x4 (&acc)[2][2][4][2], const Unit& u, int wr, int wc, int fr, int fq) const {
;     ...
;             for (int i = 0; i < 4; ++i) {
;                 float ag[8], av[8];
; #pragma unroll
;                 for (int j = 0; j < 8; ++j) { ag[j] = acc[j >> 2][0][j & 3][n][i]; av[j] = acc[j >> 2][1][j & 3][n][i]; }
;                 const float lg = dpp_shr1(ag[7]), rg = dpp_shl1(ag[0]), lv = dpp_shr1(av[7]), rv = dpp_shl1(av[0]);
; #pragma unroll
;                 for (int j = 0; j < 8; ++j) {
;                     float Lg = j == 0 ? lg : ag[j == 0 ? 0 : j - 1], Rg = j == 7 ? rg : ag[j == 7 ? 7 : j + 1];
;                     float Lv = j == 0 ? lv : av[j == 0 ? 0 : j - 1], Rv = j == 7 ? rv : av[j == 7 ? 7 : j + 1];
;                     if ((smask >> j) & 1u) { Lg = 0.f; Lv = 0.f; }
;                     if ((emask >> j) & 1u) { Rg = 0.f; Rv = 0.f; }
;                     const float cgv = w0g[i] * Lg + w1g[i] * ag[j] + w2g[i] * Rg + bg[i];
;                     const float cvv = w0v[i] * Lv + w1v[i] * av[j] + w2v[i] * Rv + bv[i];
;                     h[j][i] = gelu_t(cgv) * cvv;
;                 }
;             }
; #pragma unroll
;             for (int j = 0; j < 8; ++j) if ((vmask >> j) & 1u) { u32x2 w; w.x = cvt_pk_bf16(h[j][0], h[j][1]); w.y = cvt_pk_bf16(h[j][2], h[j][3]);
;                 *(u32x2*)(H2 + (size_t)(t0 + j) * 2048 + cg_) = w; }
.LBB0_153:
	v_cndmask_b32_e64 v23, v23, 0, s[50:51]
	v_cndmask_b32_e64 v22, v22, 0, s[50:51]
	v_pk_mul_f32 v[26:27], v[14:15], v[94:95]
	v_cndmask_b32_e64 v19, v19, 0, s[50:51]
	v_pk_fma_f32 v[22:23], v[22:23], v[82:83], v[26:27]
	v_cndmask_b32_e64 v18, v18, 0, s[50:51]
	v_pk_fma_f32 v[22:23], v[6:7], v[86:87], v[22:23]
	v_pk_mul_f32 v[28:29], v[10:11], v[70:71]
	v_pk_add_f32 v[22:23], v[90:91], v[22:23]
	v_pk_fma_f32 v[18:19], v[18:19], v[66:67], v[28:29]
	v_mul_f32_e32 v0, 0xbdd2d3e7, v22
	v_fmaak_f32 v0, v22, v0, 0xc0135761
	v_mul_f32_e32 v0, v22, v0
	v_exp_f32_e32 v0, v0
	v_pk_fma_f32 v[18:19], v[2:3], v[74:75], v[18:19]
	v_cndmask_b32_e64 v21, v21, 0, s[50:51]
	v_pk_add_f32 v[18:19], v[78:79], v[18:19]
	v_add_f32_e32 v0, 1.0, v0
	v_rcp_f32_e32 v26, v0
	v_mul_f32_e32 v0, 0xbdd2d3e7, v23
	v_fmaak_f32 v0, v23, v0, 0xc0135761
	v_mul_f32_e32 v0, v23, v0
	v_exp_f32_e32 v0, v0
	v_cndmask_b32_e64 v20, v20, 0, s[50:51]
	v_add_f32_e32 v0, 1.0, v0
	v_rcp_f32_e32 v27, v0
	s_nop 0
	v_pk_mul_f32 v[22:23], v[22:23], v[26:27]
	s_nop 0
	v_pk_mul_f32 v[18:19], v[18:19], v[22:23]
	v_cndmask_b32_e64 v23, v25, 0, s[50:51]
	v_cndmask_b32_e64 v22, v24, 0, s[50:51]
	v_pk_mul_f32 v[24:25], v[16:17], v[96:97]
	v_pk_mul_f32 v[26:27], v[12:13], v[72:73]
	v_pk_fma_f32 v[22:23], v[22:23], v[84:85], v[24:25]
	v_pk_fma_f32 v[20:21], v[20:21], v[68:69], v[26:27]
	v_pk_fma_f32 v[22:23], v[8:9], v[88:89], v[22:23]
	v_pk_fma_f32 v[20:21], v[4:5], v[76:77], v[20:21]
	v_pk_add_f32 v[22:23], v[92:93], v[22:23]
	v_pk_add_f32 v[20:21], v[80:81], v[20:21]
	v_mul_f32_e32 v0, 0xbdd2d3e7, v22
	v_fmaak_f32 v0, v22, v0, 0xc0135761
	v_mul_f32_e32 v0, v22, v0
	v_exp_f32_e32 v0, v0
	v_cvt_pk_bf16_f32 v18, v18, v19
	v_add_f32_e32 v0, 1.0, v0
	v_rcp_f32_e32 v24, v0
	v_mul_f32_e32 v0, 0xbdd2d3e7, v23
	v_fmaak_f32 v0, v23, v0, 0xc0135761
	v_mul_f32_e32 v0, v23, v0
	v_exp_f32_e32 v0, v0
	s_nop 0
	v_add_f32_e32 v0, 1.0, v0
	v_rcp_f32_e32 v25, v0
	s_nop 0
	v_pk_mul_f32 v[22:23], v[22:23], v[24:25]
	s_nop 0
	v_pk_mul_f32 v[20:21], v[20:21], v[22:23]
	s_nop 0
	v_cvt_pk_bf16_f32 v19, v20, v21
	v_lshlrev_b64 v[20:21], 12, v[128:129]
	v_lshl_add_u64 v[20:21], s[70:71], 0, v[20:21]
	v_lshl_add_u64 v[20:21], v[180:181], 1, v[20:21]
	global_store_dwordx2 v[20:21], v[18:19], off offset:8
	s_or_b64 exec, exec, s[0:1]
	s_and_saveexec_b64 s[0:1], s[66:67]
	s_cbranch_execz .LBB0_148
.LBB0_154:
	v_pk_mul_f32 v[20:21], v[6:7], v[94:95]
	v_cndmask_b32_e64 v19, v55, 0, s[52:53]
	v_cndmask_b32_e64 v18, v54, 0, s[52:53]
	v_pk_fma_f32 v[14:15], v[14:15], v[82:83], v[20:21]
	v_pk_mul_f32 v[22:23], v[2:3], v[70:71]
	v_pk_fma_f32 v[14:15], v[18:19], v[86:87], v[14:15]
	v_cndmask_b32_e64 v21, v47, 0, s[52:53]
	v_pk_add_f32 v[14:15], v[90:91], v[14:15]
	v_cndmask_b32_e64 v20, v46, 0, s[52:53]
	v_mul_f32_e32 v0, 0xbdd2d3e7, v14
	v_fmaak_f32 v0, v14, v0, 0xc0135761
	v_mul_f32_e32 v0, v14, v0
	v_exp_f32_e32 v0, v0
	v_pk_fma_f32 v[10:11], v[10:11], v[66:67], v[22:23]
	v_add_f32_e32 v0, 1.0, v0
	v_rcp_f32_e32 v18, v0
	v_mul_f32_e32 v0, 0xbdd2d3e7, v15
	v_fmaak_f32 v0, v15, v0, 0xc0135761
	v_mul_f32_e32 v0, v15, v0
	v_exp_f32_e32 v0, v0
	v_pk_fma_f32 v[10:11], v[20:21], v[74:75], v[10:11]
	v_pk_mul_f32 v[20:21], v[4:5], v[72:73]
	v_pk_add_f32 v[10:11], v[78:79], v[10:11]
	v_add_f32_e32 v0, 1.0, v0
	v_rcp_f32_e32 v19, v0
	v_pk_fma_f32 v[12:13], v[12:13], v[68:69], v[20:21]
	v_pk_mul_f32 v[14:15], v[14:15], v[18:19]
	v_pk_mul_f32 v[18:19], v[8:9], v[96:97]
	v_pk_mul_f32 v[10:11], v[10:11], v[14:15]
	v_cndmask_b32_e64 v15, v49, 0, s[52:53]
	v_cndmask_b32_e64 v14, v48, 0, s[52:53]
	v_pk_fma_f32 v[16:17], v[16:17], v[84:85], v[18:19]
	v_cndmask_b32_e64 v19, v45, 0, s[52:53]
	v_pk_fma_f32 v[14:15], v[14:15], v[88:89], v[16:17]
	v_cndmask_b32_e64 v18, v44, 0, s[52:53]
	v_pk_add_f32 v[14:15], v[92:93], v[14:15]
	v_pk_fma_f32 v[12:13], v[18:19], v[76:77], v[12:13]
	v_mul_f32_e32 v0, 0xbdd2d3e7, v14
	v_fmaak_f32 v0, v14, v0, 0xc0135761
	v_mul_f32_e32 v0, v14, v0
	v_exp_f32_e32 v0, v0
	v_pk_add_f32 v[12:13], v[80:81], v[12:13]
	v_cvt_pk_bf16_f32 v10, v10, v11
	v_add_f32_e32 v0, 1.0, v0
	v_rcp_f32_e32 v16, v0
	v_mul_f32_e32 v0, 0xbdd2d3e7, v15
	v_fmaak_f32 v0, v15, v0, 0xc0135761
	v_mul_f32_e32 v0, v15, v0
	v_exp_f32_e32 v0, v0
	s_nop 0
	v_add_f32_e32 v0, 1.0, v0
	v_rcp_f32_e32 v17, v0
	s_nop 0
	v_pk_mul_f32 v[14:15], v[14:15], v[16:17]
	s_nop 0
	v_pk_mul_f32 v[12:13], v[12:13], v[14:15]
	s_nop 0
	v_cvt_pk_bf16_f32 v11, v12, v13
	v_lshlrev_b64 v[12:13], 12, v[132:133]
	v_lshl_add_u64 v[12:13], s[70:71], 0, v[12:13]
	v_lshl_add_u64 v[12:13], v[180:181], 1, v[12:13]
	global_store_dwordx2 v[12:13], v[10:11], off offset:8
	s_or_b64 exec, exec, s[0:1]
	s_and_saveexec_b64 s[0:1], s[76:77]
	s_cbranch_execnz .LBB0_149
	s_branch .LBB0_150

; __device__ __forceinline__ void load_rs8(const float* ss, int t0, int fq, float (&rs)[8], int tmax) {
; #pragma unroll
;     for (int j = 0; j < 8; ++j) { int t = t0 + j; t = t < 0 ? 0 : (t > tmax ? tmax : t);
;         const f32x4 p = *(const f32x4*)(ss + (size_t)t * 16 + 4 * fq); float s = (p.x + p.y) + (p.z + p.w);
;         s += __shfl_xor(s, 16); s += __shfl_xor(s, 32); rs[j] = __builtin_amdgcn_rsqf(s * (1.0f / DMOD) + EPS); }
;     __device__ __forceinline__ void operator()(f32x4 (&acc)[2][2][4][2], const Unit& u, int wr, int wc, int fr, int fq) const {
;     ...
;         { float rs[8]; load_rs8(ss, t0, fq, rs, M_TOK - 1);
; #pragma unroll
;           for (int ai = 0; ai < 2; ++ai)
; #pragma unroll
;             for (int m = 0; m < 4; ++m)
; #pragma unroll
;                 for (int bj = 0; bj < 2; ++bj)
; #pragma unroll
;                     for (int n = 0; n < 2; ++n) acc[ai][bj][m][n] = acc[ai][bj][m][n] * rs[4 * ai + m]; }
;         const int pn = u.pn;
;         {
;             const int chunk = 2 * u.pm + wr;
;             bf16_t* dst = VST + ((size_t)chunk * 512 + 256 * (pn - 5) + 32 * wc + 8 * fq) * 128 + 8 * fr;
; #pragma unroll
;             for (int ai = 0; ai < 2; ++ai)
; #pragma unroll
;                 for (int m = 0; m < 4; ++m) {
;                     float sq = 0.f;
; #pragma unroll
;                     for (int bj = 0; bj < 2; ++bj)
; #pragma unroll
;                         for (int n = 0; n < 2; ++n) { f32x4 v = acc[ai][bj][m][n]; v = (f32x4){gelu_t(v.x), gelu_t(v.y), gelu_t(v.z), gelu_t(v.w)}; acc[ai][bj][m][n] = v;
;                             sq += (v.x * v.x + v.y * v.y) + (v.z * v.z + v.w * v.w); }
;                     sq += __shfl_xor(sq, 16); sq += __shfl_xor(sq, 32);
;                     if (fq == 0) ssg[(size_t)(t0 + 4 * ai + m) * 8 + 4 * (pn - 5) + wc] = sq;
.LBB0_406:
	s_lshl_b32 s33, s46, 8
	s_add_i32 s33, s33, s80
	v_or_b32_e32 v160, s33, v162
	v_min_u32_e32 v0, 0x17fff, v160
	s_cmp_gt_i32 s33, -1
	v_lshlrev_b32_e32 v0, 4, v0
	s_cselect_b64 vcc, -1, 0
	v_cndmask_b32_e32 v0, 0, v0, vcc
	v_lshlrev_b32_e32 v0, 2, v0
	v_lshl_add_u64 v[130:131], v[154:155], 0, v[0:1]
	v_min_i32_e32 v0, 0x17ffe, v160
	v_lshl_or_b32 v0, v0, 4, 16
	v_cmp_lt_i32_e32 vcc, -2, v160
	global_load_dwordx4 v[130:133], v[130:131], off
	v_and_b32_e32 v161, 64, v219
	v_cndmask_b32_e32 v0, 0, v0, vcc
	v_lshl_add_u64 v[134:135], v[0:1], 2, v[154:155]
	v_min_i32_e32 v0, 0x17ffd, v160
	v_lshl_or_b32 v0, v0, 4, 32
	v_cmp_lt_i32_e32 vcc, -3, v160
	global_load_dwordx4 v[134:137], v[134:135], off
	v_add_u32_e32 v161, 64, v161
	v_cndmask_b32_e32 v0, 0, v0, vcc
	v_lshl_add_u64 v[138:139], v[0:1], 2, v[154:155]
	v_min_i32_e32 v0, 0x17ffc, v160
	v_lshl_or_b32 v0, v0, 4, 48
	v_cmp_lt_i32_e32 vcc, -4, v160
	global_load_dwordx4 v[166:169], v[138:139], off
	v_xor_b32_e32 v164, 32, v219
	v_cndmask_b32_e32 v0, 0, v0, vcc
	v_lshl_add_u64 v[138:139], v[0:1], 2, v[154:155]
	v_min_i32_e32 v0, 0x17ffb, v160
	v_lshl_or_b32 v0, v0, 4, 64
	v_cmp_lt_i32_e32 vcc, -5, v160
	global_load_dwordx4 v[170:173], v[138:139], off
	s_add_i32 s33, s20, -5
	v_cndmask_b32_e32 v0, 0, v0, vcc
	v_lshl_add_u64 v[138:139], v[0:1], 2, v[154:155]
	v_min_i32_e32 v0, 0x17ffa, v160
	v_lshl_or_b32 v0, v0, 4, v220
	v_cmp_lt_i32_e32 vcc, -6, v160
	global_load_dwordx4 v[174:177], v[138:139], off
	s_lshl_b32 s56, s33, 2
	v_cndmask_b32_e32 v0, 0, v0, vcc
	v_lshl_add_u64 v[138:139], v[0:1], 2, v[154:155]
	v_min_i32_e32 v0, 0x17ff9, v160
	v_lshl_or_b32 v0, v0, 4, v221
	v_cmp_lt_i32_e32 vcc, -7, v160
	global_load_dwordx4 v[178:181], v[138:139], off
	s_ashr_i32 s57, s56, 31
	v_cndmask_b32_e32 v0, 0, v0, vcc
	v_lshl_add_u64 v[138:139], v[0:1], 2, v[154:155]
	v_min_i32_e32 v0, 0x17ff8, v160
	v_lshl_or_b32 v0, v0, 4, v222
	v_cmp_lt_i32_e32 vcc, -8, v160
	global_load_dwordx4 v[182:185], v[138:139], off
	s_waitcnt vmcnt(0)
	v_mov_b32_e32 v186, v131
	v_cndmask_b32_e32 v0, 0, v0, vcc
	v_lshl_add_u64 v[138:139], v[0:1], 2, v[154:155]
	global_load_dwordx4 v[138:141], v[138:139], off
	v_xor_b32_e32 v0, 16, v219
	v_cmp_lt_i32_e32 vcc, v0, v161
	v_mov_b32_e32 v187, v132
	v_mov_b32_e32 v131, v133
	v_cndmask_b32_e32 v0, v219, v0, vcc
	v_pk_add_f32 v[130:131], v[186:187], v[130:131]
	v_lshlrev_b32_e32 v165, 2, v0
	v_mov_b32_e32 v132, v135
	v_mov_b32_e32 v133, v136
	v_mov_b32_e32 v135, v137
	v_add_f32_e32 v0, v130, v131
	v_pk_add_f32 v[130:131], v[132:133], v[134:135]
	ds_bpermute_b32 v134, v165, v0
	v_cmp_lt_i32_e32 vcc, v164, v161
	v_mov_b32_e32 v132, v167
	v_mov_b32_e32 v133, v168
	v_cndmask_b32_e32 v161, v219, v164, vcc
	v_lshlrev_b32_e32 v164, 2, v161
	s_waitcnt lgkmcnt(0)
	v_add_f32_e32 v0, v0, v134
	v_mov_b32_e32 v167, v169
	ds_bpermute_b32 v134, v164, v0
	v_add_f32_e32 v135, v130, v131
	v_pk_add_f32 v[130:131], v[132:133], v[166:167]
	v_mov_b32_e32 v132, v171
	v_mov_b32_e32 v133, v172
	v_mov_b32_e32 v171, v173
	v_add_f32_e32 v137, v130, v131
	v_pk_add_f32 v[130:131], v[132:133], v[170:171]
	v_mov_b32_e32 v132, v175
	v_mov_b32_e32 v133, v176
	v_mov_b32_e32 v175, v177
	v_add_f32_e32 v166, v130, v131
	v_pk_add_f32 v[130:131], v[132:133], v[174:175]
	ds_bpermute_b32 v167, v165, v166
	v_add_f32_e32 v172, v130, v131
	ds_bpermute_b32 v173, v165, v172
	s_waitcnt lgkmcnt(2)
	v_add_f32_e32 v0, v0, v134
	v_fmamk_f32 v0, v0, 0x3a800000, v218
	v_rsq_f32_e32 v0, v0
	s_waitcnt lgkmcnt(1)
	v_add_f32_e32 v168, v166, v167
	s_waitcnt lgkmcnt(0)
	v_add_f32_e32 v166, v172, v173
	ds_bpermute_b32 v161, v165, v137
	v_pk_mul_f32 v[174:175], v[58:59], v[0:1] op_sel_hi:[1,0]
	v_pk_mul_f32 v[58:59], v[54:55], v[0:1] op_sel_hi:[1,0]
	v_mul_f32_e32 v54, 0xbdd2d3e7, v175
	v_fmaak_f32 v54, v175, v54, 0xc0135761
	v_mul_f32_e32 v54, v175, v54
	v_exp_f32_e32 v55, v54
	s_waitcnt lgkmcnt(0)
	v_add_f32_e32 v170, v137, v161
	v_mul_f32_e32 v137, 0xbdd2d3e7, v59
	v_fmaak_f32 v137, v59, v137, 0xc0135761
	v_mul_f32_e32 v137, v59, v137
	v_exp_f32_e32 v137, v137
	v_mov_b32_e32 v132, v179
	v_mov_b32_e32 v133, v180
	v_mov_b32_e32 v179, v181
	v_pk_add_f32 v[132:133], v[132:133], v[178:179]
	ds_bpermute_b32 v136, v165, v135
	v_add_f32_e32 v132, v132, v133
	ds_bpermute_b32 v133, v165, v132
	ds_bpermute_b32 v171, v164, v170
	ds_bpermute_b32 v169, v164, v168
	s_waitcnt lgkmcnt(3)
	v_add_f32_e32 v130, v135, v136
	ds_bpermute_b32 v131, v164, v130
	s_waitcnt lgkmcnt(3)
	v_add_f32_e32 v135, v132, v133
	v_mov_b32_e32 v132, v183
	v_mov_b32_e32 v133, v184
	v_mov_b32_e32 v183, v185
	v_pk_add_f32 v[132:133], v[132:133], v[182:183]
	ds_bpermute_b32 v167, v164, v166
	v_add_f32_e32 v132, v132, v133
	ds_bpermute_b32 v133, v165, v132
	ds_bpermute_b32 v136, v164, v135
	s_waitcnt vmcnt(0)
;     __device__ __forceinline__ void operator()(f32x4 (&acc)[2][2][4][2], const Unit& u, int wr, int wc, int fr, int fq) const {
;     ...
;                     float sq = 0.f;
; #pragma unroll
;                     for (int bj = 0; bj < 2; ++bj)
; #pragma unroll
;                         for (int n = 0; n < 2; ++n) { f32x4 v = acc[ai][bj][m][n]; v = (f32x4){gelu_t(v.x), gelu_t(v.y), gelu_t(v.z), gelu_t(v.w)}; acc[ai][bj][m][n] = v;
;                             sq += (v.x * v.x + v.y * v.y) + (v.z * v.z + v.w * v.w); }
;                     sq += __shfl_xor(sq, 16); sq += __shfl_xor(sq, 32);
;                     if (fq == 0) ssg[(size_t)(t0 + 4 * ai + m) * 8 + 4 * (pn - 5) + wc] = sq;
	v_mov_b32_e32 v172, v139
	v_mov_b32_e32 v173, v140
	v_mov_b32_e32 v139, v141
	v_pk_add_f32 v[138:139], v[172:173], v[138:139]
	v_pk_mul_f32 v[140:141], v[62:63], v[0:1] op_sel_hi:[1,0]
	v_add_f32_e32 v134, v138, v139
	v_pk_mul_f32 v[138:139], v[64:65], v[0:1] op_sel_hi:[1,0]
	v_pk_mul_f32 v[64:65], v[52:53], v[0:1] op_sel_hi:[1,0]
	v_mul_f32_e32 v52, 0xbdd2d3e7, v140
	v_fmaak_f32 v52, v140, v52, 0xc0135761
	v_mul_f32_e32 v53, 0xbdd2d3e7, v141
	v_mul_f32_e32 v52, v140, v52
	v_fmaak_f32 v53, v141, v53, 0xc0135761
	v_mul_f32_e32 v53, v141, v53
	v_exp_f32_e32 v52, v52
	s_nop 0
	v_exp_f32_e32 v53, v53
	v_pk_mul_f32 v[172:173], v[60:61], v[0:1] op_sel_hi:[1,0]
	v_pk_mul_f32 v[60:61], v[56:57], v[0:1] op_sel_hi:[1,0]
	v_pk_mul_f32 v[62:63], v[50:51], v[0:1] op_sel_hi:[1,0]
	v_add_f32_e32 v0, 1.0, v52
	v_rcp_f32_e32 v50, v0
	v_add_f32_e32 v0, 1.0, v53
	v_rcp_f32_e32 v51, v0
	v_mul_f32_e32 v0, 0xbdd2d3e7, v138
	v_fmaak_f32 v0, v138, v0, 0xc0135761
	v_mul_f32_e32 v52, 0xbdd2d3e7, v139
	v_mul_f32_e32 v0, v138, v0
	v_fmaak_f32 v52, v139, v52, 0xc0135761
	v_mul_f32_e32 v52, v139, v52
	v_exp_f32_e32 v0, v0
	s_nop 0
	v_exp_f32_e32 v53, v52
	v_pk_mul_f32 v[50:51], v[140:141], v[50:51]
	v_add_f32_e32 v0, 1.0, v0
	v_rcp_f32_e32 v52, v0
	v_add_f32_e32 v0, 1.0, v53
	v_rcp_f32_e32 v53, v0
	v_mul_f32_e32 v0, 0xbdd2d3e7, v174
	v_fmaak_f32 v0, v174, v0, 0xc0135761
	v_mul_f32_e32 v0, v174, v0
	v_exp_f32_e32 v0, v0
	v_pk_mul_f32 v[52:53], v[138:139], v[52:53]
	v_pk_mul_f32 v[138:139], v[50:51], v[50:51]
	v_pk_mul_f32 v[140:141], v[52:53], v[52:53]
	v_add_f32_e32 v0, 1.0, v0
	v_rcp_f32_e32 v54, v0
	v_add_f32_e32 v0, 1.0, v55
	v_mul_f32_e32 v55, 0xbdd2d3e7, v172
	v_fmaak_f32 v55, v172, v55, 0xc0135761
	v_mul_f32_e32 v55, v172, v55
	v_exp_f32_e32 v56, v55
	v_mul_f32_e32 v55, 0xbdd2d3e7, v173
	v_fmaak_f32 v55, v173, v55, 0xc0135761
	v_mul_f32_e32 v55, v173, v55
	v_exp_f32_e32 v57, v55
	v_rcp_f32_e32 v55, v0
	v_add_f32_e32 v0, 1.0, v56
	v_rcp_f32_e32 v56, v0
	v_add_f32_e32 v0, 1.0, v57
	v_rcp_f32_e32 v57, v0
	v_mul_f32_e32 v0, 0xbdd2d3e7, v58
	v_fmaak_f32 v0, v58, v0, 0xc0135761
	v_mul_f32_e32 v0, v58, v0
	v_exp_f32_e32 v0, v0
	v_pk_mul_f32 v[54:55], v[174:175], v[54:55]
	v_pk_mul_f32 v[56:57], v[172:173], v[56:57]
	v_pk_mul_f32 v[172:173], v[54:55], v[54:55]
	v_add_f32_e32 v0, 1.0, v0
	v_rcp_f32_e32 v176, v0
	v_add_f32_e32 v0, 1.0, v137
	v_rcp_f32_e32 v177, v0
	v_mul_f32_e32 v0, 0xbdd2d3e7, v60
	v_fmaak_f32 v0, v60, v0, 0xc0135761
	v_mul_f32_e32 v137, 0xbdd2d3e7, v61
	v_mul_f32_e32 v0, v60, v0
	v_fmaak_f32 v137, v61, v137, 0xc0135761
	v_mul_f32_e32 v137, v61, v137
	v_exp_f32_e32 v0, v0
	s_nop 0
	v_exp_f32_e32 v137, v137
	v_pk_mul_f32 v[58:59], v[58:59], v[176:177]
	v_add_f32_e32 v0, 1.0, v0
	v_rcp_f32_e32 v176, v0
	v_add_f32_e32 v0, 1.0, v137
	v_rcp_f32_e32 v177, v0
	v_mul_f32_e32 v0, 0xbdd2d3e7, v62
	v_fmaak_f32 v0, v62, v0, 0xc0135761
	v_mul_f32_e32 v137, 0xbdd2d3e7, v63
	v_mul_f32_e32 v0, v62, v0
	v_fmaak_f32 v137, v63, v137, 0xc0135761
	v_mul_f32_e32 v137, v63, v137
	v_exp_f32_e32 v0, v0
	s_nop 0
	v_exp_f32_e32 v137, v137
	v_pk_mul_f32 v[60:61], v[60:61], v[176:177]
	v_add_f32_e32 v0, 1.0, v0
	v_rcp_f32_e32 v176, v0
	v_add_f32_e32 v0, 1.0, v137
	v_mul_f32_e32 v137, 0xbdd2d3e7, v64
	v_fmaak_f32 v137, v64, v137, 0xc0135761
	v_mul_f32_e32 v177, 0xbdd2d3e7, v65
	v_mul_f32_e32 v137, v64, v137
	v_fmaak_f32 v177, v65, v177, 0xc0135761
	v_mul_f32_e32 v177, v65, v177
	v_exp_f32_e32 v137, v137
	s_nop 0
	v_exp_f32_e32 v179, v177
	v_rcp_f32_e32 v177, v0
	v_add_f32_e32 v0, 1.0, v137
	v_rcp_f32_e32 v178, v0
	v_add_f32_e32 v0, 1.0, v179
	v_pk_mul_f32 v[174:175], v[56:57], v[56:57]
	v_rcp_f32_e32 v179, v0
	v_add_f32_e32 v0, v174, v175
	v_add_f32_e32 v137, v172, v173
	v_add_f32_e32 v0, v137, v0
	v_add_f32_e32 v137, v140, v141
	v_add_f32_e32 v138, v138, v139
	v_pk_mul_f32 v[180:181], v[58:59], v[58:59]
	v_pk_mul_f32 v[182:183], v[60:61], v[60:61]
	v_add_f32_e32 v137, v138, v137
	v_pk_mul_f32 v[62:63], v[62:63], v[176:177]
	v_pk_mul_f32 v[64:65], v[64:65], v[178:179]
	v_add_f32_e32 v0, v137, v0
	v_add_f32_e32 v137, v182, v183
	v_add_f32_e32 v138, v180, v181
	v_pk_mul_f32 v[176:177], v[62:63], v[62:63]
	v_pk_mul_f32 v[178:179], v[64:65], v[64:65]
	v_add_f32_e32 v137, v138, v137
	v_add_f32_e32 v0, v137, v0
	v_add_f32_e32 v137, v178, v179
	v_add_f32_e32 v138, v176, v177
	v_add_f32_e32 v137, v138, v137
	v_add_f32_e32 v139, v137, v0
	ds_bpermute_b32 v161, v165, v134
	ds_bpermute_b32 v140, v165, v139
	s_waitcnt lgkmcnt(3)
	v_add_f32_e32 v137, v132, v133
	ds_bpermute_b32 v138, v164, v137
	s_waitcnt lgkmcnt(2)
	v_add_f32_e32 v0, v134, v161
	s_waitcnt lgkmcnt(1)
	v_add_f32_e32 v132, v139, v140
	ds_bpermute_b32 v134, v164, v0
	ds_bpermute_b32 v133, v164, v132
	s_and_saveexec_b64 s[58:59], s[38:39]
	v_readlane_b32 s34, v252, 13
	v_readlane_b32 s35, v252, 14
	s_cbranch_execz .LBB0_408
	v_ashrrev_i32_e32 v161, 31, v160
	v_lshlrev_b64 v[140:141], 5, v[160:161]
	v_lshl_add_u64 v[140:141], s[34:35], 0, v[140:141]
	v_lshl_add_u64 v[140:141], s[56:57], 2, v[140:141]
	s_lshl_b32 s20, s75, 2
	v_lshl_add_u64 v[140:141], v[140:141], 0, s[20:21]
	s_waitcnt lgkmcnt(0)
	v_add_f32_e32 v132, v132, v133
	global_store_dword v[140:141], v132, off
;     __device__ __forceinline__ void operator()(f32x4 (&acc)[2][2][4][2], const Unit& u, int wr, int wc, int fr, int fq) const {
;     ...
;                     float sq = 0.f;
; #pragma unroll
;                     for (int bj = 0; bj < 2; ++bj)
; #pragma unroll
;                         for (int n = 0; n < 2; ++n) { f32x4 v = acc[ai][bj][m][n]; v = (f32x4){gelu_t(v.x), gelu_t(v.y), gelu_t(v.z), gelu_t(v.w)}; acc[ai][bj][m][n] = v;
;                             sq += (v.x * v.x + v.y * v.y) + (v.z * v.z + v.w * v.w); }
;                     sq += __shfl_xor(sq, 16); sq += __shfl_xor(sq, 32);
;                     if (fq == 0) ssg[(size_t)(t0 + 4 * ai + m) * 8 + 4 * (pn - 5) + wc] = sq;
.LBB0_408:
	s_or_b64 exec, exec, s[58:59]
	v_add_f32_e32 v130, v130, v131
	v_fmamk_f32 v130, v130, 0x3a800000, v218
	v_rsq_f32_e32 v130, v130
	s_nop 0
	v_pk_mul_f32 v[174:175], v[90:91], v[130:131] op_sel_hi:[1,0]
	v_pk_mul_f32 v[90:91], v[86:87], v[130:131] op_sel_hi:[1,0]
	v_mul_f32_e32 v86, 0xbdd2d3e7, v174
	v_mul_f32_e32 v87, 0xbdd2d3e7, v175
	v_fmaak_f32 v86, v174, v86, 0xc0135761
	v_fmaak_f32 v87, v175, v87, 0xc0135761
	v_mul_f32_e32 v86, v174, v86
	v_mul_f32_e32 v87, v175, v87
	v_exp_f32_e32 v86, v86
	v_exp_f32_e32 v87, v87
	v_mul_f32_e32 v139, 0xbdd2d3e7, v90
	v_fmaak_f32 v139, v90, v139, 0xc0135761
	v_mul_f32_e32 v139, v90, v139
	v_add_f32_e32 v86, 1.0, v86
	v_add_f32_e32 v87, 1.0, v87
	v_exp_f32_e32 v139, v139
	v_rcp_f32_e32 v86, v86
	v_rcp_f32_e32 v87, v87
	v_pk_mul_f32 v[172:173], v[92:93], v[130:131] op_sel_hi:[1,0]
	v_add_f32_e32 v139, 1.0, v139
	v_pk_mul_f32 v[92:93], v[88:89], v[130:131] op_sel_hi:[1,0]
	v_pk_mul_f32 v[86:87], v[174:175], v[86:87]
	v_rcp_f32_e32 v174, v139
	v_mul_f32_e32 v139, 0xbdd2d3e7, v91
	v_fmaak_f32 v139, v91, v139, 0xc0135761
	v_mul_f32_e32 v139, v91, v139
	v_exp_f32_e32 v139, v139
	v_pk_mul_f32 v[140:141], v[94:95], v[130:131] op_sel_hi:[1,0]
	v_pk_mul_f32 v[94:95], v[82:83], v[130:131] op_sel_hi:[1,0]
	s_waitcnt lgkmcnt(0)
	v_pk_mul_f32 v[132:133], v[96:97], v[130:131] op_sel_hi:[1,0]
	v_add_f32_e32 v139, 1.0, v139
	v_rcp_f32_e32 v175, v139
	v_mul_f32_e32 v139, 0xbdd2d3e7, v92
	v_fmaak_f32 v139, v92, v139, 0xc0135761
	v_mul_f32_e32 v139, v92, v139
	v_exp_f32_e32 v139, v139
	v_pk_mul_f32 v[90:91], v[90:91], v[174:175]
	v_pk_mul_f32 v[96:97], v[84:85], v[130:131] op_sel_hi:[1,0]
	v_mul_f32_e32 v82, 0xbdd2d3e7, v140
	v_add_f32_e32 v139, 1.0, v139
	v_rcp_f32_e32 v174, v139
	v_mul_f32_e32 v139, 0xbdd2d3e7, v93
	v_fmaak_f32 v139, v93, v139, 0xc0135761
	v_mul_f32_e32 v139, v93, v139
	v_exp_f32_e32 v139, v139
	v_mul_f32_e32 v83, 0xbdd2d3e7, v141
	v_mul_f32_e32 v84, 0xbdd2d3e7, v132
	v_mul_f32_e32 v85, 0xbdd2d3e7, v133
	v_add_f32_e32 v139, 1.0, v139
	v_rcp_f32_e32 v175, v139
	v_mul_f32_e32 v139, 0xbdd2d3e7, v94
	v_fmaak_f32 v139, v94, v139, 0xc0135761
	v_mul_f32_e32 v139, v94, v139
	v_exp_f32_e32 v139, v139
	v_mul_f32_e32 v88, 0xbdd2d3e7, v172
	v_mul_f32_e32 v89, 0xbdd2d3e7, v173
	v_fmaak_f32 v82, v140, v82, 0xc0135761
	v_add_f32_e32 v139, 1.0, v139
	v_rcp_f32_e32 v178, v139
	v_mul_f32_e32 v139, 0xbdd2d3e7, v95
	v_fmaak_f32 v139, v95, v139, 0xc0135761
	v_mul_f32_e32 v139, v95, v139
	v_exp_f32_e32 v139, v139
	v_fmaak_f32 v83, v141, v83, 0xc0135761
	v_fmaak_f32 v84, v132, v84, 0xc0135761
	v_fmaak_f32 v85, v133, v85, 0xc0135761
	v_add_f32_e32 v139, 1.0, v139
	v_rcp_f32_e32 v179, v139
	v_mul_f32_e32 v139, 0xbdd2d3e7, v96
	v_fmaak_f32 v139, v96, v139, 0xc0135761
	v_mul_f32_e32 v139, v96, v139
	v_exp_f32_e32 v139, v139
	v_fmaak_f32 v88, v172, v88, 0xc0135761
	v_fmaak_f32 v89, v173, v89, 0xc0135761
	v_mul_f32_e32 v82, v140, v82
	v_mul_f32_e32 v83, v141, v83
	v_mul_f32_e32 v84, v132, v84
	v_mul_f32_e32 v85, v133, v85
	v_mul_f32_e32 v88, v172, v88
	v_mul_f32_e32 v89, v173, v89
	v_add_f32_e32 v139, 1.0, v139
	v_pk_mul_f32 v[94:95], v[94:95], v[178:179]
	v_rcp_f32_e32 v178, v139
	v_mul_f32_e32 v139, 0xbdd2d3e7, v97
	v_exp_f32_e32 v82, v82
	v_exp_f32_e32 v83, v83
	v_exp_f32_e32 v84, v84
	v_exp_f32_e32 v85, v85
	v_exp_f32_e32 v88, v88
	v_exp_f32_e32 v89, v89
	v_fmaak_f32 v139, v97, v139, 0xc0135761
	v_mul_f32_e32 v139, v97, v139
	v_exp_f32_e32 v139, v139
	v_add_f32_e32 v82, 1.0, v82
	v_add_f32_e32 v83, 1.0, v83
	v_add_f32_e32 v84, 1.0, v84
	v_add_f32_e32 v85, 1.0, v85
	v_add_f32_e32 v88, 1.0, v88
	v_add_f32_e32 v89, 1.0, v89
	v_rcp_f32_e32 v82, v82
	v_rcp_f32_e32 v83, v83
	v_rcp_f32_e32 v84, v84
	v_rcp_f32_e32 v85, v85
	v_rcp_f32_e32 v88, v88
	v_rcp_f32_e32 v89, v89
	v_add_f32_e32 v139, 1.0, v139
	v_rcp_f32_e32 v179, v139
	v_pk_mul_f32 v[82:83], v[140:141], v[82:83]
	v_pk_mul_f32 v[84:85], v[132:133], v[84:85]
	v_pk_mul_f32 v[88:89], v[172:173], v[88:89]
	v_pk_mul_f32 v[130:131], v[82:83], v[82:83]
	v_pk_mul_f32 v[132:133], v[84:85], v[84:85]
	v_pk_mul_f32 v[140:141], v[86:87], v[86:87]
	v_pk_mul_f32 v[172:173], v[88:89], v[88:89]
	v_pk_mul_f32 v[92:93], v[92:93], v[174:175]
	v_pk_mul_f32 v[174:175], v[90:91], v[90:91]
	v_pk_mul_f32 v[176:177], v[92:93], v[92:93]
	v_add_f32_e32 v139, v172, v173
	v_add_f32_e32 v140, v140, v141
	v_add_f32_e32 v132, v132, v133
	v_add_f32_e32 v130, v130, v131
	v_pk_mul_f32 v[96:97], v[96:97], v[178:179]
	v_add_f32_e32 v139, v140, v139
	v_add_f32_e32 v130, v130, v132
	v_add_f32_e32 v131, v176, v177
	v_add_f32_e32 v132, v174, v175
	v_pk_mul_f32 v[178:179], v[94:95], v[94:95]
	v_pk_mul_f32 v[180:181], v[96:97], v[96:97]
	v_add_f32_e32 v130, v130, v139
	v_add_f32_e32 v131, v132, v131
	v_add_f32_e32 v130, v131, v130
	v_add_f32_e32 v131, v180, v181
	v_add_f32_e32 v132, v178, v179
	v_add_f32_e32 v131, v132, v131
	v_add_f32_e32 v130, v131, v130
	ds_bpermute_b32 v131, v165, v130
	s_waitcnt lgkmcnt(0)
	v_add_f32_e32 v130, v130, v131
	ds_bpermute_b32 v131, v164, v130
	s_and_saveexec_b64 s[58:59], s[38:39]
	s_cbranch_execz .LBB0_410
	s_waitcnt lgkmcnt(0)
	v_add_f32_e32 v132, v130, v131
	v_or_b32_e32 v130, 1, v160
	v_ashrrev_i32_e32 v131, 31, v130
	v_lshlrev_b64 v[130:131], 5, v[130:131]
	v_lshl_add_u64 v[130:131], s[34:35], 0, v[130:131]
	v_lshl_add_u64 v[130:131], s[56:57], 2, v[130:131]
	s_lshl_b32 s20, s75, 2
	v_lshl_add_u64 v[130:131], v[130:131], 0, s[20:21]
	global_store_dword v[130:131], v132, off
;     __device__ __forceinline__ void operator()(f32x4 (&acc)[2][2][4][2], const Unit& u, int wr, int wc, int fr, int fq) const {
;     ...
;                     float sq = 0.f;
; #pragma unroll
;                     for (int bj = 0; bj < 2; ++bj)
; #pragma unroll
;                         for (int n = 0; n < 2; ++n) { f32x4 v = acc[ai][bj][m][n]; v = (f32x4){gelu_t(v.x), gelu_t(v.y), gelu_t(v.z), gelu_t(v.w)}; acc[ai][bj][m][n] = v;
;                             sq += (v.x * v.x + v.y * v.y) + (v.z * v.z + v.w * v.w); }
;                     sq += __shfl_xor(sq, 16); sq += __shfl_xor(sq, 32);
;                     if (fq == 0) ssg[(size_t)(t0 + 4 * ai + m) * 8 + 4 * (pn - 5) + wc] = sq;
.LBB0_410:
	s_or_b64 exec, exec, s[58:59]
	v_add_f32_e32 v130, v170, v171
	v_fmamk_f32 v130, v130, 0x3a800000, v218
	v_rsq_f32_e32 v130, v130
	s_waitcnt lgkmcnt(0)
	v_pk_mul_f32 v[172:173], v[122:123], v[130:131] op_sel_hi:[1,0]
	v_pk_mul_f32 v[122:123], v[118:119], v[130:131] op_sel_hi:[1,0]
	v_mul_f32_e32 v118, 0xbdd2d3e7, v172
	v_mul_f32_e32 v119, 0xbdd2d3e7, v173
	v_fmaak_f32 v118, v172, v118, 0xc0135761
	v_fmaak_f32 v119, v173, v119, 0xc0135761
	v_mul_f32_e32 v118, v172, v118
	v_mul_f32_e32 v119, v173, v119
	v_exp_f32_e32 v118, v118
	v_exp_f32_e32 v119, v119
	v_mul_f32_e32 v139, 0xbdd2d3e7, v122
	v_fmaak_f32 v139, v122, v139, 0xc0135761
	v_mul_f32_e32 v139, v122, v139
	v_add_f32_e32 v118, 1.0, v118
	v_add_f32_e32 v119, 1.0, v119
	v_exp_f32_e32 v139, v139
	v_rcp_f32_e32 v118, v118
	v_rcp_f32_e32 v119, v119
	v_pk_mul_f32 v[170:171], v[124:125], v[130:131] op_sel_hi:[1,0]
	v_add_f32_e32 v139, 1.0, v139
	v_pk_mul_f32 v[124:125], v[120:121], v[130:131] op_sel_hi:[1,0]
	v_pk_mul_f32 v[118:119], v[172:173], v[118:119]
	v_rcp_f32_e32 v172, v139
	v_mul_f32_e32 v139, 0xbdd2d3e7, v123
	v_fmaak_f32 v139, v123, v139, 0xc0135761
	v_mul_f32_e32 v139, v123, v139
	v_exp_f32_e32 v139, v139
	v_pk_mul_f32 v[140:141], v[126:127], v[130:131] op_sel_hi:[1,0]
	v_pk_mul_f32 v[126:127], v[106:107], v[130:131] op_sel_hi:[1,0]
	v_pk_mul_f32 v[132:133], v[128:129], v[130:131] op_sel_hi:[1,0]
	v_add_f32_e32 v139, 1.0, v139
	v_rcp_f32_e32 v173, v139
	v_mul_f32_e32 v139, 0xbdd2d3e7, v124
	v_fmaak_f32 v139, v124, v139, 0xc0135761
	v_mul_f32_e32 v139, v124, v139
	v_exp_f32_e32 v139, v139
	v_pk_mul_f32 v[122:123], v[122:123], v[172:173]
	v_pk_mul_f32 v[128:129], v[108:109], v[130:131] op_sel_hi:[1,0]
	v_mul_f32_e32 v106, 0xbdd2d3e7, v140
	v_add_f32_e32 v139, 1.0, v139
	v_rcp_f32_e32 v172, v139
	v_mul_f32_e32 v139, 0xbdd2d3e7, v125
	v_fmaak_f32 v139, v125, v139, 0xc0135761
	v_mul_f32_e32 v139, v125, v139
	v_exp_f32_e32 v139, v139
	v_mul_f32_e32 v107, 0xbdd2d3e7, v141
	v_mul_f32_e32 v108, 0xbdd2d3e7, v132
	v_mul_f32_e32 v109, 0xbdd2d3e7, v133
	v_add_f32_e32 v139, 1.0, v139
	v_rcp_f32_e32 v173, v139
	v_mul_f32_e32 v139, 0xbdd2d3e7, v126
	v_fmaak_f32 v139, v126, v139, 0xc0135761
	v_mul_f32_e32 v139, v126, v139
	v_exp_f32_e32 v139, v139
	v_mul_f32_e32 v120, 0xbdd2d3e7, v170
	v_mul_f32_e32 v121, 0xbdd2d3e7, v171
	v_fmaak_f32 v106, v140, v106, 0xc0135761
	v_add_f32_e32 v139, 1.0, v139
	v_rcp_f32_e32 v176, v139
	v_mul_f32_e32 v139, 0xbdd2d3e7, v127
	v_fmaak_f32 v139, v127, v139, 0xc0135761
	v_mul_f32_e32 v139, v127, v139
	v_exp_f32_e32 v139, v139
	v_fmaak_f32 v107, v141, v107, 0xc0135761
	v_fmaak_f32 v108, v132, v108, 0xc0135761
	v_fmaak_f32 v109, v133, v109, 0xc0135761
	v_add_f32_e32 v139, 1.0, v139
	v_rcp_f32_e32 v177, v139
	v_mul_f32_e32 v139, 0xbdd2d3e7, v128
	v_fmaak_f32 v139, v128, v139, 0xc0135761
	v_mul_f32_e32 v139, v128, v139
	v_exp_f32_e32 v139, v139
	v_fmaak_f32 v120, v170, v120, 0xc0135761
	v_fmaak_f32 v121, v171, v121, 0xc0135761
	v_mul_f32_e32 v106, v140, v106
	v_mul_f32_e32 v107, v141, v107
	v_mul_f32_e32 v108, v132, v108
	v_mul_f32_e32 v109, v133, v109
	v_mul_f32_e32 v120, v170, v120
	v_mul_f32_e32 v121, v171, v121
	v_add_f32_e32 v139, 1.0, v139
	v_pk_mul_f32 v[126:127], v[126:127], v[176:177]
	v_rcp_f32_e32 v176, v139
	v_mul_f32_e32 v139, 0xbdd2d3e7, v129
	v_exp_f32_e32 v106, v106
	v_exp_f32_e32 v107, v107
	v_exp_f32_e32 v108, v108
	v_exp_f32_e32 v109, v109
	v_exp_f32_e32 v120, v120
	v_exp_f32_e32 v121, v121
	v_fmaak_f32 v139, v129, v139, 0xc0135761
	v_mul_f32_e32 v139, v129, v139
	v_exp_f32_e32 v139, v139
	v_add_f32_e32 v106, 1.0, v106
	v_add_f32_e32 v107, 1.0, v107
	v_add_f32_e32 v108, 1.0, v108
	v_add_f32_e32 v109, 1.0, v109
	v_add_f32_e32 v120, 1.0, v120
	v_add_f32_e32 v121, 1.0, v121
	v_rcp_f32_e32 v106, v106
	v_rcp_f32_e32 v107, v107
	v_rcp_f32_e32 v108, v108
	v_rcp_f32_e32 v109, v109
	v_rcp_f32_e32 v120, v120
	v_rcp_f32_e32 v121, v121
	v_add_f32_e32 v139, 1.0, v139
	v_rcp_f32_e32 v177, v139
	v_pk_mul_f32 v[106:107], v[140:141], v[106:107]
	v_pk_mul_f32 v[108:109], v[132:133], v[108:109]
	v_pk_mul_f32 v[120:121], v[170:171], v[120:121]
	v_pk_mul_f32 v[130:131], v[106:107], v[106:107]
	v_pk_mul_f32 v[132:133], v[108:109], v[108:109]
	v_pk_mul_f32 v[140:141], v[118:119], v[118:119]
	v_pk_mul_f32 v[170:171], v[120:121], v[120:121]
	v_pk_mul_f32 v[124:125], v[124:125], v[172:173]
	v_pk_mul_f32 v[172:173], v[122:123], v[122:123]
	v_pk_mul_f32 v[174:175], v[124:125], v[124:125]
	v_add_f32_e32 v139, v170, v171
	v_add_f32_e32 v140, v140, v141
	v_add_f32_e32 v132, v132, v133
	v_add_f32_e32 v130, v130, v131
	v_pk_mul_f32 v[128:129], v[128:129], v[176:177]
	v_add_f32_e32 v139, v140, v139
	v_add_f32_e32 v130, v130, v132
	v_add_f32_e32 v131, v174, v175
	v_add_f32_e32 v132, v172, v173
	v_pk_mul_f32 v[176:177], v[126:127], v[126:127]
	v_pk_mul_f32 v[178:179], v[128:129], v[128:129]
	v_add_f32_e32 v130, v130, v139
	v_add_f32_e32 v131, v132, v131
	v_add_f32_e32 v130, v131, v130
	v_add_f32_e32 v131, v178, v179
	v_add_f32_e32 v132, v176, v177
	v_add_f32_e32 v131, v132, v131
	v_add_f32_e32 v130, v131, v130
	ds_bpermute_b32 v131, v165, v130
	s_waitcnt lgkmcnt(0)
	v_add_f32_e32 v130, v130, v131
	ds_bpermute_b32 v131, v164, v130
	s_and_saveexec_b64 s[58:59], s[38:39]
	s_cbranch_execz .LBB0_412
	s_waitcnt lgkmcnt(0)
	v_add_f32_e32 v132, v130, v131
	v_or_b32_e32 v130, 2, v160
	v_ashrrev_i32_e32 v131, 31, v130
	v_lshlrev_b64 v[130:131], 5, v[130:131]
	v_lshl_add_u64 v[130:131], s[34:35], 0, v[130:131]
	v_lshl_add_u64 v[130:131], s[56:57], 2, v[130:131]
	s_lshl_b32 s20, s75, 2
	v_lshl_add_u64 v[130:131], v[130:131], 0, s[20:21]
	global_store_dword v[130:131], v132, off
;     __device__ __forceinline__ void operator()(f32x4 (&acc)[2][2][4][2], const Unit& u, int wr, int wc, int fr, int fq) const {
;     ...
;                     float sq = 0.f;
; #pragma unroll
;                     for (int bj = 0; bj < 2; ++bj)
; #pragma unroll
;                         for (int n = 0; n < 2; ++n) { f32x4 v = acc[ai][bj][m][n]; v = (f32x4){gelu_t(v.x), gelu_t(v.y), gelu_t(v.z), gelu_t(v.w)}; acc[ai][bj][m][n] = v;
;                             sq += (v.x * v.x + v.y * v.y) + (v.z * v.z + v.w * v.w); }
;                     sq += __shfl_xor(sq, 16); sq += __shfl_xor(sq, 32);
;                     if (fq == 0) ssg[(size_t)(t0 + 4 * ai + m) * 8 + 4 * (pn - 5) + wc] = sq;
.LBB0_412:
	s_or_b64 exec, exec, s[58:59]
	v_add_f32_e32 v130, v168, v169
	v_fmamk_f32 v130, v130, 0x3a800000, v218
	v_rsq_f32_e32 v130, v130
	s_waitcnt lgkmcnt(0)
	v_pk_mul_f32 v[170:171], v[110:111], v[130:131] op_sel_hi:[1,0]
	v_pk_mul_f32 v[110:111], v[102:103], v[130:131] op_sel_hi:[1,0]
	v_mul_f32_e32 v102, 0xbdd2d3e7, v170
	v_mul_f32_e32 v103, 0xbdd2d3e7, v171
	v_fmaak_f32 v102, v170, v102, 0xc0135761
	v_fmaak_f32 v103, v171, v103, 0xc0135761
	v_mul_f32_e32 v102, v170, v102
	v_mul_f32_e32 v103, v171, v103
	v_exp_f32_e32 v102, v102
	v_exp_f32_e32 v103, v103
	v_mul_f32_e32 v139, 0xbdd2d3e7, v110
	v_fmaak_f32 v139, v110, v139, 0xc0135761
	v_mul_f32_e32 v139, v110, v139
	v_add_f32_e32 v102, 1.0, v102
	v_add_f32_e32 v103, 1.0, v103
	v_exp_f32_e32 v139, v139
	v_rcp_f32_e32 v102, v102
	v_rcp_f32_e32 v103, v103
	v_pk_mul_f32 v[168:169], v[112:113], v[130:131] op_sel_hi:[1,0]
	v_add_f32_e32 v139, 1.0, v139
	v_pk_mul_f32 v[112:113], v[104:105], v[130:131] op_sel_hi:[1,0]
	v_pk_mul_f32 v[102:103], v[170:171], v[102:103]
	v_rcp_f32_e32 v170, v139
	v_mul_f32_e32 v139, 0xbdd2d3e7, v111
	v_fmaak_f32 v139, v111, v139, 0xc0135761
	v_mul_f32_e32 v139, v111, v139
	v_exp_f32_e32 v139, v139
	v_pk_mul_f32 v[140:141], v[114:115], v[130:131] op_sel_hi:[1,0]
	v_pk_mul_f32 v[114:115], v[98:99], v[130:131] op_sel_hi:[1,0]
	v_pk_mul_f32 v[132:133], v[116:117], v[130:131] op_sel_hi:[1,0]
	v_add_f32_e32 v139, 1.0, v139
	v_rcp_f32_e32 v171, v139
	v_mul_f32_e32 v139, 0xbdd2d3e7, v112
	v_fmaak_f32 v139, v112, v139, 0xc0135761
	v_mul_f32_e32 v139, v112, v139
	v_exp_f32_e32 v139, v139
	v_pk_mul_f32 v[110:111], v[110:111], v[170:171]
	v_pk_mul_f32 v[116:117], v[100:101], v[130:131] op_sel_hi:[1,0]
	v_mul_f32_e32 v98, 0xbdd2d3e7, v140
	v_add_f32_e32 v139, 1.0, v139
	v_rcp_f32_e32 v170, v139
	v_mul_f32_e32 v139, 0xbdd2d3e7, v113
	v_fmaak_f32 v139, v113, v139, 0xc0135761
	v_mul_f32_e32 v139, v113, v139
	v_exp_f32_e32 v139, v139
	v_mul_f32_e32 v99, 0xbdd2d3e7, v141
	v_mul_f32_e32 v100, 0xbdd2d3e7, v132
	v_mul_f32_e32 v101, 0xbdd2d3e7, v133
	v_add_f32_e32 v139, 1.0, v139
	v_rcp_f32_e32 v171, v139
	v_mul_f32_e32 v139, 0xbdd2d3e7, v114
	v_fmaak_f32 v139, v114, v139, 0xc0135761
	v_mul_f32_e32 v139, v114, v139
	v_exp_f32_e32 v139, v139
	v_mul_f32_e32 v104, 0xbdd2d3e7, v168
	v_mul_f32_e32 v105, 0xbdd2d3e7, v169
	v_fmaak_f32 v98, v140, v98, 0xc0135761
	v_add_f32_e32 v139, 1.0, v139
	v_rcp_f32_e32 v174, v139
	v_mul_f32_e32 v139, 0xbdd2d3e7, v115
	v_fmaak_f32 v139, v115, v139, 0xc0135761
	v_mul_f32_e32 v139, v115, v139
	v_exp_f32_e32 v139, v139
	v_fmaak_f32 v99, v141, v99, 0xc0135761
	v_fmaak_f32 v100, v132, v100, 0xc0135761
	v_fmaak_f32 v101, v133, v101, 0xc0135761
	v_add_f32_e32 v139, 1.0, v139
	v_rcp_f32_e32 v175, v139
	v_mul_f32_e32 v139, 0xbdd2d3e7, v116
	v_fmaak_f32 v139, v116, v139, 0xc0135761
	v_mul_f32_e32 v139, v116, v139
	v_exp_f32_e32 v139, v139
	v_fmaak_f32 v104, v168, v104, 0xc0135761
	v_fmaak_f32 v105, v169, v105, 0xc0135761
	v_mul_f32_e32 v98, v140, v98
	v_mul_f32_e32 v99, v141, v99
	v_mul_f32_e32 v100, v132, v100
	v_mul_f32_e32 v101, v133, v101
	v_mul_f32_e32 v104, v168, v104
	v_mul_f32_e32 v105, v169, v105
	v_add_f32_e32 v139, 1.0, v139
	v_pk_mul_f32 v[114:115], v[114:115], v[174:175]
	v_rcp_f32_e32 v174, v139
	v_mul_f32_e32 v139, 0xbdd2d3e7, v117
	v_exp_f32_e32 v98, v98
	v_exp_f32_e32 v99, v99
	v_exp_f32_e32 v100, v100
	v_exp_f32_e32 v101, v101
	v_exp_f32_e32 v104, v104
	v_exp_f32_e32 v105, v105
	v_fmaak_f32 v139, v117, v139, 0xc0135761
	v_mul_f32_e32 v139, v117, v139
	v_exp_f32_e32 v139, v139
	v_add_f32_e32 v98, 1.0, v98
	v_add_f32_e32 v99, 1.0, v99
	v_add_f32_e32 v100, 1.0, v100
	v_add_f32_e32 v101, 1.0, v101
	v_add_f32_e32 v104, 1.0, v104
	v_add_f32_e32 v105, 1.0, v105
	v_rcp_f32_e32 v98, v98
	v_rcp_f32_e32 v99, v99
	v_rcp_f32_e32 v100, v100
	v_rcp_f32_e32 v101, v101
	v_rcp_f32_e32 v104, v104
	v_rcp_f32_e32 v105, v105
	v_add_f32_e32 v139, 1.0, v139
	v_rcp_f32_e32 v175, v139
	v_pk_mul_f32 v[98:99], v[140:141], v[98:99]
	v_pk_mul_f32 v[100:101], v[132:133], v[100:101]
	v_pk_mul_f32 v[104:105], v[168:169], v[104:105]
	v_pk_mul_f32 v[130:131], v[98:99], v[98:99]
	v_pk_mul_f32 v[132:133], v[100:101], v[100:101]
	v_pk_mul_f32 v[140:141], v[102:103], v[102:103]
	v_pk_mul_f32 v[168:169], v[104:105], v[104:105]
	v_pk_mul_f32 v[112:113], v[112:113], v[170:171]
	v_pk_mul_f32 v[170:171], v[110:111], v[110:111]
	v_pk_mul_f32 v[172:173], v[112:113], v[112:113]
	v_add_f32_e32 v139, v168, v169
	v_add_f32_e32 v140, v140, v141
	v_add_f32_e32 v132, v132, v133
	v_add_f32_e32 v130, v130, v131
	v_pk_mul_f32 v[116:117], v[116:117], v[174:175]
	v_add_f32_e32 v139, v140, v139
	v_add_f32_e32 v130, v130, v132
	v_add_f32_e32 v131, v172, v173
	v_add_f32_e32 v132, v170, v171
	v_pk_mul_f32 v[174:175], v[114:115], v[114:115]
	v_pk_mul_f32 v[176:177], v[116:117], v[116:117]
	v_add_f32_e32 v130, v130, v139
	v_add_f32_e32 v131, v132, v131
	v_add_f32_e32 v130, v131, v130
	v_add_f32_e32 v131, v176, v177
	v_add_f32_e32 v132, v174, v175
	v_add_f32_e32 v131, v132, v131
	v_add_f32_e32 v130, v131, v130
	ds_bpermute_b32 v131, v165, v130
	s_waitcnt lgkmcnt(0)
	v_add_f32_e32 v130, v130, v131
	ds_bpermute_b32 v131, v164, v130
	s_and_saveexec_b64 s[58:59], s[38:39]
	s_cbranch_execz .LBB0_414
	s_waitcnt lgkmcnt(0)
	v_add_f32_e32 v132, v130, v131
	v_or_b32_e32 v130, 3, v160
	v_ashrrev_i32_e32 v131, 31, v130
	v_lshlrev_b64 v[130:131], 5, v[130:131]
	v_lshl_add_u64 v[130:131], s[34:35], 0, v[130:131]
	v_lshl_add_u64 v[130:131], s[56:57], 2, v[130:131]
	s_lshl_b32 s20, s75, 2
	v_lshl_add_u64 v[130:131], v[130:131], 0, s[20:21]
	global_store_dword v[130:131], v132, off
;     __device__ __forceinline__ void operator()(f32x4 (&acc)[2][2][4][2], const Unit& u, int wr, int wc, int fr, int fq) const {
;     ...
;                     float sq = 0.f;
; #pragma unroll
;                     for (int bj = 0; bj < 2; ++bj)
; #pragma unroll
;                         for (int n = 0; n < 2; ++n) { f32x4 v = acc[ai][bj][m][n]; v = (f32x4){gelu_t(v.x), gelu_t(v.y), gelu_t(v.z), gelu_t(v.w)}; acc[ai][bj][m][n] = v;
;                             sq += (v.x * v.x + v.y * v.y) + (v.z * v.z + v.w * v.w); }
;                     sq += __shfl_xor(sq, 16); sq += __shfl_xor(sq, 32);
;                     if (fq == 0) ssg[(size_t)(t0 + 4 * ai + m) * 8 + 4 * (pn - 5) + wc] = sq;
.LBB0_414:
	s_or_b64 exec, exec, s[58:59]
	v_add_f32_e32 v130, v166, v167
	v_fmamk_f32 v130, v130, 0x3a800000, v218
	v_rsq_f32_e32 v130, v130
	s_waitcnt lgkmcnt(0)
	v_pk_mul_f32 v[168:169], v[74:75], v[130:131] op_sel_hi:[1,0]
	v_pk_mul_f32 v[74:75], v[70:71], v[130:131] op_sel_hi:[1,0]
	v_mul_f32_e32 v70, 0xbdd2d3e7, v168
	v_mul_f32_e32 v71, 0xbdd2d3e7, v169
	v_fmaak_f32 v70, v168, v70, 0xc0135761
	v_fmaak_f32 v71, v169, v71, 0xc0135761
	v_mul_f32_e32 v70, v168, v70
	v_mul_f32_e32 v71, v169, v71
	v_exp_f32_e32 v70, v70
	v_exp_f32_e32 v71, v71
	v_mul_f32_e32 v139, 0xbdd2d3e7, v74
	v_fmaak_f32 v139, v74, v139, 0xc0135761
	v_mul_f32_e32 v139, v74, v139
	v_add_f32_e32 v70, 1.0, v70
	v_add_f32_e32 v71, 1.0, v71
	v_exp_f32_e32 v139, v139
	v_rcp_f32_e32 v70, v70
	v_rcp_f32_e32 v71, v71
	v_pk_mul_f32 v[166:167], v[76:77], v[130:131] op_sel_hi:[1,0]
	v_add_f32_e32 v139, 1.0, v139
	v_pk_mul_f32 v[76:77], v[72:73], v[130:131] op_sel_hi:[1,0]
	v_pk_mul_f32 v[70:71], v[168:169], v[70:71]
	v_rcp_f32_e32 v168, v139
	v_mul_f32_e32 v139, 0xbdd2d3e7, v75
	v_fmaak_f32 v139, v75, v139, 0xc0135761
	v_mul_f32_e32 v139, v75, v139
	v_exp_f32_e32 v139, v139
	v_pk_mul_f32 v[140:141], v[78:79], v[130:131] op_sel_hi:[1,0]
	v_pk_mul_f32 v[78:79], v[66:67], v[130:131] op_sel_hi:[1,0]
	v_pk_mul_f32 v[132:133], v[80:81], v[130:131] op_sel_hi:[1,0]
	v_add_f32_e32 v139, 1.0, v139
	v_rcp_f32_e32 v169, v139
	v_mul_f32_e32 v139, 0xbdd2d3e7, v76
	v_fmaak_f32 v139, v76, v139, 0xc0135761
	v_mul_f32_e32 v139, v76, v139
	v_exp_f32_e32 v139, v139
	v_pk_mul_f32 v[74:75], v[74:75], v[168:169]
	v_pk_mul_f32 v[80:81], v[68:69], v[130:131] op_sel_hi:[1,0]
	v_mul_f32_e32 v66, 0xbdd2d3e7, v140
	v_add_f32_e32 v139, 1.0, v139
	v_rcp_f32_e32 v168, v139
	v_mul_f32_e32 v139, 0xbdd2d3e7, v77
	v_fmaak_f32 v139, v77, v139, 0xc0135761
	v_mul_f32_e32 v139, v77, v139
	v_exp_f32_e32 v139, v139
	v_mul_f32_e32 v67, 0xbdd2d3e7, v141
	v_mul_f32_e32 v68, 0xbdd2d3e7, v132
	v_mul_f32_e32 v69, 0xbdd2d3e7, v133
	v_add_f32_e32 v139, 1.0, v139
	v_rcp_f32_e32 v169, v139
	v_mul_f32_e32 v139, 0xbdd2d3e7, v78
	v_fmaak_f32 v139, v78, v139, 0xc0135761
	v_mul_f32_e32 v139, v78, v139
	v_exp_f32_e32 v139, v139
	v_mul_f32_e32 v72, 0xbdd2d3e7, v166
	v_mul_f32_e32 v73, 0xbdd2d3e7, v167
	v_fmaak_f32 v66, v140, v66, 0xc0135761
	v_add_f32_e32 v139, 1.0, v139
	v_rcp_f32_e32 v172, v139
	v_mul_f32_e32 v139, 0xbdd2d3e7, v79
	v_fmaak_f32 v139, v79, v139, 0xc0135761
	v_mul_f32_e32 v139, v79, v139
	v_exp_f32_e32 v139, v139
	v_fmaak_f32 v67, v141, v67, 0xc0135761
	v_fmaak_f32 v68, v132, v68, 0xc0135761
	v_fmaak_f32 v69, v133, v69, 0xc0135761
	v_add_f32_e32 v139, 1.0, v139
	v_rcp_f32_e32 v173, v139
	v_mul_f32_e32 v139, 0xbdd2d3e7, v80
	v_fmaak_f32 v139, v80, v139, 0xc0135761
	v_mul_f32_e32 v139, v80, v139
	v_exp_f32_e32 v139, v139
	v_fmaak_f32 v72, v166, v72, 0xc0135761
	v_fmaak_f32 v73, v167, v73, 0xc0135761
	v_mul_f32_e32 v66, v140, v66
	v_mul_f32_e32 v67, v141, v67
	v_mul_f32_e32 v68, v132, v68
	v_mul_f32_e32 v69, v133, v69
	v_mul_f32_e32 v72, v166, v72
	v_mul_f32_e32 v73, v167, v73
	v_add_f32_e32 v139, 1.0, v139
	v_pk_mul_f32 v[78:79], v[78:79], v[172:173]
	v_rcp_f32_e32 v172, v139
	v_mul_f32_e32 v139, 0xbdd2d3e7, v81
	v_exp_f32_e32 v66, v66
	v_exp_f32_e32 v67, v67
	v_exp_f32_e32 v68, v68
	v_exp_f32_e32 v69, v69
	v_exp_f32_e32 v72, v72
	v_exp_f32_e32 v73, v73
	v_fmaak_f32 v139, v81, v139, 0xc0135761
	v_mul_f32_e32 v139, v81, v139
	v_exp_f32_e32 v139, v139
	v_add_f32_e32 v66, 1.0, v66
	v_add_f32_e32 v67, 1.0, v67
	v_add_f32_e32 v68, 1.0, v68
	v_add_f32_e32 v69, 1.0, v69
	v_add_f32_e32 v72, 1.0, v72
	v_add_f32_e32 v73, 1.0, v73
	v_rcp_f32_e32 v66, v66
	v_rcp_f32_e32 v67, v67
	v_rcp_f32_e32 v68, v68
	v_rcp_f32_e32 v69, v69
	v_rcp_f32_e32 v72, v72
	v_rcp_f32_e32 v73, v73
	v_add_f32_e32 v139, 1.0, v139
	v_rcp_f32_e32 v173, v139
	v_pk_mul_f32 v[66:67], v[140:141], v[66:67]
	v_pk_mul_f32 v[68:69], v[132:133], v[68:69]
	v_pk_mul_f32 v[72:73], v[166:167], v[72:73]
	v_pk_mul_f32 v[130:131], v[66:67], v[66:67]
	v_pk_mul_f32 v[132:133], v[68:69], v[68:69]
	v_pk_mul_f32 v[140:141], v[70:71], v[70:71]
	v_pk_mul_f32 v[166:167], v[72:73], v[72:73]
	v_pk_mul_f32 v[76:77], v[76:77], v[168:169]
	v_pk_mul_f32 v[168:169], v[74:75], v[74:75]
	v_pk_mul_f32 v[170:171], v[76:77], v[76:77]
	v_add_f32_e32 v139, v166, v167
	v_add_f32_e32 v140, v140, v141
	v_add_f32_e32 v132, v132, v133
	v_add_f32_e32 v130, v130, v131
	v_pk_mul_f32 v[80:81], v[80:81], v[172:173]
	v_add_f32_e32 v139, v140, v139
	v_add_f32_e32 v130, v130, v132
	v_add_f32_e32 v131, v170, v171
	v_add_f32_e32 v132, v168, v169
	v_pk_mul_f32 v[172:173], v[78:79], v[78:79]
	v_pk_mul_f32 v[174:175], v[80:81], v[80:81]
	v_add_f32_e32 v130, v130, v139
	v_add_f32_e32 v131, v132, v131
	v_add_f32_e32 v130, v131, v130
	v_add_f32_e32 v131, v174, v175
	v_add_f32_e32 v132, v172, v173
	v_add_f32_e32 v131, v132, v131
	v_add_f32_e32 v130, v131, v130
	ds_bpermute_b32 v131, v165, v130
	s_waitcnt lgkmcnt(0)
	v_add_f32_e32 v130, v130, v131
	ds_bpermute_b32 v131, v164, v130
	s_and_saveexec_b64 s[58:59], s[38:39]
	s_cbranch_execz .LBB0_416
	v_or_b32_e32 v132, 4, v160
	v_ashrrev_i32_e32 v133, 31, v132
	s_waitcnt lgkmcnt(0)
	v_add_f32_e32 v139, v130, v131
	v_lshlrev_b64 v[130:131], 5, v[132:133]
	v_lshl_add_u64 v[130:131], s[34:35], 0, v[130:131]
	v_lshl_add_u64 v[130:131], s[56:57], 2, v[130:131]
	s_lshl_b32 s20, s75, 2
	v_lshl_add_u64 v[130:131], v[130:131], 0, s[20:21]
	global_store_dword v[130:131], v139, off
;     __device__ __forceinline__ void operator()(f32x4 (&acc)[2][2][4][2], const Unit& u, int wr, int wc, int fr, int fq) const {
;     ...
;                     float sq = 0.f;
; #pragma unroll
;                     for (int bj = 0; bj < 2; ++bj)
; #pragma unroll
;                         for (int n = 0; n < 2; ++n) { f32x4 v = acc[ai][bj][m][n]; v = (f32x4){gelu_t(v.x), gelu_t(v.y), gelu_t(v.z), gelu_t(v.w)}; acc[ai][bj][m][n] = v;
;                             sq += (v.x * v.x + v.y * v.y) + (v.z * v.z + v.w * v.w); }
;                     sq += __shfl_xor(sq, 16); sq += __shfl_xor(sq, 32);
;                     if (fq == 0) ssg[(size_t)(t0 + 4 * ai + m) * 8 + 4 * (pn - 5) + wc] = sq;
.LBB0_416:
	s_or_b64 exec, exec, s[58:59]
	v_add_f32_e32 v130, v135, v136
	v_fmamk_f32 v130, v130, 0x3a800000, v218
	v_rsq_f32_e32 v130, v130
	s_waitcnt lgkmcnt(0)
	v_pk_mul_f32 v[168:169], v[42:43], v[130:131] op_sel_hi:[1,0]
	v_pk_mul_f32 v[42:43], v[38:39], v[130:131] op_sel_hi:[1,0]
	v_mul_f32_e32 v38, 0xbdd2d3e7, v168
	v_mul_f32_e32 v39, 0xbdd2d3e7, v169
	v_fmaak_f32 v38, v168, v38, 0xc0135761
	v_fmaak_f32 v39, v169, v39, 0xc0135761
	v_mul_f32_e32 v38, v168, v38
	v_mul_f32_e32 v39, v169, v39
	v_exp_f32_e32 v38, v38
	v_exp_f32_e32 v39, v39
	v_mul_f32_e32 v135, 0xbdd2d3e7, v42
	v_fmaak_f32 v135, v42, v135, 0xc0135761
	v_mul_f32_e32 v135, v42, v135
	v_add_f32_e32 v38, 1.0, v38
	v_add_f32_e32 v39, 1.0, v39
	v_exp_f32_e32 v135, v135
	v_rcp_f32_e32 v38, v38
	v_rcp_f32_e32 v39, v39
	v_pk_mul_f32 v[166:167], v[44:45], v[130:131] op_sel_hi:[1,0]
	v_add_f32_e32 v135, 1.0, v135
	v_pk_mul_f32 v[44:45], v[40:41], v[130:131] op_sel_hi:[1,0]
	v_pk_mul_f32 v[38:39], v[168:169], v[38:39]
	v_rcp_f32_e32 v168, v135
	v_mul_f32_e32 v135, 0xbdd2d3e7, v43
	v_fmaak_f32 v135, v43, v135, 0xc0135761
	v_mul_f32_e32 v135, v43, v135
	v_exp_f32_e32 v135, v135
	v_pk_mul_f32 v[140:141], v[46:47], v[130:131] op_sel_hi:[1,0]
	v_pk_mul_f32 v[46:47], v[34:35], v[130:131] op_sel_hi:[1,0]
	v_pk_mul_f32 v[132:133], v[48:49], v[130:131] op_sel_hi:[1,0]
	v_add_f32_e32 v135, 1.0, v135
	v_rcp_f32_e32 v169, v135
	v_mul_f32_e32 v135, 0xbdd2d3e7, v44
	v_fmaak_f32 v135, v44, v135, 0xc0135761
	v_mul_f32_e32 v135, v44, v135
	v_exp_f32_e32 v135, v135
	v_pk_mul_f32 v[42:43], v[42:43], v[168:169]
	v_pk_mul_f32 v[48:49], v[36:37], v[130:131] op_sel_hi:[1,0]
	v_mul_f32_e32 v34, 0xbdd2d3e7, v140
	v_add_f32_e32 v135, 1.0, v135
	v_rcp_f32_e32 v168, v135
	v_mul_f32_e32 v135, 0xbdd2d3e7, v45
	v_fmaak_f32 v135, v45, v135, 0xc0135761
	v_mul_f32_e32 v135, v45, v135
	v_exp_f32_e32 v135, v135
	v_mul_f32_e32 v35, 0xbdd2d3e7, v141
	v_mul_f32_e32 v36, 0xbdd2d3e7, v132
	v_mul_f32_e32 v37, 0xbdd2d3e7, v133
	v_add_f32_e32 v135, 1.0, v135
	v_rcp_f32_e32 v169, v135
	v_mul_f32_e32 v135, 0xbdd2d3e7, v46
	v_fmaak_f32 v135, v46, v135, 0xc0135761
	v_mul_f32_e32 v135, v46, v135
	v_exp_f32_e32 v135, v135
	v_mul_f32_e32 v40, 0xbdd2d3e7, v166
	v_mul_f32_e32 v41, 0xbdd2d3e7, v167
	v_fmaak_f32 v34, v140, v34, 0xc0135761
	v_add_f32_e32 v135, 1.0, v135
	v_rcp_f32_e32 v172, v135
	v_mul_f32_e32 v135, 0xbdd2d3e7, v47
	v_fmaak_f32 v135, v47, v135, 0xc0135761
	v_mul_f32_e32 v135, v47, v135
	v_exp_f32_e32 v135, v135
	v_fmaak_f32 v35, v141, v35, 0xc0135761
	v_fmaak_f32 v36, v132, v36, 0xc0135761
	v_fmaak_f32 v37, v133, v37, 0xc0135761
	v_add_f32_e32 v135, 1.0, v135
	v_rcp_f32_e32 v173, v135
	v_mul_f32_e32 v135, 0xbdd2d3e7, v48
	v_fmaak_f32 v135, v48, v135, 0xc0135761
	v_mul_f32_e32 v135, v48, v135
	v_exp_f32_e32 v135, v135
	v_fmaak_f32 v40, v166, v40, 0xc0135761
	v_fmaak_f32 v41, v167, v41, 0xc0135761
	v_mul_f32_e32 v34, v140, v34
	v_mul_f32_e32 v35, v141, v35
	v_mul_f32_e32 v36, v132, v36
	v_mul_f32_e32 v37, v133, v37
	v_mul_f32_e32 v40, v166, v40
	v_mul_f32_e32 v41, v167, v41
	v_add_f32_e32 v135, 1.0, v135
	v_pk_mul_f32 v[46:47], v[46:47], v[172:173]
	v_rcp_f32_e32 v172, v135
	v_mul_f32_e32 v135, 0xbdd2d3e7, v49
	v_exp_f32_e32 v34, v34
	v_exp_f32_e32 v35, v35
	v_exp_f32_e32 v36, v36
	v_exp_f32_e32 v37, v37
	v_exp_f32_e32 v40, v40
	v_exp_f32_e32 v41, v41
	v_fmaak_f32 v135, v49, v135, 0xc0135761
	v_mul_f32_e32 v135, v49, v135
	v_exp_f32_e32 v135, v135
	v_add_f32_e32 v34, 1.0, v34
	v_add_f32_e32 v35, 1.0, v35
	v_add_f32_e32 v36, 1.0, v36
	v_add_f32_e32 v37, 1.0, v37
	v_add_f32_e32 v40, 1.0, v40
	v_add_f32_e32 v41, 1.0, v41
	v_rcp_f32_e32 v34, v34
	v_rcp_f32_e32 v35, v35
	v_rcp_f32_e32 v36, v36
	v_rcp_f32_e32 v37, v37
	v_rcp_f32_e32 v40, v40
	v_rcp_f32_e32 v41, v41
	v_add_f32_e32 v135, 1.0, v135
	v_rcp_f32_e32 v173, v135
	v_pk_mul_f32 v[34:35], v[140:141], v[34:35]
	v_pk_mul_f32 v[36:37], v[132:133], v[36:37]
	v_pk_mul_f32 v[40:41], v[166:167], v[40:41]
	v_pk_mul_f32 v[130:131], v[34:35], v[34:35]
	v_pk_mul_f32 v[132:133], v[36:37], v[36:37]
	v_pk_mul_f32 v[140:141], v[38:39], v[38:39]
	v_pk_mul_f32 v[166:167], v[40:41], v[40:41]
	v_pk_mul_f32 v[44:45], v[44:45], v[168:169]
	v_pk_mul_f32 v[168:169], v[42:43], v[42:43]
	v_pk_mul_f32 v[170:171], v[44:45], v[44:45]
	v_add_f32_e32 v135, v166, v167
	v_add_f32_e32 v136, v140, v141
	v_add_f32_e32 v132, v132, v133
	v_add_f32_e32 v130, v130, v131
	v_pk_mul_f32 v[48:49], v[48:49], v[172:173]
	v_add_f32_e32 v135, v136, v135
	v_add_f32_e32 v130, v130, v132
	v_add_f32_e32 v131, v170, v171
	v_add_f32_e32 v132, v168, v169
	v_pk_mul_f32 v[172:173], v[46:47], v[46:47]
	v_pk_mul_f32 v[174:175], v[48:49], v[48:49]
	v_add_f32_e32 v130, v130, v135
	v_add_f32_e32 v131, v132, v131
	v_add_f32_e32 v130, v131, v130
	v_add_f32_e32 v131, v174, v175
	v_add_f32_e32 v132, v172, v173
	v_add_f32_e32 v131, v132, v131
	v_add_f32_e32 v130, v131, v130
	ds_bpermute_b32 v131, v165, v130
	s_waitcnt lgkmcnt(0)
	v_add_f32_e32 v130, v130, v131
	ds_bpermute_b32 v131, v164, v130
	s_and_saveexec_b64 s[58:59], s[38:39]
	s_cbranch_execz .LBB0_418
	s_waitcnt lgkmcnt(0)
	v_add_f32_e32 v132, v130, v131
	v_or_b32_e32 v130, 5, v160
	v_ashrrev_i32_e32 v131, 31, v130
	v_lshlrev_b64 v[130:131], 5, v[130:131]
	v_lshl_add_u64 v[130:131], s[34:35], 0, v[130:131]
	v_lshl_add_u64 v[130:131], s[56:57], 2, v[130:131]
	s_lshl_b32 s20, s75, 2
	v_lshl_add_u64 v[130:131], v[130:131], 0, s[20:21]
	global_store_dword v[130:131], v132, off
;     __device__ __forceinline__ void operator()(f32x4 (&acc)[2][2][4][2], const Unit& u, int wr, int wc, int fr, int fq) const {
;     ...
;                     float sq = 0.f;
; #pragma unroll
;                     for (int bj = 0; bj < 2; ++bj)
; #pragma unroll
;                         for (int n = 0; n < 2; ++n) { f32x4 v = acc[ai][bj][m][n]; v = (f32x4){gelu_t(v.x), gelu_t(v.y), gelu_t(v.z), gelu_t(v.w)}; acc[ai][bj][m][n] = v;
;                             sq += (v.x * v.x + v.y * v.y) + (v.z * v.z + v.w * v.w); }
;                     sq += __shfl_xor(sq, 16); sq += __shfl_xor(sq, 32);
;                     if (fq == 0) ssg[(size_t)(t0 + 4 * ai + m) * 8 + 4 * (pn - 5) + wc] = sq;
.LBB0_418:
	s_or_b64 exec, exec, s[58:59]
	v_add_f32_e32 v130, v137, v138
	v_fmamk_f32 v130, v130, 0x3a800000, v218
	v_rsq_f32_e32 v130, v130
	s_waitcnt lgkmcnt(0)
	v_pk_mul_f32 v[140:141], v[26:27], v[130:131] op_sel_hi:[1,0]
	v_pk_mul_f32 v[26:27], v[22:23], v[130:131] op_sel_hi:[1,0]
	v_mul_f32_e32 v22, 0xbdd2d3e7, v140
	v_mul_f32_e32 v23, 0xbdd2d3e7, v141
	v_fmaak_f32 v22, v140, v22, 0xc0135761
	v_fmaak_f32 v23, v141, v23, 0xc0135761
	v_mul_f32_e32 v22, v140, v22
	v_mul_f32_e32 v23, v141, v23
	v_exp_f32_e32 v22, v22
	v_exp_f32_e32 v23, v23
	v_mul_f32_e32 v135, 0xbdd2d3e7, v26
	v_fmaak_f32 v135, v26, v135, 0xc0135761
	v_mul_f32_e32 v135, v26, v135
	v_add_f32_e32 v22, 1.0, v22
	v_add_f32_e32 v23, 1.0, v23
	v_exp_f32_e32 v135, v135
	v_rcp_f32_e32 v22, v22
	v_rcp_f32_e32 v23, v23
	v_pk_mul_f32 v[138:139], v[28:29], v[130:131] op_sel_hi:[1,0]
	v_add_f32_e32 v135, 1.0, v135
	v_pk_mul_f32 v[28:29], v[24:25], v[130:131] op_sel_hi:[1,0]
	v_pk_mul_f32 v[22:23], v[140:141], v[22:23]
	v_rcp_f32_e32 v140, v135
	v_mul_f32_e32 v135, 0xbdd2d3e7, v27
	v_fmaak_f32 v135, v27, v135, 0xc0135761
	v_mul_f32_e32 v135, v27, v135
	v_exp_f32_e32 v135, v135
	v_pk_mul_f32 v[136:137], v[30:31], v[130:131] op_sel_hi:[1,0]
	v_pk_mul_f32 v[30:31], v[18:19], v[130:131] op_sel_hi:[1,0]
	v_pk_mul_f32 v[132:133], v[32:33], v[130:131] op_sel_hi:[1,0]
	v_add_f32_e32 v135, 1.0, v135
	v_rcp_f32_e32 v141, v135
	v_mul_f32_e32 v135, 0xbdd2d3e7, v28
	v_fmaak_f32 v135, v28, v135, 0xc0135761
	v_mul_f32_e32 v135, v28, v135
	v_exp_f32_e32 v135, v135
	v_pk_mul_f32 v[26:27], v[26:27], v[140:141]
	v_pk_mul_f32 v[32:33], v[20:21], v[130:131] op_sel_hi:[1,0]
	v_mul_f32_e32 v18, 0xbdd2d3e7, v136
	v_add_f32_e32 v135, 1.0, v135
	v_rcp_f32_e32 v140, v135
	v_mul_f32_e32 v135, 0xbdd2d3e7, v29
	v_fmaak_f32 v135, v29, v135, 0xc0135761
	v_mul_f32_e32 v135, v29, v135
	v_exp_f32_e32 v135, v135
	v_mul_f32_e32 v19, 0xbdd2d3e7, v137
	v_mul_f32_e32 v20, 0xbdd2d3e7, v132
	v_mul_f32_e32 v21, 0xbdd2d3e7, v133
	v_add_f32_e32 v135, 1.0, v135
	v_rcp_f32_e32 v141, v135
	v_mul_f32_e32 v135, 0xbdd2d3e7, v30
	v_fmaak_f32 v135, v30, v135, 0xc0135761
	v_mul_f32_e32 v135, v30, v135
	v_exp_f32_e32 v135, v135
	v_mul_f32_e32 v24, 0xbdd2d3e7, v138
	v_mul_f32_e32 v25, 0xbdd2d3e7, v139
	v_fmaak_f32 v18, v136, v18, 0xc0135761
	v_add_f32_e32 v135, 1.0, v135
	v_rcp_f32_e32 v168, v135
	v_mul_f32_e32 v135, 0xbdd2d3e7, v31
	v_fmaak_f32 v135, v31, v135, 0xc0135761
	v_mul_f32_e32 v135, v31, v135
	v_exp_f32_e32 v135, v135
	v_fmaak_f32 v19, v137, v19, 0xc0135761
	v_fmaak_f32 v20, v132, v20, 0xc0135761
	v_fmaak_f32 v21, v133, v21, 0xc0135761
	v_add_f32_e32 v135, 1.0, v135
	v_rcp_f32_e32 v169, v135
	v_mul_f32_e32 v135, 0xbdd2d3e7, v32
	v_fmaak_f32 v135, v32, v135, 0xc0135761
	v_mul_f32_e32 v135, v32, v135
	v_exp_f32_e32 v135, v135
	v_fmaak_f32 v24, v138, v24, 0xc0135761
	v_fmaak_f32 v25, v139, v25, 0xc0135761
	v_mul_f32_e32 v18, v136, v18
	v_mul_f32_e32 v19, v137, v19
	v_mul_f32_e32 v20, v132, v20
	v_mul_f32_e32 v21, v133, v21
	v_mul_f32_e32 v24, v138, v24
	v_mul_f32_e32 v25, v139, v25
	v_add_f32_e32 v135, 1.0, v135
	v_pk_mul_f32 v[30:31], v[30:31], v[168:169]
	v_rcp_f32_e32 v168, v135
	v_mul_f32_e32 v135, 0xbdd2d3e7, v33
	v_exp_f32_e32 v18, v18
	v_exp_f32_e32 v19, v19
	v_exp_f32_e32 v20, v20
	v_exp_f32_e32 v21, v21
	v_exp_f32_e32 v24, v24
	v_exp_f32_e32 v25, v25
	v_fmaak_f32 v135, v33, v135, 0xc0135761
	v_mul_f32_e32 v135, v33, v135
	v_exp_f32_e32 v135, v135
	v_add_f32_e32 v18, 1.0, v18
	v_add_f32_e32 v19, 1.0, v19
	v_add_f32_e32 v20, 1.0, v20
	v_add_f32_e32 v21, 1.0, v21
	v_add_f32_e32 v24, 1.0, v24
	v_add_f32_e32 v25, 1.0, v25
	v_rcp_f32_e32 v18, v18
	v_rcp_f32_e32 v19, v19
	v_rcp_f32_e32 v20, v20
	v_rcp_f32_e32 v21, v21
	v_rcp_f32_e32 v24, v24
	v_rcp_f32_e32 v25, v25
	v_add_f32_e32 v135, 1.0, v135
	v_rcp_f32_e32 v169, v135
	v_pk_mul_f32 v[18:19], v[136:137], v[18:19]
	v_pk_mul_f32 v[20:21], v[132:133], v[20:21]
	v_pk_mul_f32 v[24:25], v[138:139], v[24:25]
	v_pk_mul_f32 v[130:131], v[18:19], v[18:19]
	v_pk_mul_f32 v[132:133], v[20:21], v[20:21]
	v_pk_mul_f32 v[136:137], v[22:23], v[22:23]
	v_pk_mul_f32 v[138:139], v[24:25], v[24:25]
	v_pk_mul_f32 v[28:29], v[28:29], v[140:141]
	v_pk_mul_f32 v[140:141], v[26:27], v[26:27]
	v_pk_mul_f32 v[166:167], v[28:29], v[28:29]
	v_add_f32_e32 v135, v138, v139
	v_add_f32_e32 v136, v136, v137
	v_add_f32_e32 v132, v132, v133
	v_add_f32_e32 v130, v130, v131
	v_pk_mul_f32 v[32:33], v[32:33], v[168:169]
	v_add_f32_e32 v135, v136, v135
	v_add_f32_e32 v130, v130, v132
	v_add_f32_e32 v131, v166, v167
	v_add_f32_e32 v132, v140, v141
	v_pk_mul_f32 v[168:169], v[30:31], v[30:31]
	v_pk_mul_f32 v[170:171], v[32:33], v[32:33]
	v_add_f32_e32 v130, v130, v135
	v_add_f32_e32 v131, v132, v131
	v_add_f32_e32 v130, v131, v130
	v_add_f32_e32 v131, v170, v171
	v_add_f32_e32 v132, v168, v169
	v_add_f32_e32 v131, v132, v131
	v_add_f32_e32 v130, v131, v130
	ds_bpermute_b32 v131, v165, v130
	s_waitcnt lgkmcnt(0)
	v_add_f32_e32 v130, v130, v131
	ds_bpermute_b32 v131, v164, v130
	s_and_saveexec_b64 s[58:59], s[38:39]
	s_cbranch_execz .LBB0_420
	s_waitcnt lgkmcnt(0)
	v_add_f32_e32 v132, v130, v131
	v_or_b32_e32 v130, 6, v160
	v_ashrrev_i32_e32 v131, 31, v130
	v_lshlrev_b64 v[130:131], 5, v[130:131]
	v_lshl_add_u64 v[130:131], s[34:35], 0, v[130:131]
	v_lshl_add_u64 v[130:131], s[56:57], 2, v[130:131]
	s_lshl_b32 s20, s75, 2
	v_lshl_add_u64 v[130:131], v[130:131], 0, s[20:21]
	global_store_dword v[130:131], v132, off
;     __device__ __forceinline__ void operator()(f32x4 (&acc)[2][2][4][2], const Unit& u, int wr, int wc, int fr, int fq) const {
;     ...
;                     float sq = 0.f;
; #pragma unroll
;                     for (int bj = 0; bj < 2; ++bj)
; #pragma unroll
;                         for (int n = 0; n < 2; ++n) { f32x4 v = acc[ai][bj][m][n]; v = (f32x4){gelu_t(v.x), gelu_t(v.y), gelu_t(v.z), gelu_t(v.w)}; acc[ai][bj][m][n] = v;
;                             sq += (v.x * v.x + v.y * v.y) + (v.z * v.z + v.w * v.w); }
;                     sq += __shfl_xor(sq, 16); sq += __shfl_xor(sq, 32);
;                     if (fq == 0) ssg[(size_t)(t0 + 4 * ai + m) * 8 + 4 * (pn - 5) + wc] = sq;
.LBB0_420:
	s_or_b64 exec, exec, s[58:59]
	v_add_f32_e32 v0, v0, v134
	v_fmamk_f32 v0, v0, 0x3a800000, v218
	v_rsq_f32_e32 v0, v0
	s_nop 0
	v_pk_mul_f32 v[132:133], v[14:15], v[0:1] op_sel_hi:[1,0]
	s_waitcnt lgkmcnt(0)
	v_pk_mul_f32 v[130:131], v[16:17], v[0:1] op_sel_hi:[1,0]
	v_pk_mul_f32 v[134:135], v[12:13], v[0:1] op_sel_hi:[1,0]
	v_pk_mul_f32 v[136:137], v[10:11], v[0:1] op_sel_hi:[1,0]
	v_pk_mul_f32 v[12:13], v[8:9], v[0:1] op_sel_hi:[1,0]
	v_pk_mul_f32 v[10:11], v[6:7], v[0:1] op_sel_hi:[1,0]
	v_pk_mul_f32 v[16:17], v[4:5], v[0:1] op_sel_hi:[1,0]
	v_pk_mul_f32 v[14:15], v[2:3], v[0:1] op_sel_hi:[1,0]
	v_mul_f32_e32 v0, 0xbdd2d3e7, v132
	v_fmaak_f32 v0, v132, v0, 0xc0135761
	v_mul_f32_e32 v0, v132, v0
	v_exp_f32_e32 v0, v0
	s_nop 0
	v_add_f32_e32 v0, 1.0, v0
	v_rcp_f32_e32 v2, v0
	v_mul_f32_e32 v0, 0xbdd2d3e7, v133
	v_fmaak_f32 v0, v133, v0, 0xc0135761
	v_mul_f32_e32 v0, v133, v0
	v_exp_f32_e32 v0, v0
	s_nop 0
	v_add_f32_e32 v0, 1.0, v0
	v_rcp_f32_e32 v3, v0
	v_mul_f32_e32 v0, 0xbdd2d3e7, v130
	v_fmaak_f32 v0, v130, v0, 0xc0135761
	v_mul_f32_e32 v0, v130, v0
	v_exp_f32_e32 v0, v0
	v_pk_mul_f32 v[2:3], v[132:133], v[2:3]
	v_add_f32_e32 v0, 1.0, v0
	v_rcp_f32_e32 v4, v0
	v_mul_f32_e32 v0, 0xbdd2d3e7, v131
	v_fmaak_f32 v0, v131, v0, 0xc0135761
	v_mul_f32_e32 v0, v131, v0
	v_exp_f32_e32 v0, v0
	s_nop 0
	v_add_f32_e32 v0, 1.0, v0
	v_rcp_f32_e32 v5, v0
	v_mul_f32_e32 v0, 0xbdd2d3e7, v136
	v_fmaak_f32 v0, v136, v0, 0xc0135761
	v_mul_f32_e32 v0, v136, v0
	v_exp_f32_e32 v0, v0
	v_pk_mul_f32 v[4:5], v[130:131], v[4:5]
	v_pk_mul_f32 v[130:131], v[2:3], v[2:3]
	v_pk_mul_f32 v[132:133], v[4:5], v[4:5]
	v_add_f32_e32 v0, 1.0, v0
	v_rcp_f32_e32 v6, v0
	v_mul_f32_e32 v0, 0xbdd2d3e7, v137
	v_fmaak_f32 v0, v137, v0, 0xc0135761
	v_mul_f32_e32 v0, v137, v0
	v_exp_f32_e32 v0, v0
	v_add_f32_e32 v132, v132, v133
	v_add_f32_e32 v130, v130, v131
	v_add_f32_e32 v130, v130, v132
	v_add_f32_e32 v0, 1.0, v0
	v_rcp_f32_e32 v7, v0
	v_mul_f32_e32 v0, 0xbdd2d3e7, v134
	v_fmaak_f32 v0, v134, v0, 0xc0135761
	v_mul_f32_e32 v0, v134, v0
	v_exp_f32_e32 v0, v0
	v_pk_mul_f32 v[6:7], v[136:137], v[6:7]
	v_add_f32_e32 v0, 1.0, v0
	v_rcp_f32_e32 v8, v0
	v_mul_f32_e32 v0, 0xbdd2d3e7, v135
	v_fmaak_f32 v0, v135, v0, 0xc0135761
	v_mul_f32_e32 v0, v135, v0
	v_exp_f32_e32 v0, v0
	s_nop 0
	v_add_f32_e32 v0, 1.0, v0
	v_rcp_f32_e32 v9, v0
	v_mul_f32_e32 v0, 0xbdd2d3e7, v10
	v_fmaak_f32 v0, v10, v0, 0xc0135761
	v_mul_f32_e32 v0, v10, v0
	v_exp_f32_e32 v0, v0
	v_pk_mul_f32 v[8:9], v[134:135], v[8:9]
	v_pk_mul_f32 v[134:135], v[6:7], v[6:7]
	v_pk_mul_f32 v[136:137], v[8:9], v[8:9]
	v_add_f32_e32 v0, 1.0, v0
	v_rcp_f32_e32 v138, v0
	v_mul_f32_e32 v0, 0xbdd2d3e7, v11
	v_fmaak_f32 v0, v11, v0, 0xc0135761
	v_mul_f32_e32 v0, v11, v0
	v_exp_f32_e32 v0, v0
	v_add_f32_e32 v134, v134, v135
	v_add_f32_e32 v0, 1.0, v0
	v_rcp_f32_e32 v139, v0
	v_mul_f32_e32 v0, 0xbdd2d3e7, v12
	v_fmaak_f32 v0, v12, v0, 0xc0135761
	v_mul_f32_e32 v0, v12, v0
	v_exp_f32_e32 v0, v0
	v_pk_mul_f32 v[10:11], v[10:11], v[138:139]
	v_add_f32_e32 v0, 1.0, v0
	v_rcp_f32_e32 v138, v0
	v_mul_f32_e32 v0, 0xbdd2d3e7, v13
	v_fmaak_f32 v0, v13, v0, 0xc0135761
	v_mul_f32_e32 v0, v13, v0
	v_exp_f32_e32 v0, v0
	s_nop 0
	v_add_f32_e32 v0, 1.0, v0
	v_rcp_f32_e32 v139, v0
	v_mul_f32_e32 v0, 0xbdd2d3e7, v14
	v_fmaak_f32 v0, v14, v0, 0xc0135761
	v_mul_f32_e32 v0, v14, v0
	v_exp_f32_e32 v0, v0
	v_pk_mul_f32 v[12:13], v[12:13], v[138:139]
	v_pk_mul_f32 v[138:139], v[10:11], v[10:11]
	v_pk_mul_f32 v[140:141], v[12:13], v[12:13]
	v_add_f32_e32 v0, 1.0, v0
	v_rcp_f32_e32 v166, v0
	v_mul_f32_e32 v0, 0xbdd2d3e7, v15
	v_fmaak_f32 v0, v15, v0, 0xc0135761
	v_mul_f32_e32 v0, v15, v0
	v_exp_f32_e32 v0, v0
	v_add_f32_e32 v131, v138, v139
	v_add_f32_e32 v0, 1.0, v0
	v_rcp_f32_e32 v167, v0
	v_mul_f32_e32 v0, 0xbdd2d3e7, v16
	v_fmaak_f32 v0, v16, v0, 0xc0135761
	v_mul_f32_e32 v0, v16, v0
	v_exp_f32_e32 v0, v0
	v_pk_mul_f32 v[14:15], v[14:15], v[166:167]
	v_add_f32_e32 v0, 1.0, v0
	v_rcp_f32_e32 v166, v0
	v_mul_f32_e32 v0, 0xbdd2d3e7, v17
	v_fmaak_f32 v0, v17, v0, 0xc0135761
	v_mul_f32_e32 v0, v17, v0
	v_exp_f32_e32 v0, v0
	s_nop 0
	v_add_f32_e32 v0, 1.0, v0
	v_rcp_f32_e32 v167, v0
	v_add_f32_e32 v0, v136, v137
	v_add_f32_e32 v0, v134, v0
	v_add_f32_e32 v0, v130, v0
	v_pk_mul_f32 v[16:17], v[16:17], v[166:167]
	v_add_f32_e32 v130, v140, v141
	v_pk_mul_f32 v[166:167], v[14:15], v[14:15]
	v_pk_mul_f32 v[168:169], v[16:17], v[16:17]
	v_add_f32_e32 v130, v131, v130
	v_add_f32_e32 v0, v130, v0
	v_add_f32_e32 v130, v168, v169
	v_add_f32_e32 v131, v166, v167
	v_add_f32_e32 v130, v131, v130
	v_add_f32_e32 v0, v130, v0
	ds_bpermute_b32 v130, v165, v0
	s_waitcnt lgkmcnt(0)
	v_add_f32_e32 v0, v0, v130
	ds_bpermute_b32 v130, v164, v0
	s_and_saveexec_b64 s[58:59], s[38:39]
	s_cbranch_execz .LBB0_422
	s_waitcnt lgkmcnt(0)
	v_add_f32_e32 v0, v0, v130
	v_or_b32_e32 v130, 7, v160
	v_ashrrev_i32_e32 v131, 31, v130
	v_lshlrev_b64 v[130:131], 5, v[130:131]
	v_lshl_add_u64 v[130:131], s[34:35], 0, v[130:131]
	v_lshl_add_u64 v[130:131], s[56:57], 2, v[130:131]
	s_lshl_b32 s20, s75, 2
	v_lshl_add_u64 v[130:131], v[130:131], 0, s[20:21]
	global_store_dword v[130:131], v0, off

; __device__ __forceinline__ unsigned cvt_pk_bf16(float lo, float hi) { f32x2 v = {lo, hi}; bf16x2_t_ b = __builtin_convertvector(v, bf16x2_t_); return __builtin_bit_cast(unsigned, b); }
; __device__ __forceinline__ float gelu_t(float x) {
;     const float u = x * (0.7978845608f + 0.0356774081f * x * x);
;     const float e = __builtin_amdgcn_exp2f(u * -2.8853900818f);
;     return x * __builtin_amdgcn_rcpf(1.0f + e);
; }
;     __device__ __forceinline__ void operator()(f32x4 (&acc)[2][2][4][2], const Unit& u, int wr, int wc, int fr, int fq) const {
;     ...
;         bf16_t* dst = QU + 512 + 256 * (pn - 3) + (size_t)t0 * 1024 + 32 * wc + 8 * fq;
;         if (isu) {
; #pragma unroll
;             for (int ai = 0; ai < 2; ++ai)
; #pragma unroll
;                 for (int m = 0; m < 4; ++m)
; #pragma unroll
;                     for (int bj = 0; bj < 2; ++bj) { const f32x4 a = acc[ai][bj][m][0] * rs[4 * ai + m], b = acc[ai][bj][m][1] * rs[4 * ai + m]; u32x4 w;
;                         w.x = cvt_pk_bf16(gelu_t(a.x), gelu_t(a.y)); w.y = cvt_pk_bf16(gelu_t(a.z), gelu_t(a.w)); w.z = cvt_pk_bf16(gelu_t(b.x), gelu_t(b.y)); w.w = cvt_pk_bf16(gelu_t(b.z), gelu_t(b.w));
;                         *(u32x4*)(dst + (size_t)(4 * ai + m) * 1024 + 128 * bj) = w; }
.LBB0_445:
	s_lshl_b32 s20, s33, 8
	s_add_i32 s36, s20, 0xfffffd00
	s_ashr_i32 s37, s36, 31
	s_lshl_b64 s[36:37], s[36:37], 1
	v_readlane_b32 s20, v253, 26
	s_add_u32 s36, s20, s36
	v_readlane_b32 s20, v253, 27
	s_addc_u32 s37, s20, s37
	v_lshl_add_u64 v[138:139], v[138:139], 1, s[36:37]
	s_lshl_b32 s20, s67, 1
	v_lshl_add_u64 v[138:139], v[138:139], 0, s[20:21]
	v_pk_mul_f32 v[126:127], v[126:127], v[164:165] op_sel_hi:[1,0]
	v_lshl_add_u64 v[138:139], v[138:139], 0, v[0:1]
	v_mul_f32_e32 v0, 0xbdd2d3e7, v126
	v_fmaak_f32 v0, v126, v0, 0xc0135761
	v_mul_f32_e32 v0, v126, v0
	v_exp_f32_e32 v0, v0
	v_pk_mul_f32 v[140:141], v[124:125], v[164:165] op_sel_hi:[1,0]
	v_pk_mul_f32 v[124:125], v[122:123], v[164:165] op_sel_hi:[1,0]
	v_pk_mul_f32 v[128:129], v[128:129], v[164:165] op_sel_hi:[1,0]
	v_add_f32_e32 v0, 1.0, v0
	v_rcp_f32_e32 v122, v0
	v_mul_f32_e32 v0, 0xbdd2d3e7, v127
	v_fmaak_f32 v0, v127, v0, 0xc0135761
	v_mul_f32_e32 v0, v127, v0
	v_exp_f32_e32 v0, v0
	v_pk_mul_f32 v[118:119], v[118:119], v[164:165] op_sel_hi:[1,0]
	v_pk_mul_f32 v[120:121], v[120:121], v[164:165] op_sel_hi:[1,0]
	v_pk_mul_f32 v[110:111], v[110:111], v[162:163] op_sel_hi:[1,0]
	v_add_f32_e32 v0, 1.0, v0
	v_rcp_f32_e32 v123, v0
	v_mul_f32_e32 v0, 0xbdd2d3e7, v128
	v_fmaak_f32 v0, v128, v0, 0xc0135761
	v_mul_f32_e32 v0, v128, v0
	v_exp_f32_e32 v0, v0
	v_pk_mul_f32 v[122:123], v[126:127], v[122:123]
	v_pk_mul_f32 v[112:113], v[112:113], v[162:163] op_sel_hi:[1,0]
	v_cvt_pk_bf16_f32 v122, v122, v123
	v_add_f32_e32 v0, 1.0, v0
	v_rcp_f32_e32 v126, v0
	v_mul_f32_e32 v0, 0xbdd2d3e7, v129
	v_fmaak_f32 v0, v129, v0, 0xc0135761
	v_mul_f32_e32 v0, v129, v0
	v_exp_f32_e32 v0, v0
	v_pk_mul_f32 v[102:103], v[102:103], v[162:163] op_sel_hi:[1,0]
	v_pk_mul_f32 v[104:105], v[104:105], v[162:163] op_sel_hi:[1,0]
	v_pk_mul_f32 v[94:95], v[94:95], v[160:161] op_sel_hi:[1,0]
	v_add_f32_e32 v0, 1.0, v0
	v_rcp_f32_e32 v127, v0
	v_mul_f32_e32 v0, 0xbdd2d3e7, v124
	v_fmaak_f32 v0, v124, v0, 0xc0135761
	v_mul_f32_e32 v0, v124, v0
	v_exp_f32_e32 v0, v0
	v_pk_mul_f32 v[126:127], v[128:129], v[126:127]
	v_pk_mul_f32 v[96:97], v[96:97], v[160:161] op_sel_hi:[1,0]
	v_cvt_pk_bf16_f32 v123, v126, v127
	v_add_f32_e32 v0, 1.0, v0
	v_rcp_f32_e32 v126, v0
	v_mul_f32_e32 v0, 0xbdd2d3e7, v125
	v_fmaak_f32 v0, v125, v0, 0xc0135761
	v_mul_f32_e32 v0, v125, v0
	v_exp_f32_e32 v0, v0
	v_pk_mul_f32 v[90:91], v[90:91], v[160:161] op_sel_hi:[1,0]
	v_pk_mul_f32 v[92:93], v[92:93], v[160:161] op_sel_hi:[1,0]
	v_pk_mul_f32 v[86:87], v[86:87], v[160:161] op_sel_hi:[1,0]
	v_add_f32_e32 v0, 1.0, v0
	v_rcp_f32_e32 v127, v0
	v_mul_f32_e32 v0, 0xbdd2d3e7, v140
	v_fmaak_f32 v0, v140, v0, 0xc0135761
	v_mul_f32_e32 v0, v140, v0
	v_exp_f32_e32 v0, v0
	v_pk_mul_f32 v[124:125], v[124:125], v[126:127]
	v_pk_mul_f32 v[88:89], v[88:89], v[160:161] op_sel_hi:[1,0]
	v_cvt_pk_bf16_f32 v124, v124, v125
	v_add_f32_e32 v0, 1.0, v0
	v_rcp_f32_e32 v126, v0
	v_mul_f32_e32 v0, 0xbdd2d3e7, v141
	v_fmaak_f32 v0, v141, v0, 0xc0135761
	v_mul_f32_e32 v0, v141, v0
	v_exp_f32_e32 v0, v0
	v_pk_mul_f32 v[78:79], v[78:79], v[158:159] op_sel_hi:[1,0]
	v_pk_mul_f32 v[80:81], v[80:81], v[158:159] op_sel_hi:[1,0]
	v_pk_mul_f32 v[70:71], v[70:71], v[158:159] op_sel_hi:[1,0]
	v_add_f32_e32 v0, 1.0, v0
	v_rcp_f32_e32 v127, v0
	v_mul_f32_e32 v0, 0xbdd2d3e7, v118
	v_fmaak_f32 v0, v118, v0, 0xc0135761
	v_mul_f32_e32 v0, v118, v0
	v_exp_f32_e32 v0, v0
	v_pk_mul_f32 v[126:127], v[140:141], v[126:127]
	v_pk_mul_f32 v[72:73], v[72:73], v[158:159] op_sel_hi:[1,0]
	v_cvt_pk_bf16_f32 v125, v126, v127
	v_add_f32_e32 v0, 1.0, v0
	global_store_dwordx4 v[138:139], v[122:125], off
	v_pk_mul_f32 v[62:63], v[62:63], v[136:137] op_sel_hi:[1,0]
	v_pk_mul_f32 v[64:65], v[64:65], v[136:137] op_sel_hi:[1,0]
	v_pk_mul_f32 v[122:123], v[116:117], v[164:165] op_sel_hi:[1,0]
	v_pk_mul_f32 v[116:117], v[114:115], v[164:165] op_sel_hi:[1,0]
	v_rcp_f32_e32 v114, v0
	v_mul_f32_e32 v0, 0xbdd2d3e7, v119
	v_fmaak_f32 v0, v119, v0, 0xc0135761
	v_mul_f32_e32 v0, v119, v0
	v_exp_f32_e32 v0, v0
	v_pk_mul_f32 v[54:55], v[54:55], v[136:137] op_sel_hi:[1,0]
	v_pk_mul_f32 v[56:57], v[56:57], v[136:137] op_sel_hi:[1,0]
	v_pk_mul_f32 v[46:47], v[46:47], v[134:135] op_sel_hi:[1,0]
	v_add_f32_e32 v0, 1.0, v0
	v_rcp_f32_e32 v115, v0
	v_mul_f32_e32 v0, 0xbdd2d3e7, v120
	v_fmaak_f32 v0, v120, v0, 0xc0135761
	v_mul_f32_e32 v0, v120, v0
	v_exp_f32_e32 v0, v0
	v_pk_mul_f32 v[114:115], v[118:119], v[114:115]
	v_pk_mul_f32 v[48:49], v[48:49], v[134:135] op_sel_hi:[1,0]
	v_cvt_pk_bf16_f32 v114, v114, v115
	v_add_f32_e32 v0, 1.0, v0
	v_rcp_f32_e32 v118, v0
	v_mul_f32_e32 v0, 0xbdd2d3e7, v121
	v_fmaak_f32 v0, v121, v0, 0xc0135761
	v_mul_f32_e32 v0, v121, v0
	v_exp_f32_e32 v0, v0
	v_pk_mul_f32 v[38:39], v[38:39], v[134:135] op_sel_hi:[1,0]
	v_pk_mul_f32 v[40:41], v[40:41], v[134:135] op_sel_hi:[1,0]
	v_pk_mul_f32 v[30:31], v[30:31], v[132:133] op_sel_hi:[1,0]
	v_add_f32_e32 v0, 1.0, v0
	v_rcp_f32_e32 v119, v0
	v_mul_f32_e32 v0, 0xbdd2d3e7, v116
	v_fmaak_f32 v0, v116, v0, 0xc0135761
	v_mul_f32_e32 v0, v116, v0
	v_exp_f32_e32 v0, v0
	v_pk_mul_f32 v[118:119], v[120:121], v[118:119]
	v_pk_mul_f32 v[32:33], v[32:33], v[132:133] op_sel_hi:[1,0]
	v_cvt_pk_bf16_f32 v115, v118, v119
	v_add_f32_e32 v0, 1.0, v0
	v_rcp_f32_e32 v118, v0
	v_mul_f32_e32 v0, 0xbdd2d3e7, v117
	v_fmaak_f32 v0, v117, v0, 0xc0135761
	v_mul_f32_e32 v0, v117, v0
	v_exp_f32_e32 v0, v0
	v_pk_mul_f32 v[26:27], v[26:27], v[132:133] op_sel_hi:[1,0]
	v_pk_mul_f32 v[22:23], v[22:23], v[132:133] op_sel_hi:[1,0]
	s_movk_i32 s20, 0x3000
	v_add_f32_e32 v0, 1.0, v0
	v_rcp_f32_e32 v119, v0
	v_mul_f32_e32 v0, 0xbdd2d3e7, v122
	v_fmaak_f32 v0, v122, v0, 0xc0135761
; __device__ __forceinline__ unsigned cvt_pk_bf16(float lo, float hi) { f32x2 v = {lo, hi}; bf16x2_t_ b = __builtin_convertvector(v, bf16x2_t_); return __builtin_bit_cast(unsigned, b); }
; __device__ __forceinline__ float gelu_t(float x) {
;     const float u = x * (0.7978845608f + 0.0356774081f * x * x);
;     const float e = __builtin_amdgcn_exp2f(u * -2.8853900818f);
;     return x * __builtin_amdgcn_rcpf(1.0f + e);
; }
;     __device__ __forceinline__ void operator()(f32x4 (&acc)[2][2][4][2], const Unit& u, int wr, int wc, int fr, int fq) const {
;     ...
; #pragma unroll
;                     for (int bj = 0; bj < 2; ++bj) { const f32x4 a = acc[ai][bj][m][0] * rs[4 * ai + m], b = acc[ai][bj][m][1] * rs[4 * ai + m]; u32x4 w;
;                         w.x = cvt_pk_bf16(gelu_t(a.x), gelu_t(a.y)); w.y = cvt_pk_bf16(gelu_t(a.z), gelu_t(a.w)); w.z = cvt_pk_bf16(gelu_t(b.x), gelu_t(b.y)); w.w = cvt_pk_bf16(gelu_t(b.z), gelu_t(b.w));
;                         *(u32x4*)(dst + (size_t)(4 * ai + m) * 1024 + 128 * bj) = w; }
	v_mul_f32_e32 v0, v122, v0
	v_exp_f32_e32 v0, v0
	v_pk_mul_f32 v[116:117], v[116:117], v[118:119]
	v_pk_mul_f32 v[24:25], v[24:25], v[132:133] op_sel_hi:[1,0]
	v_cvt_pk_bf16_f32 v116, v116, v117
	v_add_f32_e32 v0, 1.0, v0
	v_rcp_f32_e32 v118, v0
	v_mul_f32_e32 v0, 0xbdd2d3e7, v123
	v_fmaak_f32 v0, v123, v0, 0xc0135761
	v_mul_f32_e32 v0, v123, v0
	v_exp_f32_e32 v0, v0
	v_pk_mul_f32 v[14:15], v[14:15], v[130:131] op_sel_hi:[1,0]
	v_pk_mul_f32 v[16:17], v[16:17], v[130:131] op_sel_hi:[1,0]
	v_pk_mul_f32 v[6:7], v[6:7], v[130:131] op_sel_hi:[1,0]
	v_add_f32_e32 v0, 1.0, v0
	v_rcp_f32_e32 v119, v0
	v_mul_f32_e32 v0, 0xbdd2d3e7, v110
	v_fmaak_f32 v0, v110, v0, 0xc0135761
	v_mul_f32_e32 v0, v110, v0
	v_exp_f32_e32 v0, v0
	v_pk_mul_f32 v[118:119], v[122:123], v[118:119]
	v_pk_mul_f32 v[8:9], v[8:9], v[130:131] op_sel_hi:[1,0]
	v_cvt_pk_bf16_f32 v117, v118, v119
	v_add_f32_e32 v0, 1.0, v0
	global_store_dwordx4 v[138:139], v[114:117], off offset:256
	s_nop 1
	v_pk_mul_f32 v[114:115], v[108:109], v[162:163] op_sel_hi:[1,0]
	v_pk_mul_f32 v[108:109], v[106:107], v[162:163] op_sel_hi:[1,0]
	v_rcp_f32_e32 v106, v0
	v_mul_f32_e32 v0, 0xbdd2d3e7, v111
	v_fmaak_f32 v0, v111, v0, 0xc0135761
	v_mul_f32_e32 v0, v111, v0
	v_exp_f32_e32 v0, v0
	s_nop 0
	v_add_f32_e32 v0, 1.0, v0
	v_rcp_f32_e32 v107, v0
	v_mul_f32_e32 v0, 0xbdd2d3e7, v112
	v_fmaak_f32 v0, v112, v0, 0xc0135761
	v_mul_f32_e32 v0, v112, v0
	v_exp_f32_e32 v0, v0
	v_pk_mul_f32 v[106:107], v[110:111], v[106:107]
	v_add_f32_e32 v0, 1.0, v0
	v_rcp_f32_e32 v110, v0
	v_mul_f32_e32 v0, 0xbdd2d3e7, v113
	v_fmaak_f32 v0, v113, v0, 0xc0135761
	v_mul_f32_e32 v0, v113, v0
	v_exp_f32_e32 v0, v0
	v_cvt_pk_bf16_f32 v106, v106, v107
	v_add_f32_e32 v0, 1.0, v0
	v_rcp_f32_e32 v111, v0
	v_mul_f32_e32 v0, 0xbdd2d3e7, v108
	v_fmaak_f32 v0, v108, v0, 0xc0135761
	v_mul_f32_e32 v0, v108, v0
	v_exp_f32_e32 v0, v0
	v_pk_mul_f32 v[110:111], v[112:113], v[110:111]
	v_add_f32_e32 v0, 1.0, v0
	v_cvt_pk_bf16_f32 v107, v110, v111
	v_rcp_f32_e32 v110, v0
	v_mul_f32_e32 v0, 0xbdd2d3e7, v109
	v_fmaak_f32 v0, v109, v0, 0xc0135761
	v_mul_f32_e32 v0, v109, v0
	v_exp_f32_e32 v0, v0
	s_nop 0
	v_add_f32_e32 v0, 1.0, v0
	v_rcp_f32_e32 v111, v0
	v_mul_f32_e32 v0, 0xbdd2d3e7, v114
	v_fmaak_f32 v0, v114, v0, 0xc0135761
	v_mul_f32_e32 v0, v114, v0
	v_exp_f32_e32 v0, v0
	v_pk_mul_f32 v[108:109], v[108:109], v[110:111]
	v_add_f32_e32 v0, 1.0, v0
	v_rcp_f32_e32 v110, v0
	v_mul_f32_e32 v0, 0xbdd2d3e7, v115
	v_fmaak_f32 v0, v115, v0, 0xc0135761
	v_mul_f32_e32 v0, v115, v0
	v_exp_f32_e32 v0, v0
	v_cvt_pk_bf16_f32 v108, v108, v109
	v_add_f32_e32 v0, 1.0, v0
	v_rcp_f32_e32 v111, v0
	v_mul_f32_e32 v0, 0xbdd2d3e7, v102
	v_fmaak_f32 v0, v102, v0, 0xc0135761
	v_mul_f32_e32 v0, v102, v0
	v_exp_f32_e32 v0, v0
	v_pk_mul_f32 v[110:111], v[114:115], v[110:111]
	v_add_f32_e32 v0, 1.0, v0
	v_cvt_pk_bf16_f32 v109, v110, v111
	global_store_dwordx4 v[138:139], v[106:109], off offset:2048
	s_nop 1
	v_pk_mul_f32 v[106:107], v[100:101], v[162:163] op_sel_hi:[1,0]
	v_pk_mul_f32 v[100:101], v[98:99], v[162:163] op_sel_hi:[1,0]
	v_rcp_f32_e32 v98, v0
	v_mul_f32_e32 v0, 0xbdd2d3e7, v103
	v_fmaak_f32 v0, v103, v0, 0xc0135761
	v_mul_f32_e32 v0, v103, v0
	v_exp_f32_e32 v0, v0
	s_nop 0
	v_add_f32_e32 v0, 1.0, v0
	v_rcp_f32_e32 v99, v0
	v_mul_f32_e32 v0, 0xbdd2d3e7, v104
	v_fmaak_f32 v0, v104, v0, 0xc0135761
	v_mul_f32_e32 v0, v104, v0
	v_exp_f32_e32 v0, v0
	v_pk_mul_f32 v[98:99], v[102:103], v[98:99]
	v_add_f32_e32 v0, 1.0, v0
	v_rcp_f32_e32 v102, v0
	v_mul_f32_e32 v0, 0xbdd2d3e7, v105
	v_fmaak_f32 v0, v105, v0, 0xc0135761
	v_mul_f32_e32 v0, v105, v0
	v_exp_f32_e32 v0, v0
	v_cvt_pk_bf16_f32 v98, v98, v99
	v_add_f32_e32 v0, 1.0, v0
	v_rcp_f32_e32 v103, v0
	v_mul_f32_e32 v0, 0xbdd2d3e7, v100
	v_fmaak_f32 v0, v100, v0, 0xc0135761
	v_mul_f32_e32 v0, v100, v0
	v_exp_f32_e32 v0, v0
	v_pk_mul_f32 v[102:103], v[104:105], v[102:103]
	v_add_f32_e32 v0, 1.0, v0
	v_cvt_pk_bf16_f32 v99, v102, v103
	v_rcp_f32_e32 v102, v0
	v_mul_f32_e32 v0, 0xbdd2d3e7, v101
	v_fmaak_f32 v0, v101, v0, 0xc0135761
	v_mul_f32_e32 v0, v101, v0
	v_exp_f32_e32 v0, v0
	s_nop 0
	v_add_f32_e32 v0, 1.0, v0
	v_rcp_f32_e32 v103, v0
	v_mul_f32_e32 v0, 0xbdd2d3e7, v106
	v_fmaak_f32 v0, v106, v0, 0xc0135761
	v_mul_f32_e32 v0, v106, v0
	v_exp_f32_e32 v0, v0
	v_pk_mul_f32 v[100:101], v[100:101], v[102:103]
	v_add_f32_e32 v0, 1.0, v0
	v_rcp_f32_e32 v102, v0
	v_mul_f32_e32 v0, 0xbdd2d3e7, v107
	v_fmaak_f32 v0, v107, v0, 0xc0135761
	v_mul_f32_e32 v0, v107, v0
	v_exp_f32_e32 v0, v0
	v_cvt_pk_bf16_f32 v100, v100, v101
	v_add_f32_e32 v0, 1.0, v0
	v_rcp_f32_e32 v103, v0
	v_mul_f32_e32 v0, 0xbdd2d3e7, v94
	v_fmaak_f32 v0, v94, v0, 0xc0135761
	v_mul_f32_e32 v0, v94, v0
	v_exp_f32_e32 v0, v0
	v_pk_mul_f32 v[102:103], v[106:107], v[102:103]
	v_add_f32_e32 v0, 1.0, v0
	v_cvt_pk_bf16_f32 v101, v102, v103
	global_store_dwordx4 v[138:139], v[98:101], off offset:2304
	s_nop 1
	v_rcp_f32_e32 v98, v0
	v_mul_f32_e32 v0, 0xbdd2d3e7, v95
	v_fmaak_f32 v0, v95, v0, 0xc0135761
	v_mul_f32_e32 v0, v95, v0
	v_exp_f32_e32 v0, v0
	s_nop 0
	v_add_f32_e32 v0, 1.0, v0
	v_rcp_f32_e32 v99, v0
	v_mul_f32_e32 v0, 0xbdd2d3e7, v96
	v_fmaak_f32 v0, v96, v0, 0xc0135761
	v_mul_f32_e32 v0, v96, v0
	v_exp_f32_e32 v0, v0
	v_pk_mul_f32 v[94:95], v[94:95], v[98:99]
	v_add_f32_e32 v0, 1.0, v0
	v_rcp_f32_e32 v98, v0
	v_mul_f32_e32 v0, 0xbdd2d3e7, v97
	v_fmaak_f32 v0, v97, v0, 0xc0135761
	v_mul_f32_e32 v0, v97, v0
	v_exp_f32_e32 v0, v0
	v_cvt_pk_bf16_f32 v94, v94, v95
	v_add_f32_e32 v0, 1.0, v0
	v_rcp_f32_e32 v99, v0
	v_mul_f32_e32 v0, 0xbdd2d3e7, v90
	v_fmaak_f32 v0, v90, v0, 0xc0135761
	v_mul_f32_e32 v0, v90, v0
	v_exp_f32_e32 v0, v0
	v_pk_mul_f32 v[96:97], v[96:97], v[98:99]
; __device__ __forceinline__ unsigned cvt_pk_bf16(float lo, float hi) { f32x2 v = {lo, hi}; bf16x2_t_ b = __builtin_convertvector(v, bf16x2_t_); return __builtin_bit_cast(unsigned, b); }
; __device__ __forceinline__ float gelu_t(float x) {
;     const float u = x * (0.7978845608f + 0.0356774081f * x * x);
;     const float e = __builtin_amdgcn_exp2f(u * -2.8853900818f);
;     return x * __builtin_amdgcn_rcpf(1.0f + e);
; }
;     __device__ __forceinline__ void operator()(f32x4 (&acc)[2][2][4][2], const Unit& u, int wr, int wc, int fr, int fq) const {
;     ...
; #pragma unroll
;                     for (int bj = 0; bj < 2; ++bj) { const f32x4 a = acc[ai][bj][m][0] * rs[4 * ai + m], b = acc[ai][bj][m][1] * rs[4 * ai + m]; u32x4 w;
;                         w.x = cvt_pk_bf16(gelu_t(a.x), gelu_t(a.y)); w.y = cvt_pk_bf16(gelu_t(a.z), gelu_t(a.w)); w.z = cvt_pk_bf16(gelu_t(b.x), gelu_t(b.y)); w.w = cvt_pk_bf16(gelu_t(b.z), gelu_t(b.w));
;                         *(u32x4*)(dst + (size_t)(4 * ai + m) * 1024 + 128 * bj) = w; }
	v_add_f32_e32 v0, 1.0, v0
	v_cvt_pk_bf16_f32 v95, v96, v97
	v_rcp_f32_e32 v96, v0
	v_mul_f32_e32 v0, 0xbdd2d3e7, v91
	v_fmaak_f32 v0, v91, v0, 0xc0135761
	v_mul_f32_e32 v0, v91, v0
	v_exp_f32_e32 v0, v0
	s_nop 0
	v_add_f32_e32 v0, 1.0, v0
	v_rcp_f32_e32 v97, v0
	v_mul_f32_e32 v0, 0xbdd2d3e7, v92
	v_fmaak_f32 v0, v92, v0, 0xc0135761
	v_mul_f32_e32 v0, v92, v0
	v_exp_f32_e32 v0, v0
	v_pk_mul_f32 v[90:91], v[90:91], v[96:97]
	v_add_f32_e32 v0, 1.0, v0
	v_cvt_pk_bf16_f32 v96, v90, v91
	v_rcp_f32_e32 v90, v0
	v_mul_f32_e32 v0, 0xbdd2d3e7, v93
	v_fmaak_f32 v0, v93, v0, 0xc0135761
	v_mul_f32_e32 v0, v93, v0
	v_exp_f32_e32 v0, v0
	s_nop 0
	v_add_f32_e32 v0, 1.0, v0
	v_rcp_f32_e32 v91, v0
	v_mul_f32_e32 v0, 0xbdd2d3e7, v86
	v_fmaak_f32 v0, v86, v0, 0xc0135761
	v_mul_f32_e32 v0, v86, v0
	v_exp_f32_e32 v0, v0
	v_pk_mul_f32 v[90:91], v[92:93], v[90:91]
	v_add_co_u32_e32 v92, vcc, s83, v138
	v_cvt_pk_bf16_f32 v97, v90, v91
	s_nop 0
	v_addc_co_u32_e32 v93, vcc, 0, v139, vcc
	v_add_co_u32_e32 v90, vcc, s82, v138
	v_add_f32_e32 v0, 1.0, v0
	s_nop 0
	v_addc_co_u32_e32 v91, vcc, 0, v139, vcc
	global_store_dwordx4 v[90:91], v[94:97], off offset:-4096
	s_nop 1
	v_pk_mul_f32 v[94:95], v[84:85], v[160:161] op_sel_hi:[1,0]
	v_pk_mul_f32 v[84:85], v[82:83], v[160:161] op_sel_hi:[1,0]
	v_rcp_f32_e32 v82, v0
	v_mul_f32_e32 v0, 0xbdd2d3e7, v87
	v_fmaak_f32 v0, v87, v0, 0xc0135761
	v_mul_f32_e32 v0, v87, v0
	v_exp_f32_e32 v0, v0
	s_nop 0
	v_add_f32_e32 v0, 1.0, v0
	v_rcp_f32_e32 v83, v0
	v_mul_f32_e32 v0, 0xbdd2d3e7, v88
	v_fmaak_f32 v0, v88, v0, 0xc0135761
	v_mul_f32_e32 v0, v88, v0
	v_exp_f32_e32 v0, v0
	v_pk_mul_f32 v[82:83], v[86:87], v[82:83]
	v_add_f32_e32 v0, 1.0, v0
	v_rcp_f32_e32 v86, v0
	v_mul_f32_e32 v0, 0xbdd2d3e7, v89
	v_fmaak_f32 v0, v89, v0, 0xc0135761
	v_mul_f32_e32 v0, v89, v0
	v_exp_f32_e32 v0, v0
	v_cvt_pk_bf16_f32 v82, v82, v83
	v_add_f32_e32 v0, 1.0, v0
	v_rcp_f32_e32 v87, v0
	v_mul_f32_e32 v0, 0xbdd2d3e7, v84
	v_fmaak_f32 v0, v84, v0, 0xc0135761
	v_mul_f32_e32 v0, v84, v0
	v_exp_f32_e32 v0, v0
	v_pk_mul_f32 v[86:87], v[88:89], v[86:87]
	v_add_f32_e32 v0, 1.0, v0
	v_cvt_pk_bf16_f32 v83, v86, v87
	v_rcp_f32_e32 v86, v0
	v_mul_f32_e32 v0, 0xbdd2d3e7, v85
	v_fmaak_f32 v0, v85, v0, 0xc0135761
	v_mul_f32_e32 v0, v85, v0
	v_exp_f32_e32 v0, v0
	s_nop 0
	v_add_f32_e32 v0, 1.0, v0
	v_rcp_f32_e32 v87, v0
	v_mul_f32_e32 v0, 0xbdd2d3e7, v94
	v_fmaak_f32 v0, v94, v0, 0xc0135761
	v_mul_f32_e32 v0, v94, v0
	v_exp_f32_e32 v0, v0
	v_pk_mul_f32 v[84:85], v[84:85], v[86:87]
	v_add_f32_e32 v0, 1.0, v0
	v_rcp_f32_e32 v86, v0
	v_mul_f32_e32 v0, 0xbdd2d3e7, v95
	v_fmaak_f32 v0, v95, v0, 0xc0135761
	v_mul_f32_e32 v0, v95, v0
	v_exp_f32_e32 v0, v0
	v_cvt_pk_bf16_f32 v84, v84, v85
	v_add_f32_e32 v0, 1.0, v0
	v_rcp_f32_e32 v87, v0
	v_mul_f32_e32 v0, 0xbdd2d3e7, v78
	v_fmaak_f32 v0, v78, v0, 0xc0135761
	v_mul_f32_e32 v0, v78, v0
	v_exp_f32_e32 v0, v0
	v_pk_mul_f32 v[86:87], v[94:95], v[86:87]
	v_add_f32_e32 v0, 1.0, v0
	v_cvt_pk_bf16_f32 v85, v86, v87
	global_store_dwordx4 v[92:93], v[82:85], off offset:256
	s_nop 1
	v_pk_mul_f32 v[82:83], v[76:77], v[158:159] op_sel_hi:[1,0]
	v_pk_mul_f32 v[76:77], v[74:75], v[158:159] op_sel_hi:[1,0]
	v_rcp_f32_e32 v74, v0
	v_mul_f32_e32 v0, 0xbdd2d3e7, v79
	v_fmaak_f32 v0, v79, v0, 0xc0135761
	v_mul_f32_e32 v0, v79, v0
	v_exp_f32_e32 v0, v0
	s_nop 0
	v_add_f32_e32 v0, 1.0, v0
	v_rcp_f32_e32 v75, v0
	v_mul_f32_e32 v0, 0xbdd2d3e7, v80
	v_fmaak_f32 v0, v80, v0, 0xc0135761
	v_mul_f32_e32 v0, v80, v0
	v_exp_f32_e32 v0, v0
	v_pk_mul_f32 v[74:75], v[78:79], v[74:75]
	v_add_f32_e32 v0, 1.0, v0
	v_rcp_f32_e32 v78, v0
	v_mul_f32_e32 v0, 0xbdd2d3e7, v81
	v_fmaak_f32 v0, v81, v0, 0xc0135761
	v_mul_f32_e32 v0, v81, v0
	v_exp_f32_e32 v0, v0
	v_cvt_pk_bf16_f32 v74, v74, v75
	v_add_f32_e32 v0, 1.0, v0
	v_rcp_f32_e32 v79, v0
	v_mul_f32_e32 v0, 0xbdd2d3e7, v76
	v_fmaak_f32 v0, v76, v0, 0xc0135761
	v_mul_f32_e32 v0, v76, v0
	v_exp_f32_e32 v0, v0
	v_pk_mul_f32 v[78:79], v[80:81], v[78:79]
	v_add_f32_e32 v0, 1.0, v0
	v_cvt_pk_bf16_f32 v75, v78, v79
	v_rcp_f32_e32 v78, v0
	v_mul_f32_e32 v0, 0xbdd2d3e7, v77
	v_fmaak_f32 v0, v77, v0, 0xc0135761
	v_mul_f32_e32 v0, v77, v0
	v_exp_f32_e32 v0, v0
	s_nop 0
	v_add_f32_e32 v0, 1.0, v0
	v_rcp_f32_e32 v79, v0
	v_mul_f32_e32 v0, 0xbdd2d3e7, v82
	v_fmaak_f32 v0, v82, v0, 0xc0135761
	v_mul_f32_e32 v0, v82, v0
	v_exp_f32_e32 v0, v0
	v_pk_mul_f32 v[76:77], v[76:77], v[78:79]
	v_add_f32_e32 v0, 1.0, v0
	v_rcp_f32_e32 v78, v0
	v_mul_f32_e32 v0, 0xbdd2d3e7, v83
	v_fmaak_f32 v0, v83, v0, 0xc0135761
	v_mul_f32_e32 v0, v83, v0
	v_exp_f32_e32 v0, v0
	v_cvt_pk_bf16_f32 v76, v76, v77
	v_add_f32_e32 v0, 1.0, v0
	v_rcp_f32_e32 v79, v0
	v_mul_f32_e32 v0, 0xbdd2d3e7, v70
	v_fmaak_f32 v0, v70, v0, 0xc0135761
	v_mul_f32_e32 v0, v70, v0
	v_exp_f32_e32 v0, v0
	v_pk_mul_f32 v[78:79], v[82:83], v[78:79]
	v_add_f32_e32 v0, 1.0, v0
	v_cvt_pk_bf16_f32 v77, v78, v79
	global_store_dwordx4 v[92:93], v[74:77], off offset:2048
	s_nop 1
	v_pk_mul_f32 v[74:75], v[68:69], v[158:159] op_sel_hi:[1,0]
	v_pk_mul_f32 v[68:69], v[66:67], v[158:159] op_sel_hi:[1,0]
	v_rcp_f32_e32 v66, v0
	v_mul_f32_e32 v0, 0xbdd2d3e7, v71
	v_fmaak_f32 v0, v71, v0, 0xc0135761
	v_mul_f32_e32 v0, v71, v0
	v_exp_f32_e32 v0, v0
	s_nop 0
	v_add_f32_e32 v0, 1.0, v0
	v_rcp_f32_e32 v67, v0
	v_mul_f32_e32 v0, 0xbdd2d3e7, v72
	v_fmaak_f32 v0, v72, v0, 0xc0135761
	v_mul_f32_e32 v0, v72, v0
	v_exp_f32_e32 v0, v0
	v_pk_mul_f32 v[66:67], v[70:71], v[66:67]
	v_add_f32_e32 v0, 1.0, v0
	v_rcp_f32_e32 v70, v0
	v_mul_f32_e32 v0, 0xbdd2d3e7, v73
	v_fmaak_f32 v0, v73, v0, 0xc0135761
	v_mul_f32_e32 v0, v73, v0
	v_exp_f32_e32 v0, v0
	v_cvt_pk_bf16_f32 v66, v66, v67
	v_add_f32_e32 v0, 1.0, v0
; __device__ __forceinline__ unsigned cvt_pk_bf16(float lo, float hi) { f32x2 v = {lo, hi}; bf16x2_t_ b = __builtin_convertvector(v, bf16x2_t_); return __builtin_bit_cast(unsigned, b); }
; __device__ __forceinline__ float gelu_t(float x) {
;     const float u = x * (0.7978845608f + 0.0356774081f * x * x);
;     const float e = __builtin_amdgcn_exp2f(u * -2.8853900818f);
;     return x * __builtin_amdgcn_rcpf(1.0f + e);
; }
;     __device__ __forceinline__ void operator()(f32x4 (&acc)[2][2][4][2], const Unit& u, int wr, int wc, int fr, int fq) const {
;     ...
; #pragma unroll
;                     for (int bj = 0; bj < 2; ++bj) { const f32x4 a = acc[ai][bj][m][0] * rs[4 * ai + m], b = acc[ai][bj][m][1] * rs[4 * ai + m]; u32x4 w;
;                         w.x = cvt_pk_bf16(gelu_t(a.x), gelu_t(a.y)); w.y = cvt_pk_bf16(gelu_t(a.z), gelu_t(a.w)); w.z = cvt_pk_bf16(gelu_t(b.x), gelu_t(b.y)); w.w = cvt_pk_bf16(gelu_t(b.z), gelu_t(b.w));
;                         *(u32x4*)(dst + (size_t)(4 * ai + m) * 1024 + 128 * bj) = w; }
	v_rcp_f32_e32 v71, v0
	v_mul_f32_e32 v0, 0xbdd2d3e7, v68
	v_fmaak_f32 v0, v68, v0, 0xc0135761
	v_mul_f32_e32 v0, v68, v0
	v_exp_f32_e32 v0, v0
	v_pk_mul_f32 v[70:71], v[72:73], v[70:71]
	v_add_f32_e32 v0, 1.0, v0
	v_cvt_pk_bf16_f32 v67, v70, v71
	v_rcp_f32_e32 v70, v0
	v_mul_f32_e32 v0, 0xbdd2d3e7, v69
	v_fmaak_f32 v0, v69, v0, 0xc0135761
	v_mul_f32_e32 v0, v69, v0
	v_exp_f32_e32 v0, v0
	s_nop 0
	v_add_f32_e32 v0, 1.0, v0
	v_rcp_f32_e32 v71, v0
	v_mul_f32_e32 v0, 0xbdd2d3e7, v74
	v_fmaak_f32 v0, v74, v0, 0xc0135761
	v_mul_f32_e32 v0, v74, v0
	v_exp_f32_e32 v0, v0
	v_pk_mul_f32 v[68:69], v[68:69], v[70:71]
	v_add_f32_e32 v0, 1.0, v0
	v_rcp_f32_e32 v70, v0
	v_mul_f32_e32 v0, 0xbdd2d3e7, v75
	v_fmaak_f32 v0, v75, v0, 0xc0135761
	v_mul_f32_e32 v0, v75, v0
	v_exp_f32_e32 v0, v0
	v_cvt_pk_bf16_f32 v68, v68, v69
	v_add_f32_e32 v0, 1.0, v0
	v_rcp_f32_e32 v71, v0
	v_mul_f32_e32 v0, 0xbdd2d3e7, v62
	v_fmaak_f32 v0, v62, v0, 0xc0135761
	v_mul_f32_e32 v0, v62, v0
	v_exp_f32_e32 v0, v0
	v_pk_mul_f32 v[70:71], v[74:75], v[70:71]
	v_add_f32_e32 v0, 1.0, v0
	v_cvt_pk_bf16_f32 v69, v70, v71
	global_store_dwordx4 v[92:93], v[66:69], off offset:2304
	s_nop 1
	v_pk_mul_f32 v[66:67], v[60:61], v[136:137] op_sel_hi:[1,0]
	v_pk_mul_f32 v[60:61], v[58:59], v[136:137] op_sel_hi:[1,0]
	v_rcp_f32_e32 v58, v0
	v_mul_f32_e32 v0, 0xbdd2d3e7, v63
	v_fmaak_f32 v0, v63, v0, 0xc0135761
	v_mul_f32_e32 v0, v63, v0
	v_exp_f32_e32 v0, v0
	s_nop 0
	v_add_f32_e32 v0, 1.0, v0
	v_rcp_f32_e32 v59, v0
	v_mul_f32_e32 v0, 0xbdd2d3e7, v64
	v_fmaak_f32 v0, v64, v0, 0xc0135761
	v_mul_f32_e32 v0, v64, v0
	v_exp_f32_e32 v0, v0
	v_pk_mul_f32 v[58:59], v[62:63], v[58:59]
	v_add_f32_e32 v0, 1.0, v0
	v_rcp_f32_e32 v62, v0
	v_mul_f32_e32 v0, 0xbdd2d3e7, v65
	v_fmaak_f32 v0, v65, v0, 0xc0135761
	v_mul_f32_e32 v0, v65, v0
	v_exp_f32_e32 v0, v0
	v_cvt_pk_bf16_f32 v58, v58, v59
	v_add_f32_e32 v0, 1.0, v0
	v_rcp_f32_e32 v63, v0
	v_mul_f32_e32 v0, 0xbdd2d3e7, v60
	v_fmaak_f32 v0, v60, v0, 0xc0135761
	v_mul_f32_e32 v0, v60, v0
	v_exp_f32_e32 v0, v0
	v_pk_mul_f32 v[62:63], v[64:65], v[62:63]
	v_add_f32_e32 v0, 1.0, v0
	v_cvt_pk_bf16_f32 v59, v62, v63
	v_rcp_f32_e32 v62, v0
	v_mul_f32_e32 v0, 0xbdd2d3e7, v61
	v_fmaak_f32 v0, v61, v0, 0xc0135761
	v_mul_f32_e32 v0, v61, v0
	v_exp_f32_e32 v0, v0
	s_nop 0
	v_add_f32_e32 v0, 1.0, v0
	v_rcp_f32_e32 v63, v0
	v_mul_f32_e32 v0, 0xbdd2d3e7, v66
	v_fmaak_f32 v0, v66, v0, 0xc0135761
	v_mul_f32_e32 v0, v66, v0
	v_exp_f32_e32 v0, v0
	v_pk_mul_f32 v[60:61], v[60:61], v[62:63]
	v_add_f32_e32 v0, 1.0, v0
	v_rcp_f32_e32 v62, v0
	v_mul_f32_e32 v0, 0xbdd2d3e7, v67
	v_fmaak_f32 v0, v67, v0, 0xc0135761
	v_mul_f32_e32 v0, v67, v0
	v_exp_f32_e32 v0, v0
	v_cvt_pk_bf16_f32 v60, v60, v61
	v_add_f32_e32 v0, 1.0, v0
	v_rcp_f32_e32 v63, v0
	v_mul_f32_e32 v0, 0xbdd2d3e7, v54
	v_fmaak_f32 v0, v54, v0, 0xc0135761
	v_mul_f32_e32 v0, v54, v0
	v_exp_f32_e32 v0, v0
	v_pk_mul_f32 v[62:63], v[66:67], v[62:63]
	v_add_f32_e32 v0, 1.0, v0
	v_cvt_pk_bf16_f32 v61, v62, v63
	global_store_dwordx4 v[90:91], v[58:61], off
	s_nop 1
	v_pk_mul_f32 v[58:59], v[52:53], v[136:137] op_sel_hi:[1,0]
	v_pk_mul_f32 v[52:53], v[50:51], v[136:137] op_sel_hi:[1,0]
	v_rcp_f32_e32 v50, v0
	v_mul_f32_e32 v0, 0xbdd2d3e7, v55
	v_fmaak_f32 v0, v55, v0, 0xc0135761
	v_mul_f32_e32 v0, v55, v0
	v_exp_f32_e32 v0, v0
	s_nop 0
	v_add_f32_e32 v0, 1.0, v0
	v_rcp_f32_e32 v51, v0
	v_mul_f32_e32 v0, 0xbdd2d3e7, v56
	v_fmaak_f32 v0, v56, v0, 0xc0135761
	v_mul_f32_e32 v0, v56, v0
	v_exp_f32_e32 v0, v0
	v_pk_mul_f32 v[50:51], v[54:55], v[50:51]
	v_add_f32_e32 v0, 1.0, v0
	v_rcp_f32_e32 v54, v0
	v_mul_f32_e32 v0, 0xbdd2d3e7, v57
	v_fmaak_f32 v0, v57, v0, 0xc0135761
	v_mul_f32_e32 v0, v57, v0
	v_exp_f32_e32 v0, v0
	v_cvt_pk_bf16_f32 v50, v50, v51
	v_add_f32_e32 v0, 1.0, v0
	v_rcp_f32_e32 v55, v0
	v_mul_f32_e32 v0, 0xbdd2d3e7, v52
	v_fmaak_f32 v0, v52, v0, 0xc0135761
	v_mul_f32_e32 v0, v52, v0
	v_exp_f32_e32 v0, v0
	v_pk_mul_f32 v[54:55], v[56:57], v[54:55]
	v_add_f32_e32 v0, 1.0, v0
	v_cvt_pk_bf16_f32 v51, v54, v55
	v_rcp_f32_e32 v54, v0
	v_mul_f32_e32 v0, 0xbdd2d3e7, v53
	v_fmaak_f32 v0, v53, v0, 0xc0135761
	v_mul_f32_e32 v0, v53, v0
	v_exp_f32_e32 v0, v0
	s_nop 0
	v_add_f32_e32 v0, 1.0, v0
	v_rcp_f32_e32 v55, v0
	v_mul_f32_e32 v0, 0xbdd2d3e7, v58
	v_fmaak_f32 v0, v58, v0, 0xc0135761
	v_mul_f32_e32 v0, v58, v0
	v_exp_f32_e32 v0, v0
	v_pk_mul_f32 v[52:53], v[52:53], v[54:55]
	v_add_f32_e32 v0, 1.0, v0
	v_rcp_f32_e32 v54, v0
	v_mul_f32_e32 v0, 0xbdd2d3e7, v59
	v_fmaak_f32 v0, v59, v0, 0xc0135761
	v_mul_f32_e32 v0, v59, v0
	v_exp_f32_e32 v0, v0
	v_cvt_pk_bf16_f32 v52, v52, v53
	v_add_f32_e32 v0, 1.0, v0
	v_rcp_f32_e32 v55, v0
	v_mul_f32_e32 v0, 0xbdd2d3e7, v46
	v_fmaak_f32 v0, v46, v0, 0xc0135761
	v_mul_f32_e32 v0, v46, v0
	v_exp_f32_e32 v0, v0
	v_pk_mul_f32 v[54:55], v[58:59], v[54:55]
	v_add_f32_e32 v0, 1.0, v0
	v_cvt_pk_bf16_f32 v53, v54, v55
	global_store_dwordx4 v[90:91], v[50:53], off offset:256
	s_nop 1
	v_pk_mul_f32 v[50:51], v[44:45], v[134:135] op_sel_hi:[1,0]
	v_pk_mul_f32 v[44:45], v[42:43], v[134:135] op_sel_hi:[1,0]
	v_rcp_f32_e32 v42, v0
	v_mul_f32_e32 v0, 0xbdd2d3e7, v47
	v_fmaak_f32 v0, v47, v0, 0xc0135761
	v_mul_f32_e32 v0, v47, v0
	v_exp_f32_e32 v0, v0
	s_nop 0
	v_add_f32_e32 v0, 1.0, v0
	v_rcp_f32_e32 v43, v0
	v_mul_f32_e32 v0, 0xbdd2d3e7, v48
	v_fmaak_f32 v0, v48, v0, 0xc0135761
	v_mul_f32_e32 v0, v48, v0
	v_exp_f32_e32 v0, v0
	v_pk_mul_f32 v[42:43], v[46:47], v[42:43]
	v_add_f32_e32 v0, 1.0, v0
	v_rcp_f32_e32 v46, v0
	v_mul_f32_e32 v0, 0xbdd2d3e7, v49
	v_fmaak_f32 v0, v49, v0, 0xc0135761
	v_mul_f32_e32 v0, v49, v0
	v_exp_f32_e32 v0, v0
	v_cvt_pk_bf16_f32 v42, v42, v43
	v_add_f32_e32 v0, 1.0, v0
	v_rcp_f32_e32 v47, v0
; __device__ __forceinline__ unsigned cvt_pk_bf16(float lo, float hi) { f32x2 v = {lo, hi}; bf16x2_t_ b = __builtin_convertvector(v, bf16x2_t_); return __builtin_bit_cast(unsigned, b); }
; __device__ __forceinline__ float gelu_t(float x) {
;     const float u = x * (0.7978845608f + 0.0356774081f * x * x);
;     const float e = __builtin_amdgcn_exp2f(u * -2.8853900818f);
;     return x * __builtin_amdgcn_rcpf(1.0f + e);
; }
;     __device__ __forceinline__ void operator()(f32x4 (&acc)[2][2][4][2], const Unit& u, int wr, int wc, int fr, int fq) const {
;     ...
; #pragma unroll
;                     for (int bj = 0; bj < 2; ++bj) { const f32x4 a = acc[ai][bj][m][0] * rs[4 * ai + m], b = acc[ai][bj][m][1] * rs[4 * ai + m]; u32x4 w;
;                         w.x = cvt_pk_bf16(gelu_t(a.x), gelu_t(a.y)); w.y = cvt_pk_bf16(gelu_t(a.z), gelu_t(a.w)); w.z = cvt_pk_bf16(gelu_t(b.x), gelu_t(b.y)); w.w = cvt_pk_bf16(gelu_t(b.z), gelu_t(b.w));
;                         *(u32x4*)(dst + (size_t)(4 * ai + m) * 1024 + 128 * bj) = w; }
	v_mul_f32_e32 v0, 0xbdd2d3e7, v44
	v_fmaak_f32 v0, v44, v0, 0xc0135761
	v_mul_f32_e32 v0, v44, v0
	v_exp_f32_e32 v0, v0
	v_pk_mul_f32 v[46:47], v[48:49], v[46:47]
	v_add_f32_e32 v0, 1.0, v0
	v_cvt_pk_bf16_f32 v43, v46, v47
	v_rcp_f32_e32 v46, v0
	v_mul_f32_e32 v0, 0xbdd2d3e7, v45
	v_fmaak_f32 v0, v45, v0, 0xc0135761
	v_mul_f32_e32 v0, v45, v0
	v_exp_f32_e32 v0, v0
	s_nop 0
	v_add_f32_e32 v0, 1.0, v0
	v_rcp_f32_e32 v47, v0
	v_mul_f32_e32 v0, 0xbdd2d3e7, v50
	v_fmaak_f32 v0, v50, v0, 0xc0135761
	v_mul_f32_e32 v0, v50, v0
	v_exp_f32_e32 v0, v0
	v_pk_mul_f32 v[44:45], v[44:45], v[46:47]
	v_add_f32_e32 v0, 1.0, v0
	v_rcp_f32_e32 v46, v0
	v_mul_f32_e32 v0, 0xbdd2d3e7, v51
	v_fmaak_f32 v0, v51, v0, 0xc0135761
	v_mul_f32_e32 v0, v51, v0
	v_exp_f32_e32 v0, v0
	v_cvt_pk_bf16_f32 v44, v44, v45
	v_add_f32_e32 v0, 1.0, v0
	v_rcp_f32_e32 v47, v0
	v_mul_f32_e32 v0, 0xbdd2d3e7, v38
	v_fmaak_f32 v0, v38, v0, 0xc0135761
	v_mul_f32_e32 v0, v38, v0
	v_exp_f32_e32 v0, v0
	v_pk_mul_f32 v[46:47], v[50:51], v[46:47]
	v_add_f32_e32 v0, 1.0, v0
	v_cvt_pk_bf16_f32 v45, v46, v47
	global_store_dwordx4 v[90:91], v[42:45], off offset:2048
	s_nop 1
	v_pk_mul_f32 v[42:43], v[36:37], v[134:135] op_sel_hi:[1,0]
	v_pk_mul_f32 v[36:37], v[34:35], v[134:135] op_sel_hi:[1,0]
	v_rcp_f32_e32 v34, v0
	v_mul_f32_e32 v0, 0xbdd2d3e7, v39
	v_fmaak_f32 v0, v39, v0, 0xc0135761
	v_mul_f32_e32 v0, v39, v0
	v_exp_f32_e32 v0, v0
	s_nop 0
	v_add_f32_e32 v0, 1.0, v0
	v_rcp_f32_e32 v35, v0
	v_mul_f32_e32 v0, 0xbdd2d3e7, v40
	v_fmaak_f32 v0, v40, v0, 0xc0135761
	v_mul_f32_e32 v0, v40, v0
	v_exp_f32_e32 v0, v0
	v_pk_mul_f32 v[34:35], v[38:39], v[34:35]
	v_add_f32_e32 v0, 1.0, v0
	v_rcp_f32_e32 v38, v0
	v_mul_f32_e32 v0, 0xbdd2d3e7, v41
	v_fmaak_f32 v0, v41, v0, 0xc0135761
	v_mul_f32_e32 v0, v41, v0
	v_exp_f32_e32 v0, v0
	v_cvt_pk_bf16_f32 v34, v34, v35
	v_add_f32_e32 v0, 1.0, v0
	v_rcp_f32_e32 v39, v0
	v_mul_f32_e32 v0, 0xbdd2d3e7, v36
	v_fmaak_f32 v0, v36, v0, 0xc0135761
	v_mul_f32_e32 v0, v36, v0
	v_exp_f32_e32 v0, v0
	v_pk_mul_f32 v[38:39], v[40:41], v[38:39]
	v_add_f32_e32 v0, 1.0, v0
	v_cvt_pk_bf16_f32 v35, v38, v39
	v_rcp_f32_e32 v38, v0
	v_mul_f32_e32 v0, 0xbdd2d3e7, v37
	v_fmaak_f32 v0, v37, v0, 0xc0135761
	v_mul_f32_e32 v0, v37, v0
	v_exp_f32_e32 v0, v0
	s_nop 0
	v_add_f32_e32 v0, 1.0, v0
	v_rcp_f32_e32 v39, v0
	v_mul_f32_e32 v0, 0xbdd2d3e7, v42
	v_fmaak_f32 v0, v42, v0, 0xc0135761
	v_mul_f32_e32 v0, v42, v0
	v_exp_f32_e32 v0, v0
	v_pk_mul_f32 v[36:37], v[36:37], v[38:39]
	v_add_f32_e32 v0, 1.0, v0
	v_rcp_f32_e32 v38, v0
	v_mul_f32_e32 v0, 0xbdd2d3e7, v43
	v_fmaak_f32 v0, v43, v0, 0xc0135761
	v_mul_f32_e32 v0, v43, v0
	v_exp_f32_e32 v0, v0
	v_cvt_pk_bf16_f32 v36, v36, v37
	v_add_f32_e32 v0, 1.0, v0
	v_rcp_f32_e32 v39, v0
	v_mul_f32_e32 v0, 0xbdd2d3e7, v30
	v_fmaak_f32 v0, v30, v0, 0xc0135761
	v_mul_f32_e32 v0, v30, v0
	v_exp_f32_e32 v0, v0
	v_pk_mul_f32 v[38:39], v[42:43], v[38:39]
	v_add_f32_e32 v0, 1.0, v0
	v_cvt_pk_bf16_f32 v37, v38, v39
	global_store_dwordx4 v[90:91], v[34:37], off offset:2304
	s_nop 1
	v_pk_mul_f32 v[34:35], v[28:29], v[132:133] op_sel_hi:[1,0]
	v_rcp_f32_e32 v28, v0
	v_mul_f32_e32 v0, 0xbdd2d3e7, v31
	v_fmaak_f32 v0, v31, v0, 0xc0135761
	v_mul_f32_e32 v0, v31, v0
	v_exp_f32_e32 v0, v0
	s_nop 0
	v_add_f32_e32 v0, 1.0, v0
	v_rcp_f32_e32 v29, v0
	v_mul_f32_e32 v0, 0xbdd2d3e7, v32
	v_fmaak_f32 v0, v32, v0, 0xc0135761
	v_mul_f32_e32 v0, v32, v0
	v_exp_f32_e32 v0, v0
	v_pk_mul_f32 v[28:29], v[30:31], v[28:29]
	v_add_f32_e32 v0, 1.0, v0
	v_rcp_f32_e32 v30, v0
	v_mul_f32_e32 v0, 0xbdd2d3e7, v33
	v_fmaak_f32 v0, v33, v0, 0xc0135761
	v_mul_f32_e32 v0, v33, v0
	v_exp_f32_e32 v0, v0
	v_cvt_pk_bf16_f32 v28, v28, v29
	v_add_f32_e32 v0, 1.0, v0
	v_rcp_f32_e32 v31, v0
	v_mul_f32_e32 v0, 0xbdd2d3e7, v26
	v_fmaak_f32 v0, v26, v0, 0xc0135761
	v_mul_f32_e32 v0, v26, v0
	v_exp_f32_e32 v0, v0
	v_pk_mul_f32 v[30:31], v[32:33], v[30:31]
	v_add_f32_e32 v0, 1.0, v0
	v_cvt_pk_bf16_f32 v29, v30, v31
	v_rcp_f32_e32 v30, v0
	v_mul_f32_e32 v0, 0xbdd2d3e7, v27
	v_fmaak_f32 v0, v27, v0, 0xc0135761
	v_mul_f32_e32 v0, v27, v0
	v_exp_f32_e32 v0, v0
	s_nop 0
	v_add_f32_e32 v0, 1.0, v0
	v_rcp_f32_e32 v31, v0
	v_mul_f32_e32 v0, 0xbdd2d3e7, v34
	v_fmaak_f32 v0, v34, v0, 0xc0135761
	v_mul_f32_e32 v0, v34, v0
	v_exp_f32_e32 v0, v0
	v_pk_mul_f32 v[26:27], v[26:27], v[30:31]
	v_add_f32_e32 v0, 1.0, v0
	v_cvt_pk_bf16_f32 v30, v26, v27
	v_rcp_f32_e32 v26, v0
	v_mul_f32_e32 v0, 0xbdd2d3e7, v35
	v_fmaak_f32 v0, v35, v0, 0xc0135761
	v_mul_f32_e32 v0, v35, v0
	v_exp_f32_e32 v0, v0
	s_nop 0
	v_add_f32_e32 v0, 1.0, v0
	v_rcp_f32_e32 v27, v0
	v_mul_f32_e32 v0, 0xbdd2d3e7, v22
	v_fmaak_f32 v0, v22, v0, 0xc0135761
	v_mul_f32_e32 v0, v22, v0
	v_exp_f32_e32 v0, v0
	v_pk_mul_f32 v[26:27], v[34:35], v[26:27]
	v_add_f32_e32 v0, 1.0, v0
	v_cvt_pk_bf16_f32 v31, v26, v27
	v_add_co_u32_e32 v26, vcc, s20, v138
	s_nop 1
	v_addc_co_u32_e32 v27, vcc, 0, v139, vcc
	global_store_dwordx4 v[26:27], v[28:31], off
	s_nop 1
	v_pk_mul_f32 v[28:29], v[20:21], v[132:133] op_sel_hi:[1,0]
	v_pk_mul_f32 v[20:21], v[18:19], v[132:133] op_sel_hi:[1,0]
	v_rcp_f32_e32 v18, v0
	v_mul_f32_e32 v0, 0xbdd2d3e7, v23
	v_fmaak_f32 v0, v23, v0, 0xc0135761
	v_mul_f32_e32 v0, v23, v0
	v_exp_f32_e32 v0, v0
	s_nop 0
	v_add_f32_e32 v0, 1.0, v0
; __device__ __forceinline__ float gelu_t(float x) {
;     const float u = x * (0.7978845608f + 0.0356774081f * x * x);
;     const float e = __builtin_amdgcn_exp2f(u * -2.8853900818f);
;     return x * __builtin_amdgcn_rcpf(1.0f + e);
; }
; template <class Epi, int PARTS>
; __device__ __forceinline__ void gemm_phase(LAS unsigned char* lds, const Gemm g, const StaticOrder& S, const Epi& E) {
;     ...
;         for (int t = 0; t < nt; t += 2) {
;             const bool last = (t == nt - 2);
;             const char* a1 = cA + (size_t)(t + 1) * kstep;
;             const char* a2 = last ? nA : cA + (size_t)(t + 2) * kstep; const char* b2 = last ? nB : cB + (size_t)(t + 2) * kstep;
;             const char* a3 = a2 + kstep; const char* b3 = b2 + kstep;
;             PG8_LDB(B0, 0, 0); PG8_LDB(B1, 0, 1); PG8_SCHED; PG8_LDA(At, 0, 0); PG8_STAGEA(PG8_SA(1, 1), a1 + hstepA, voffA);
;             PG8_WAIT_V(8); PG8_WAIT_L(0); PG8_BAR; PG8_MMA(0, 0, At, B0); PG8_MMA(0, 1, At, B1); PG8_BAR; PG8_SCHED;
;             PG8_LDA(At, 0, 1); PG8_STAGE(PG8_SB(0, 0), b2, voffB); PG8_STAGE(PG8_SB(0, 1), b2 + hstepB, voffB); PG8_STAGEA(PG8_SA(0, 0), a2, voffA);
;             PG8_WAIT_V(8); PG8_WAIT_L(0); PG8_BAR; PG8_MMA(1, 0, At, B0); PG8_MMA(1, 1, At, B1); PG8_BAR; PG8_SCHED;
;             PG8_LDB(B0, 1, 0); PG8_LDB(B1, 1, 1); PG8_SCHED; PG8_LDA(At, 1, 0); PG8_STAGEA(PG8_SA(0, 1), a2 + hstepA, voffA);
;             PG8_WAIT_V(8); PG8_WAIT_L(0); PG8_BAR; PG8_MMA(0, 0, At, B0); PG8_MMA(0, 1, At, B1); PG8_BAR; PG8_SCHED;
;             PG8_LDA(At, 1, 1); PG8_STAGE(PG8_SB(1, 0), b3, voffB); PG8_STAGE(PG8_SB(1, 1), b3 + hstepB, voffB); PG8_STAGEA(PG8_SA(1, 0), a3, voffA);
;             PG8_WAIT_V(8); PG8_WAIT_L(0); PG8_BAR; PG8_MMA(1, 0, At, B0); PG8_MMA(1, 1, At, B1); PG8_BAR; PG8_SCHED;
;         }
;     __device__ __forceinline__ void operator()(f32x4 (&acc)[2][2][4][2], const Unit& u, int wr, int wc, int fr, int fq) const {
;     ...
; #pragma unroll
;                     for (int bj = 0; bj < 2; ++bj) { const f32x4 a = acc[ai][bj][m][0] * rs[4 * ai + m], b = acc[ai][bj][m][1] * rs[4 * ai + m]; u32x4 w;
;                         w.x = cvt_pk_bf16(gelu_t(a.x), gelu_t(a.y)); w.y = cvt_pk_bf16(gelu_t(a.z), gelu_t(a.w)); w.z = cvt_pk_bf16(gelu_t(b.x), gelu_t(b.y)); w.w = cvt_pk_bf16(gelu_t(b.z), gelu_t(b.w));
;                         *(u32x4*)(dst + (size_t)(4 * ai + m) * 1024 + 128 * bj) = w; }
	v_rcp_f32_e32 v19, v0
	v_mul_f32_e32 v0, 0xbdd2d3e7, v24
	v_fmaak_f32 v0, v24, v0, 0xc0135761
	v_mul_f32_e32 v0, v24, v0
	v_exp_f32_e32 v0, v0
	v_pk_mul_f32 v[18:19], v[22:23], v[18:19]
	v_add_f32_e32 v0, 1.0, v0
	v_rcp_f32_e32 v22, v0
	v_mul_f32_e32 v0, 0xbdd2d3e7, v25
	v_fmaak_f32 v0, v25, v0, 0xc0135761
	v_mul_f32_e32 v0, v25, v0
	v_exp_f32_e32 v0, v0
	v_cvt_pk_bf16_f32 v18, v18, v19
	v_add_f32_e32 v0, 1.0, v0
	v_rcp_f32_e32 v23, v0
	v_mul_f32_e32 v0, 0xbdd2d3e7, v20
	v_fmaak_f32 v0, v20, v0, 0xc0135761
	v_mul_f32_e32 v0, v20, v0
	v_exp_f32_e32 v0, v0
	v_pk_mul_f32 v[22:23], v[24:25], v[22:23]
	v_add_f32_e32 v0, 1.0, v0
	v_cvt_pk_bf16_f32 v19, v22, v23
	v_rcp_f32_e32 v22, v0
	v_mul_f32_e32 v0, 0xbdd2d3e7, v21
	v_fmaak_f32 v0, v21, v0, 0xc0135761
	v_mul_f32_e32 v0, v21, v0
	v_exp_f32_e32 v0, v0
	s_nop 0
	v_add_f32_e32 v0, 1.0, v0
	v_rcp_f32_e32 v23, v0
	v_mul_f32_e32 v0, 0xbdd2d3e7, v28
	v_fmaak_f32 v0, v28, v0, 0xc0135761
	v_mul_f32_e32 v0, v28, v0
	v_exp_f32_e32 v0, v0
	v_pk_mul_f32 v[20:21], v[20:21], v[22:23]
	v_add_f32_e32 v0, 1.0, v0
	v_rcp_f32_e32 v22, v0
	v_mul_f32_e32 v0, 0xbdd2d3e7, v29
	v_fmaak_f32 v0, v29, v0, 0xc0135761
	v_mul_f32_e32 v0, v29, v0
	v_exp_f32_e32 v0, v0
	v_cvt_pk_bf16_f32 v20, v20, v21
	v_add_f32_e32 v0, 1.0, v0
	v_rcp_f32_e32 v23, v0
	v_mul_f32_e32 v0, 0xbdd2d3e7, v14
	v_fmaak_f32 v0, v14, v0, 0xc0135761
	v_mul_f32_e32 v0, v14, v0
	v_exp_f32_e32 v0, v0
	v_pk_mul_f32 v[22:23], v[28:29], v[22:23]
	v_add_f32_e32 v0, 1.0, v0
	v_cvt_pk_bf16_f32 v21, v22, v23
	global_store_dwordx4 v[26:27], v[18:21], off offset:256
	s_nop 1
	v_pk_mul_f32 v[18:19], v[12:13], v[130:131] op_sel_hi:[1,0]
	v_pk_mul_f32 v[12:13], v[10:11], v[130:131] op_sel_hi:[1,0]
	v_rcp_f32_e32 v10, v0
	v_mul_f32_e32 v0, 0xbdd2d3e7, v15
	v_fmaak_f32 v0, v15, v0, 0xc0135761
	v_mul_f32_e32 v0, v15, v0
	v_exp_f32_e32 v0, v0
	s_nop 0
	v_add_f32_e32 v0, 1.0, v0
	v_rcp_f32_e32 v11, v0
	v_mul_f32_e32 v0, 0xbdd2d3e7, v16
	v_fmaak_f32 v0, v16, v0, 0xc0135761
	v_mul_f32_e32 v0, v16, v0
	v_exp_f32_e32 v0, v0
	v_pk_mul_f32 v[10:11], v[14:15], v[10:11]
	v_add_f32_e32 v0, 1.0, v0
	v_rcp_f32_e32 v14, v0
	v_mul_f32_e32 v0, 0xbdd2d3e7, v17
	v_fmaak_f32 v0, v17, v0, 0xc0135761
	v_mul_f32_e32 v0, v17, v0
	v_exp_f32_e32 v0, v0
	v_cvt_pk_bf16_f32 v10, v10, v11
	v_add_f32_e32 v0, 1.0, v0
	v_rcp_f32_e32 v15, v0
	v_mul_f32_e32 v0, 0xbdd2d3e7, v12
	v_fmaak_f32 v0, v12, v0, 0xc0135761
	v_mul_f32_e32 v0, v12, v0
	v_exp_f32_e32 v0, v0
	v_pk_mul_f32 v[14:15], v[16:17], v[14:15]
	v_add_f32_e32 v0, 1.0, v0
	v_cvt_pk_bf16_f32 v11, v14, v15
	v_rcp_f32_e32 v14, v0
	v_mul_f32_e32 v0, 0xbdd2d3e7, v13
	v_fmaak_f32 v0, v13, v0, 0xc0135761
	v_mul_f32_e32 v0, v13, v0
	v_exp_f32_e32 v0, v0
	s_nop 0
	v_add_f32_e32 v0, 1.0, v0
	v_rcp_f32_e32 v15, v0
	v_mul_f32_e32 v0, 0xbdd2d3e7, v18
	v_fmaak_f32 v0, v18, v0, 0xc0135761
	v_mul_f32_e32 v0, v18, v0
	v_exp_f32_e32 v0, v0
	v_pk_mul_f32 v[12:13], v[12:13], v[14:15]
	v_add_f32_e32 v0, 1.0, v0
	v_rcp_f32_e32 v14, v0
	v_mul_f32_e32 v0, 0xbdd2d3e7, v19
	v_fmaak_f32 v0, v19, v0, 0xc0135761
	v_mul_f32_e32 v0, v19, v0
	v_exp_f32_e32 v0, v0
	v_cvt_pk_bf16_f32 v12, v12, v13
	v_add_f32_e32 v0, 1.0, v0
	v_rcp_f32_e32 v15, v0
	v_mul_f32_e32 v0, 0xbdd2d3e7, v6
	v_fmaak_f32 v0, v6, v0, 0xc0135761
	v_mul_f32_e32 v0, v6, v0
	v_exp_f32_e32 v0, v0
	v_pk_mul_f32 v[14:15], v[18:19], v[14:15]
	v_add_f32_e32 v0, 1.0, v0
	v_cvt_pk_bf16_f32 v13, v14, v15
	global_store_dwordx4 v[26:27], v[10:13], off offset:2048
	s_nop 1
	v_pk_mul_f32 v[10:11], v[4:5], v[130:131] op_sel_hi:[1,0]
	v_pk_mul_f32 v[4:5], v[2:3], v[130:131] op_sel_hi:[1,0]
	v_rcp_f32_e32 v2, v0
	v_mul_f32_e32 v0, 0xbdd2d3e7, v7
	v_fmaak_f32 v0, v7, v0, 0xc0135761
	v_mul_f32_e32 v0, v7, v0
	v_exp_f32_e32 v0, v0
	s_nop 0
	v_add_f32_e32 v0, 1.0, v0
	v_rcp_f32_e32 v3, v0
	v_mul_f32_e32 v0, 0xbdd2d3e7, v8
	v_fmaak_f32 v0, v8, v0, 0xc0135761
	v_mul_f32_e32 v0, v8, v0
	v_exp_f32_e32 v0, v0
	v_pk_mul_f32 v[2:3], v[6:7], v[2:3]
	v_add_f32_e32 v0, 1.0, v0
	v_rcp_f32_e32 v6, v0
	v_mul_f32_e32 v0, 0xbdd2d3e7, v9
	v_fmaak_f32 v0, v9, v0, 0xc0135761
	v_mul_f32_e32 v0, v9, v0
	v_exp_f32_e32 v0, v0
	v_cvt_pk_bf16_f32 v2, v2, v3
	v_add_f32_e32 v0, 1.0, v0
	v_rcp_f32_e32 v7, v0
	v_mul_f32_e32 v0, 0xbdd2d3e7, v4
	v_fmaak_f32 v0, v4, v0, 0xc0135761
	v_mul_f32_e32 v0, v4, v0
	v_exp_f32_e32 v0, v0
	v_pk_mul_f32 v[6:7], v[8:9], v[6:7]
	v_add_f32_e32 v0, 1.0, v0
	v_cvt_pk_bf16_f32 v3, v6, v7
	v_rcp_f32_e32 v6, v0
	v_mul_f32_e32 v0, 0xbdd2d3e7, v5
	v_fmaak_f32 v0, v5, v0, 0xc0135761
	v_mul_f32_e32 v0, v5, v0
	v_exp_f32_e32 v0, v0
	s_nop 0
	v_add_f32_e32 v0, 1.0, v0
	v_rcp_f32_e32 v7, v0
	v_mul_f32_e32 v0, 0xbdd2d3e7, v10
	v_fmaak_f32 v0, v10, v0, 0xc0135761
	v_mul_f32_e32 v0, v10, v0
	v_exp_f32_e32 v0, v0
	v_pk_mul_f32 v[4:5], v[4:5], v[6:7]
	v_add_f32_e32 v0, 1.0, v0
	v_rcp_f32_e32 v6, v0
	v_mul_f32_e32 v0, 0xbdd2d3e7, v11
	v_fmaak_f32 v0, v11, v0, 0xc0135761
	v_mul_f32_e32 v0, v11, v0
	v_exp_f32_e32 v0, v0
	v_cvt_pk_bf16_f32 v4, v4, v5
	v_add_f32_e32 v0, 1.0, v0
	v_rcp_f32_e32 v7, v0
	s_nop 0
	v_pk_mul_f32 v[6:7], v[10:11], v[6:7]
	s_nop 0
	v_cvt_pk_bf16_f32 v5, v6, v7
	global_store_dwordx4 v[26:27], v[2:5], off offset:2304
	s_andn2_b64 vcc, exec, s[38:39]
	s_mov_b64 s[38:39], -1
	s_cbranch_vccnz .LBB0_431
